# v14 plus: chain step-1 head St reads batched, sample loop s1/s2 DPP + s6/s7 read batches, duplicate K-loop lgkmcnt(0) waits dropped
# speedup vs baseline: 1.0100x; 1.0100x over previous
.LBB0_154:
	ds_read_b128 v[150:153], v147
	ds_read_b128 v[154:157], v147 offset:1024
	ds_read_b128 v[158:161], v147 offset:2048
	ds_read_b128 v[162:165], v147 offset:3072
	s_add_u32 s18, s16, 0xfff80080
	s_addc_u32 s19, s17, -1
	s_cmp_eq_u32 s40, 28
	s_cselect_b32 s21, s11, s19
	s_cselect_b32 s20, s36, s18
	s_cselect_b32 s19, s9, s39
	s_cselect_b32 s18, s37, s38
	s_add_i32 m0, s7, 0xc000
	ds_read_b128 v[166:169], v148
	ds_read_b128 v[170:173], v148 offset:1024
	ds_read_b128 v[174:177], v148 offset:2048
	ds_read_b128 v[178:181], v148 offset:3072
	ds_read_b128 v[182:185], v148 offset:4096
	ds_read_b128 v[186:189], v148 offset:5120
	ds_read_b128 v[190:193], v148 offset:6144
	ds_read_b128 v[194:197], v148 offset:7168
	global_load_lds_dwordx4 v136, s[16:17]
	s_add_i32 m0, s7, 0xe000
	s_nop 0
	global_load_lds_dwordx4 v138, s[16:17]
	s_waitcnt lgkmcnt(8)
	s_barrier
	s_waitcnt lgkmcnt(0)
	v_mfma_f32_16x16x32_bf16 v[124:127], v[150:153], v[166:169], v[124:127]
	v_mfma_f32_16x16x32_bf16 v[120:123], v[158:161], v[166:169], v[120:123]
	v_mfma_f32_16x16x32_bf16 v[116:119], v[150:153], v[174:177], v[116:119]
	v_mfma_f32_16x16x32_bf16 v[112:115], v[158:161], v[174:177], v[112:115]
	v_mfma_f32_16x16x32_bf16 v[100:103], v[150:153], v[182:185], v[100:103]
	v_mfma_f32_16x16x32_bf16 v[96:99], v[158:161], v[182:185], v[96:99]
	v_mfma_f32_16x16x32_bf16 v[84:87], v[150:153], v[190:193], v[84:87]
	v_mfma_f32_16x16x32_bf16 v[80:83], v[158:161], v[190:193], v[80:83]
	v_mfma_f32_16x16x32_bf16 v[124:127], v[154:157], v[170:173], v[124:127]
	v_mfma_f32_16x16x32_bf16 v[120:123], v[162:165], v[170:173], v[120:123]
	v_mfma_f32_16x16x32_bf16 v[116:119], v[154:157], v[178:181], v[116:119]
	v_mfma_f32_16x16x32_bf16 v[112:115], v[162:165], v[178:181], v[112:115]
	v_mfma_f32_16x16x32_bf16 v[100:103], v[154:157], v[186:189], v[100:103]
	v_mfma_f32_16x16x32_bf16 v[96:99], v[162:165], v[186:189], v[96:99]
	v_mfma_f32_16x16x32_bf16 v[84:87], v[154:157], v[194:197], v[84:87]
	v_mfma_f32_16x16x32_bf16 v[80:83], v[162:165], v[194:197], v[80:83]
	s_barrier
	s_add_i32 s41, s31, s23
	s_mov_b32 m0, s41
	ds_read_b128 v[198:201], v149
	ds_read_b128 v[204:207], v149 offset:1024
	ds_read_b128 v[208:211], v149 offset:2048
	ds_read_b128 v[212:215], v149 offset:3072
	global_load_lds_dwordx4 v132, s[18:19]
	s_add_i32 m0, s41, 0x2000
	s_nop 0
	global_load_lds_dwordx4 v128, s[18:19]
	s_barrier
	s_waitcnt lgkmcnt(0)
	v_mfma_f32_16x16x32_bf16 v[108:111], v[198:201], v[166:169], v[108:111]
	v_mfma_f32_16x16x32_bf16 v[104:107], v[208:211], v[166:169], v[104:107]
	v_mfma_f32_16x16x32_bf16 v[92:95], v[198:201], v[174:177], v[92:95]
	v_mfma_f32_16x16x32_bf16 v[88:91], v[208:211], v[174:177], v[88:91]
	v_mfma_f32_16x16x32_bf16 v[76:79], v[198:201], v[182:185], v[76:79]
	v_mfma_f32_16x16x32_bf16 v[72:75], v[208:211], v[182:185], v[72:75]
	v_mfma_f32_16x16x32_bf16 v[68:71], v[198:201], v[190:193], v[68:71]
	v_mfma_f32_16x16x32_bf16 v[64:67], v[208:211], v[190:193], v[64:67]
	v_mfma_f32_16x16x32_bf16 v[108:111], v[204:207], v[170:173], v[108:111]
	v_mfma_f32_16x16x32_bf16 v[104:107], v[212:215], v[170:173], v[104:107]
	v_mfma_f32_16x16x32_bf16 v[92:95], v[204:207], v[178:181], v[92:95]
	v_mfma_f32_16x16x32_bf16 v[88:91], v[212:215], v[178:181], v[88:91]
	v_mfma_f32_16x16x32_bf16 v[76:79], v[204:207], v[186:189], v[76:79]
	v_mfma_f32_16x16x32_bf16 v[72:75], v[212:215], v[186:189], v[72:75]
	v_mfma_f32_16x16x32_bf16 v[68:71], v[204:207], v[194:197], v[68:71]
	v_mfma_f32_16x16x32_bf16 v[64:67], v[212:215], v[194:197], v[64:67]
	s_mov_b32 m0, s7
	s_mov_b64 s[98:99], s[20:21]
	s_barrier
	ds_read_b128 v[166:169], v148 offset:16384
	ds_read_b128 v[170:173], v148 offset:17408
	ds_read_b128 v[174:177], v148 offset:18432
	ds_read_b128 v[178:181], v148 offset:19456
	ds_read_b128 v[182:185], v148 offset:20480
	ds_read_b128 v[186:189], v148 offset:21504
	ds_read_b128 v[190:193], v148 offset:22528
	ds_read_b128 v[194:197], v148 offset:23552
	global_load_lds_dwordx4 v134, s[20:21]
	s_mov_b32 m0, s25
	s_nop 0
	global_load_lds_dwordx4 v130, s[20:21]
	s_barrier
	s_waitcnt lgkmcnt(0)
	v_mfma_f32_16x16x32_bf16 v[60:63], v[150:153], v[166:169], v[60:63]
	v_mfma_f32_16x16x32_bf16 v[56:59], v[158:161], v[166:169], v[56:59]
	v_mfma_f32_16x16x32_bf16 v[52:55], v[150:153], v[174:177], v[52:55]
	v_mfma_f32_16x16x32_bf16 v[48:51], v[158:161], v[174:177], v[48:51]
	v_mfma_f32_16x16x32_bf16 v[36:39], v[150:153], v[182:185], v[36:39]
	v_mfma_f32_16x16x32_bf16 v[32:35], v[158:161], v[182:185], v[32:35]
	v_mfma_f32_16x16x32_bf16 v[20:23], v[150:153], v[190:193], v[20:23]
	v_mfma_f32_16x16x32_bf16 v[16:19], v[158:161], v[190:193], v[16:19]
	v_mfma_f32_16x16x32_bf16 v[60:63], v[154:157], v[170:173], v[60:63]
	v_mfma_f32_16x16x32_bf16 v[56:59], v[162:165], v[170:173], v[56:59]
	v_mfma_f32_16x16x32_bf16 v[52:55], v[154:157], v[178:181], v[52:55]
	v_mfma_f32_16x16x32_bf16 v[48:51], v[162:165], v[178:181], v[48:51]
	v_mfma_f32_16x16x32_bf16 v[36:39], v[154:157], v[186:189], v[36:39]
	v_mfma_f32_16x16x32_bf16 v[32:35], v[162:165], v[186:189], v[32:35]
	v_mfma_f32_16x16x32_bf16 v[20:23], v[154:157], v[194:197], v[20:23]
	v_mfma_f32_16x16x32_bf16 v[16:19], v[162:165], v[194:197], v[16:19]
	s_barrier
	s_add_u32 s42, s18, 0x20000
	s_addc_u32 s43, s19, 0
	s_add_i32 s41, s33, s23
	s_mov_b32 m0, s41
	s_nop 0
	global_load_lds_dwordx4 v132, s[42:43]
	s_add_i32 m0, s41, 0x2000
	s_nop 0
	global_load_lds_dwordx4 v128, s[42:43]
	s_waitcnt vmcnt(6)
	s_barrier
	v_mfma_f32_16x16x32_bf16 v[44:47], v[198:201], v[166:169], v[44:47]
	v_mfma_f32_16x16x32_bf16 v[40:43], v[208:211], v[166:169], v[40:43]
	v_mfma_f32_16x16x32_bf16 v[28:31], v[198:201], v[174:177], v[28:31]
	v_mfma_f32_16x16x32_bf16 v[24:27], v[208:211], v[174:177], v[24:27]
	v_mfma_f32_16x16x32_bf16 v[12:15], v[198:201], v[182:185], v[12:15]
	v_mfma_f32_16x16x32_bf16 v[8:11], v[208:211], v[182:185], v[8:11]
	v_mfma_f32_16x16x32_bf16 v[4:7], v[198:201], v[190:193], v[4:7]
	v_mfma_f32_16x16x32_bf16 v[0:3], v[208:211], v[190:193], v[0:3]
	v_mfma_f32_16x16x32_bf16 v[44:47], v[204:207], v[170:173], v[44:47]
	v_mfma_f32_16x16x32_bf16 v[40:43], v[212:215], v[170:173], v[40:43]
	v_mfma_f32_16x16x32_bf16 v[28:31], v[204:207], v[178:181], v[28:31]
	v_mfma_f32_16x16x32_bf16 v[24:27], v[212:215], v[178:181], v[24:27]
	v_mfma_f32_16x16x32_bf16 v[12:15], v[204:207], v[186:189], v[12:15]
	v_mfma_f32_16x16x32_bf16 v[8:11], v[212:215], v[186:189], v[8:11]
	v_mfma_f32_16x16x32_bf16 v[4:7], v[204:207], v[194:197], v[4:7]
	v_mfma_f32_16x16x32_bf16 v[0:3], v[212:215], v[194:197], v[0:3]
	s_add_i32 s41, 0, 0x18000
	v_add_u32_e32 v162, s41, v145
	s_barrier
	ds_read_b128 v[150:153], v162
	ds_read_b128 v[154:157], v162 offset:1024
	ds_read_b128 v[158:161], v162 offset:2048
	ds_read_b128 v[162:165], v162 offset:3072
	s_add_u32 s20, s20, 0x80000
	s_addc_u32 s21, s21, 0
	s_mov_b32 m0, s26
	ds_read_b128 v[166:169], v148 offset:32768
	ds_read_b128 v[170:173], v148 offset:33792
	ds_read_b128 v[174:177], v148 offset:34816
	ds_read_b128 v[178:181], v148 offset:35840
	ds_read_b128 v[182:185], v148 offset:36864
	ds_read_b128 v[186:189], v148 offset:37888
	ds_read_b128 v[190:193], v148 offset:38912
	ds_read_b128 v[194:197], v148 offset:39936
	global_load_lds_dwordx4 v134, s[20:21]
	s_mov_b32 m0, s27
	s_nop 0
	global_load_lds_dwordx4 v130, s[20:21]
	s_waitcnt lgkmcnt(8)
	s_barrier
	s_waitcnt lgkmcnt(0)
	v_mfma_f32_16x16x32_bf16 v[124:127], v[150:153], v[166:169], v[124:127]
	v_mfma_f32_16x16x32_bf16 v[120:123], v[158:161], v[166:169], v[120:123]
	v_mfma_f32_16x16x32_bf16 v[116:119], v[150:153], v[174:177], v[116:119]
	v_mfma_f32_16x16x32_bf16 v[112:115], v[158:161], v[174:177], v[112:115]
	v_mfma_f32_16x16x32_bf16 v[100:103], v[150:153], v[182:185], v[100:103]
	v_mfma_f32_16x16x32_bf16 v[96:99], v[158:161], v[182:185], v[96:99]
	v_mfma_f32_16x16x32_bf16 v[84:87], v[150:153], v[190:193], v[84:87]
	v_mfma_f32_16x16x32_bf16 v[80:83], v[158:161], v[190:193], v[80:83]
	v_mfma_f32_16x16x32_bf16 v[124:127], v[154:157], v[170:173], v[124:127]
	v_mfma_f32_16x16x32_bf16 v[120:123], v[162:165], v[170:173], v[120:123]
	v_mfma_f32_16x16x32_bf16 v[116:119], v[154:157], v[178:181], v[116:119]
	v_mfma_f32_16x16x32_bf16 v[112:115], v[162:165], v[178:181], v[112:115]
	v_mfma_f32_16x16x32_bf16 v[100:103], v[154:157], v[186:189], v[100:103]
	v_mfma_f32_16x16x32_bf16 v[96:99], v[162:165], v[186:189], v[96:99]
	v_mfma_f32_16x16x32_bf16 v[84:87], v[154:157], v[194:197], v[84:87]
	v_mfma_f32_16x16x32_bf16 v[80:83], v[162:165], v[194:197], v[80:83]
	s_barrier
	s_add_i32 s20, 0, 0x1c000
	s_add_i32 s21, s41, s23
	v_add_u32_e32 v212, s20, v145
	s_mov_b32 m0, s21
	ds_read_b128 v[198:201], v212
	ds_read_b128 v[204:207], v212 offset:1024
	ds_read_b128 v[208:211], v212 offset:2048
	ds_read_b128 v[212:215], v212 offset:3072
	s_add_u32 s100, s18, 0x80
	s_addc_u32 s101, s19, 0
	global_load_lds_dwordx4 v132, s[100:101]
	s_add_i32 m0, s21, 0x2000
	s_nop 0
	s_add_u32 s100, s18, 0x80
	s_addc_u32 s101, s19, 0
	global_load_lds_dwordx4 v128, s[100:101]
	s_barrier
	s_waitcnt lgkmcnt(0)
	v_mfma_f32_16x16x32_bf16 v[108:111], v[198:201], v[166:169], v[108:111]
	v_mfma_f32_16x16x32_bf16 v[104:107], v[208:211], v[166:169], v[104:107]
	v_mfma_f32_16x16x32_bf16 v[92:95], v[198:201], v[174:177], v[92:95]
	v_mfma_f32_16x16x32_bf16 v[88:91], v[208:211], v[174:177], v[88:91]
	v_mfma_f32_16x16x32_bf16 v[76:79], v[198:201], v[182:185], v[76:79]
	v_mfma_f32_16x16x32_bf16 v[72:75], v[208:211], v[182:185], v[72:75]
	v_mfma_f32_16x16x32_bf16 v[68:71], v[198:201], v[190:193], v[68:71]
	v_mfma_f32_16x16x32_bf16 v[64:67], v[208:211], v[190:193], v[64:67]
	v_mfma_f32_16x16x32_bf16 v[108:111], v[204:207], v[170:173], v[108:111]
	v_mfma_f32_16x16x32_bf16 v[104:107], v[212:215], v[170:173], v[104:107]
	v_mfma_f32_16x16x32_bf16 v[92:95], v[204:207], v[178:181], v[92:95]
	v_mfma_f32_16x16x32_bf16 v[88:91], v[212:215], v[178:181], v[88:91]
	v_mfma_f32_16x16x32_bf16 v[76:79], v[204:207], v[186:189], v[76:79]
	v_mfma_f32_16x16x32_bf16 v[72:75], v[212:215], v[186:189], v[72:75]
	v_mfma_f32_16x16x32_bf16 v[68:71], v[204:207], v[194:197], v[68:71]
	v_mfma_f32_16x16x32_bf16 v[64:67], v[212:215], v[194:197], v[64:67]
	s_mov_b32 m0, s29
	s_barrier
	ds_read_b128 v[166:169], v148 offset:49152
	ds_read_b128 v[170:173], v148 offset:50176
	ds_read_b128 v[174:177], v148 offset:51200
	ds_read_b128 v[178:181], v148 offset:52224
	ds_read_b128 v[182:185], v148 offset:53248
	ds_read_b128 v[186:189], v148 offset:54272
	ds_read_b128 v[190:193], v148 offset:55296
	ds_read_b128 v[194:197], v148 offset:56320
	s_add_u32 s100, s98, 0x80
	s_addc_u32 s101, s99, 0
	global_load_lds_dwordx4 v134, s[100:101]
	s_mov_b32 m0, s30
	s_nop 0
	s_add_u32 s100, s98, 0x80
	s_addc_u32 s101, s99, 0
	global_load_lds_dwordx4 v130, s[100:101]
	s_barrier
	s_waitcnt lgkmcnt(0)
	v_mfma_f32_16x16x32_bf16 v[60:63], v[150:153], v[166:169], v[60:63]
	v_mfma_f32_16x16x32_bf16 v[56:59], v[158:161], v[166:169], v[56:59]
	v_mfma_f32_16x16x32_bf16 v[52:55], v[150:153], v[174:177], v[52:55]
	v_mfma_f32_16x16x32_bf16 v[48:51], v[158:161], v[174:177], v[48:51]
	v_mfma_f32_16x16x32_bf16 v[36:39], v[150:153], v[182:185], v[36:39]
	v_mfma_f32_16x16x32_bf16 v[32:35], v[158:161], v[182:185], v[32:35]
	v_mfma_f32_16x16x32_bf16 v[20:23], v[150:153], v[190:193], v[20:23]
	v_mfma_f32_16x16x32_bf16 v[16:19], v[158:161], v[190:193], v[16:19]
	v_mfma_f32_16x16x32_bf16 v[60:63], v[154:157], v[170:173], v[60:63]
	v_mfma_f32_16x16x32_bf16 v[56:59], v[162:165], v[170:173], v[56:59]
	v_mfma_f32_16x16x32_bf16 v[52:55], v[154:157], v[178:181], v[52:55]
	v_mfma_f32_16x16x32_bf16 v[48:51], v[162:165], v[178:181], v[48:51]
	v_mfma_f32_16x16x32_bf16 v[36:39], v[154:157], v[186:189], v[36:39]
	v_mfma_f32_16x16x32_bf16 v[32:35], v[162:165], v[186:189], v[32:35]
	v_mfma_f32_16x16x32_bf16 v[20:23], v[154:157], v[194:197], v[20:23]
	v_mfma_f32_16x16x32_bf16 v[16:19], v[162:165], v[194:197], v[16:19]
	s_barrier
	s_add_u32 s18, s18, 0x20080
	s_addc_u32 s19, s19, 0
	s_add_i32 s20, s20, s23
	s_mov_b32 m0, s20
	s_nop 0
	global_load_lds_dwordx4 v132, s[18:19]
	s_add_i32 m0, s20, 0x2000
	s_nop 0
	global_load_lds_dwordx4 v128, s[18:19]
	s_waitcnt vmcnt(6)
	s_barrier
	v_mfma_f32_16x16x32_bf16 v[44:47], v[198:201], v[166:169], v[44:47]
	v_mfma_f32_16x16x32_bf16 v[40:43], v[208:211], v[166:169], v[40:43]
	v_mfma_f32_16x16x32_bf16 v[28:31], v[198:201], v[174:177], v[28:31]
	v_mfma_f32_16x16x32_bf16 v[24:27], v[208:211], v[174:177], v[24:27]
	v_mfma_f32_16x16x32_bf16 v[12:15], v[198:201], v[182:185], v[12:15]
	v_mfma_f32_16x16x32_bf16 v[8:11], v[208:211], v[182:185], v[8:11]
	v_mfma_f32_16x16x32_bf16 v[4:7], v[198:201], v[190:193], v[4:7]
	v_mfma_f32_16x16x32_bf16 v[0:3], v[208:211], v[190:193], v[0:3]
	v_mfma_f32_16x16x32_bf16 v[44:47], v[204:207], v[170:173], v[44:47]
	v_mfma_f32_16x16x32_bf16 v[40:43], v[212:215], v[170:173], v[40:43]
	v_mfma_f32_16x16x32_bf16 v[28:31], v[204:207], v[178:181], v[28:31]
	v_mfma_f32_16x16x32_bf16 v[24:27], v[212:215], v[178:181], v[24:27]
	v_mfma_f32_16x16x32_bf16 v[12:15], v[204:207], v[186:189], v[12:15]
	v_mfma_f32_16x16x32_bf16 v[8:11], v[212:215], v[186:189], v[8:11]
	v_mfma_f32_16x16x32_bf16 v[4:7], v[204:207], v[194:197], v[4:7]
	v_mfma_f32_16x16x32_bf16 v[0:3], v[212:215], v[194:197], v[0:3]
	s_add_i32 s40, s40, 2
	s_add_u32 s16, s16, 0x100
	s_addc_u32 s17, s17, 0
	s_add_u32 s38, s38, 0x100
	s_addc_u32 s39, s39, 0
	s_cmp_gt_u32 s40, 29
	s_barrier
	s_cbranch_scc0 .LBB0_154
	v_readlane_b32 s100, v248, 63
	v_readlane_b32 s101, v247, 0
	v_and_b32_e32 v242, 15, v202
	v_bfe_u32 v243, v202, 4, 2
	v_bfe_u32 v244, v202, 6, 2
	v_lshrrev_b32_e32 v245, 8, v202
	v_and_b32_e32 v240, 7, v242
	v_lshl_add_u32 v240, v245, 6, v240
	v_lshl_add_u32 v240, s6, 8, v240
	v_mul_u32_u24_e32 v240, 0x3000, v240
	v_lshrrev_b32_e32 v241, 3, v242
	v_lshlrev_b32_e32 v241, 6, v241
	v_lshl_add_u32 v241, v244, 7, v241
	v_lshl_add_u32 v241, v243, 4, v241
	v_add_u32_e32 v240, v240, v241
	s_lshl_b32 s98, s35, 9
	v_add_u32_e32 v240, s98, v240
	v_cvt_pk_bf16_f32 v228, v124, v125
	v_cvt_pk_bf16_f32 v229, v126, v127
	v_cvt_pk_bf16_f32 v230, v120, v121
	v_cvt_pk_bf16_f32 v231, v122, v123
	v_cvt_pk_bf16_f32 v232, v108, v109
	v_cvt_pk_bf16_f32 v233, v110, v111
	v_cvt_pk_bf16_f32 v234, v104, v105
	v_cvt_pk_bf16_f32 v235, v106, v107
	v_mov_b32_e32 v236, v228
	v_mov_b32_e32 v237, v229
	v_mov_b32_e32 v238, v230
	v_mov_b32_e32 v239, v231
	v_mov_b32_dpp v228, v232 row_ror:8 row_mask:0xf bank_mask:0xc
	v_mov_b32_dpp v229, v233 row_ror:8 row_mask:0xf bank_mask:0xc
	v_mov_b32_dpp v230, v234 row_ror:8 row_mask:0xf bank_mask:0xc
	v_mov_b32_dpp v231, v235 row_ror:8 row_mask:0xf bank_mask:0xc
	v_mov_b32_dpp v232, v236 row_ror:8 row_mask:0xf bank_mask:0x3
	v_mov_b32_dpp v233, v237 row_ror:8 row_mask:0xf bank_mask:0x3
	v_mov_b32_dpp v234, v238 row_ror:8 row_mask:0xf bank_mask:0x3
	v_mov_b32_dpp v235, v239 row_ror:8 row_mask:0xf bank_mask:0x3
	global_store_dwordx4 v240, v[228:231], s[100:101]
	s_add_u32 s100, s100, 0x18000
	s_addc_u32 s101, s101, 0
	global_store_dwordx4 v240, v[232:235], s[100:101]
	v_cvt_pk_bf16_f32 v228, v116, v117
	v_cvt_pk_bf16_f32 v229, v118, v119
	v_cvt_pk_bf16_f32 v230, v112, v113
	v_cvt_pk_bf16_f32 v231, v114, v115
	v_cvt_pk_bf16_f32 v232, v92, v93
	v_cvt_pk_bf16_f32 v233, v94, v95
	v_cvt_pk_bf16_f32 v234, v88, v89
	v_cvt_pk_bf16_f32 v235, v90, v91
	v_mov_b32_e32 v236, v228
	v_mov_b32_e32 v237, v229
	v_mov_b32_e32 v238, v230
	v_mov_b32_e32 v239, v231
	v_mov_b32_dpp v228, v232 row_ror:8 row_mask:0xf bank_mask:0xc
	v_mov_b32_dpp v229, v233 row_ror:8 row_mask:0xf bank_mask:0xc
	v_mov_b32_dpp v230, v234 row_ror:8 row_mask:0xf bank_mask:0xc
	v_mov_b32_dpp v231, v235 row_ror:8 row_mask:0xf bank_mask:0xc
	v_mov_b32_dpp v232, v236 row_ror:8 row_mask:0xf bank_mask:0x3
	v_mov_b32_dpp v233, v237 row_ror:8 row_mask:0xf bank_mask:0x3
	v_mov_b32_dpp v234, v238 row_ror:8 row_mask:0xf bank_mask:0x3
	v_mov_b32_dpp v235, v239 row_ror:8 row_mask:0xf bank_mask:0x3
	s_add_u32 s100, s100, 0x18000
	s_addc_u32 s101, s101, 0
	global_store_dwordx4 v240, v[228:231], s[100:101]
	s_add_u32 s100, s100, 0x18000
	s_addc_u32 s101, s101, 0
	global_store_dwordx4 v240, v[232:235], s[100:101]
	v_cvt_pk_bf16_f32 v228, v100, v101
	v_cvt_pk_bf16_f32 v229, v102, v103
	v_cvt_pk_bf16_f32 v230, v96, v97
	v_cvt_pk_bf16_f32 v231, v98, v99
	v_cvt_pk_bf16_f32 v232, v76, v77
	v_cvt_pk_bf16_f32 v233, v78, v79
	v_cvt_pk_bf16_f32 v234, v72, v73
	v_cvt_pk_bf16_f32 v235, v74, v75
	v_mov_b32_e32 v236, v228
	v_mov_b32_e32 v237, v229
	v_mov_b32_e32 v238, v230
	v_mov_b32_e32 v239, v231
	v_mov_b32_dpp v228, v232 row_ror:8 row_mask:0xf bank_mask:0xc
	v_mov_b32_dpp v229, v233 row_ror:8 row_mask:0xf bank_mask:0xc
	v_mov_b32_dpp v230, v234 row_ror:8 row_mask:0xf bank_mask:0xc
	v_mov_b32_dpp v231, v235 row_ror:8 row_mask:0xf bank_mask:0xc
	v_mov_b32_dpp v232, v236 row_ror:8 row_mask:0xf bank_mask:0x3
	v_mov_b32_dpp v233, v237 row_ror:8 row_mask:0xf bank_mask:0x3
	v_mov_b32_dpp v234, v238 row_ror:8 row_mask:0xf bank_mask:0x3
	v_mov_b32_dpp v235, v239 row_ror:8 row_mask:0xf bank_mask:0x3
	s_add_u32 s100, s100, 0x18000
	s_addc_u32 s101, s101, 0
	global_store_dwordx4 v240, v[228:231], s[100:101]
	s_add_u32 s100, s100, 0x18000
	s_addc_u32 s101, s101, 0
	global_store_dwordx4 v240, v[232:235], s[100:101]
	v_cvt_pk_bf16_f32 v228, v84, v85
	v_cvt_pk_bf16_f32 v229, v86, v87
	v_cvt_pk_bf16_f32 v230, v80, v81
	v_cvt_pk_bf16_f32 v231, v82, v83
	v_cvt_pk_bf16_f32 v232, v68, v69
	v_cvt_pk_bf16_f32 v233, v70, v71
	v_cvt_pk_bf16_f32 v234, v64, v65
	v_cvt_pk_bf16_f32 v235, v66, v67
	v_mov_b32_e32 v236, v228
	v_mov_b32_e32 v237, v229
	v_mov_b32_e32 v238, v230
	v_mov_b32_e32 v239, v231
	v_mov_b32_dpp v228, v232 row_ror:8 row_mask:0xf bank_mask:0xc
	v_mov_b32_dpp v229, v233 row_ror:8 row_mask:0xf bank_mask:0xc
	v_mov_b32_dpp v230, v234 row_ror:8 row_mask:0xf bank_mask:0xc
	v_mov_b32_dpp v231, v235 row_ror:8 row_mask:0xf bank_mask:0xc
	v_mov_b32_dpp v232, v236 row_ror:8 row_mask:0xf bank_mask:0x3
	v_mov_b32_dpp v233, v237 row_ror:8 row_mask:0xf bank_mask:0x3
	v_mov_b32_dpp v234, v238 row_ror:8 row_mask:0xf bank_mask:0x3
	v_mov_b32_dpp v235, v239 row_ror:8 row_mask:0xf bank_mask:0x3
	s_add_u32 s100, s100, 0x18000
	s_addc_u32 s101, s101, 0
	global_store_dwordx4 v240, v[228:231], s[100:101]
	s_add_u32 s100, s100, 0x18000
	s_addc_u32 s101, s101, 0
	global_store_dwordx4 v240, v[232:235], s[100:101]
	v_cvt_pk_bf16_f32 v228, v60, v61
	v_cvt_pk_bf16_f32 v229, v62, v63
	v_cvt_pk_bf16_f32 v230, v56, v57
	v_cvt_pk_bf16_f32 v231, v58, v59
	v_cvt_pk_bf16_f32 v232, v44, v45
	v_cvt_pk_bf16_f32 v233, v46, v47
	v_cvt_pk_bf16_f32 v234, v40, v41
	v_cvt_pk_bf16_f32 v235, v42, v43
	v_mov_b32_e32 v236, v228
	v_mov_b32_e32 v237, v229
	v_mov_b32_e32 v238, v230
	v_mov_b32_e32 v239, v231
	v_mov_b32_dpp v228, v232 row_ror:8 row_mask:0xf bank_mask:0xc
	v_mov_b32_dpp v229, v233 row_ror:8 row_mask:0xf bank_mask:0xc
	v_mov_b32_dpp v230, v234 row_ror:8 row_mask:0xf bank_mask:0xc
	v_mov_b32_dpp v231, v235 row_ror:8 row_mask:0xf bank_mask:0xc
	v_mov_b32_dpp v232, v236 row_ror:8 row_mask:0xf bank_mask:0x3
	v_mov_b32_dpp v233, v237 row_ror:8 row_mask:0xf bank_mask:0x3
	v_mov_b32_dpp v234, v238 row_ror:8 row_mask:0xf bank_mask:0x3
	v_mov_b32_dpp v235, v239 row_ror:8 row_mask:0xf bank_mask:0x3
	s_add_u32 s100, s100, 0xd8000
	s_addc_u32 s101, s101, 0
	global_store_dwordx4 v240, v[228:231], s[100:101]
	s_add_u32 s100, s100, 0x18000
	s_addc_u32 s101, s101, 0
	global_store_dwordx4 v240, v[232:235], s[100:101]
	v_cvt_pk_bf16_f32 v228, v52, v53
	v_cvt_pk_bf16_f32 v229, v54, v55
	v_cvt_pk_bf16_f32 v230, v48, v49
	v_cvt_pk_bf16_f32 v231, v50, v51
	v_cvt_pk_bf16_f32 v232, v28, v29
	v_cvt_pk_bf16_f32 v233, v30, v31
	v_cvt_pk_bf16_f32 v234, v24, v25
	v_cvt_pk_bf16_f32 v235, v26, v27
	v_mov_b32_e32 v236, v228
	v_mov_b32_e32 v237, v229
	v_mov_b32_e32 v238, v230
	v_mov_b32_e32 v239, v231
	v_mov_b32_dpp v228, v232 row_ror:8 row_mask:0xf bank_mask:0xc
	v_mov_b32_dpp v229, v233 row_ror:8 row_mask:0xf bank_mask:0xc
	v_mov_b32_dpp v230, v234 row_ror:8 row_mask:0xf bank_mask:0xc
	v_mov_b32_dpp v231, v235 row_ror:8 row_mask:0xf bank_mask:0xc
	v_mov_b32_dpp v232, v236 row_ror:8 row_mask:0xf bank_mask:0x3
	v_mov_b32_dpp v233, v237 row_ror:8 row_mask:0xf bank_mask:0x3
	v_mov_b32_dpp v234, v238 row_ror:8 row_mask:0xf bank_mask:0x3
	v_mov_b32_dpp v235, v239 row_ror:8 row_mask:0xf bank_mask:0x3
	s_add_u32 s100, s100, 0x18000
	s_addc_u32 s101, s101, 0
	global_store_dwordx4 v240, v[228:231], s[100:101]
	s_add_u32 s100, s100, 0x18000
	s_addc_u32 s101, s101, 0
	global_store_dwordx4 v240, v[232:235], s[100:101]
	v_cvt_pk_bf16_f32 v228, v36, v37
	v_cvt_pk_bf16_f32 v229, v38, v39
	v_cvt_pk_bf16_f32 v230, v32, v33
	v_cvt_pk_bf16_f32 v231, v34, v35
	v_cvt_pk_bf16_f32 v232, v12, v13
	v_cvt_pk_bf16_f32 v233, v14, v15
	v_cvt_pk_bf16_f32 v234, v8, v9
	v_cvt_pk_bf16_f32 v235, v10, v11
	v_mov_b32_e32 v236, v228
	v_mov_b32_e32 v237, v229
	v_mov_b32_e32 v238, v230
	v_mov_b32_e32 v239, v231
	v_mov_b32_dpp v228, v232 row_ror:8 row_mask:0xf bank_mask:0xc
	v_mov_b32_dpp v229, v233 row_ror:8 row_mask:0xf bank_mask:0xc
	v_mov_b32_dpp v230, v234 row_ror:8 row_mask:0xf bank_mask:0xc
	v_mov_b32_dpp v231, v235 row_ror:8 row_mask:0xf bank_mask:0xc
	v_mov_b32_dpp v232, v236 row_ror:8 row_mask:0xf bank_mask:0x3
	v_mov_b32_dpp v233, v237 row_ror:8 row_mask:0xf bank_mask:0x3
	v_mov_b32_dpp v234, v238 row_ror:8 row_mask:0xf bank_mask:0x3
	v_mov_b32_dpp v235, v239 row_ror:8 row_mask:0xf bank_mask:0x3
	s_add_u32 s100, s100, 0x18000
	s_addc_u32 s101, s101, 0
	global_store_dwordx4 v240, v[228:231], s[100:101]
	s_add_u32 s100, s100, 0x18000
	s_addc_u32 s101, s101, 0
	global_store_dwordx4 v240, v[232:235], s[100:101]
	v_cvt_pk_bf16_f32 v228, v20, v21
	v_cvt_pk_bf16_f32 v229, v22, v23
	v_cvt_pk_bf16_f32 v230, v16, v17
	v_cvt_pk_bf16_f32 v231, v18, v19
	v_cvt_pk_bf16_f32 v232, v4, v5
	v_cvt_pk_bf16_f32 v233, v6, v7
	v_cvt_pk_bf16_f32 v234, v0, v1
	v_cvt_pk_bf16_f32 v235, v2, v3
	v_mov_b32_e32 v236, v228
	v_mov_b32_e32 v237, v229
	v_mov_b32_e32 v238, v230
	v_mov_b32_e32 v239, v231
	v_mov_b32_dpp v228, v232 row_ror:8 row_mask:0xf bank_mask:0xc
	v_mov_b32_dpp v229, v233 row_ror:8 row_mask:0xf bank_mask:0xc
	v_mov_b32_dpp v230, v234 row_ror:8 row_mask:0xf bank_mask:0xc
	v_mov_b32_dpp v231, v235 row_ror:8 row_mask:0xf bank_mask:0xc
	v_mov_b32_dpp v232, v236 row_ror:8 row_mask:0xf bank_mask:0x3
	v_mov_b32_dpp v233, v237 row_ror:8 row_mask:0xf bank_mask:0x3
	v_mov_b32_dpp v234, v238 row_ror:8 row_mask:0xf bank_mask:0x3
	v_mov_b32_dpp v235, v239 row_ror:8 row_mask:0xf bank_mask:0x3
	s_add_u32 s100, s100, 0x18000
	s_addc_u32 s101, s101, 0
	global_store_dwordx4 v240, v[228:231], s[100:101]
	s_add_u32 s100, s100, 0x18000
	s_addc_u32 s101, s101, 0
	global_store_dwordx4 v240, v[232:235], s[100:101]
	s_and_b64 vcc, exec, s[2:3]
	s_mov_b32 s35, s8
	s_mov_b32 s6, s10
	s_mov_b64 s[18:19], s[14:15]
	s_mov_b64 s[16:17], s[12:13]
	s_cbranch_vccz .LBB0_151
	s_waitcnt vmcnt(0)
	s_cmpk_gt_u32 s22, 0xff
	s_cbranch_scc1 .LBB0_158
	s_barrier

.LBB0_368:
	ds_read_b128 v[146:149], v143
	ds_read_b128 v[150:153], v143 offset:1024
	ds_read_b128 v[154:157], v143 offset:2048
	ds_read_b128 v[158:161], v143 offset:3072
	s_add_i32 s52, s26, 2
	s_add_u32 s27, s24, 0xfff80080
	s_addc_u32 s28, s25, -1
	s_cmp_eq_u32 s49, s26
	s_cselect_b32 s26, s48, s50
	s_cselect_b32 s29, s7, s28
	s_cselect_b32 s28, s9, s27
	s_cselect_b32 s27, s47, s51
	s_add_i32 m0, s1, 0xc000
	ds_read_b128 v[162:165], v144
	ds_read_b128 v[166:169], v144 offset:1024
	ds_read_b128 v[170:173], v144 offset:2048
	ds_read_b128 v[174:177], v144 offset:3072
	ds_read_b128 v[178:181], v144 offset:4096
	ds_read_b128 v[182:185], v144 offset:5120
	ds_read_b128 v[186:189], v144 offset:6144
	ds_read_b128 v[190:193], v144 offset:7168
	global_load_lds_dwordx4 v136, s[24:25]
	s_add_i32 m0, s1, 0xe000
	s_nop 0
	global_load_lds_dwordx4 v138, s[24:25]
	s_waitcnt lgkmcnt(8)
	s_barrier
	s_waitcnt lgkmcnt(0)
	v_mfma_f32_16x16x32_bf16 v[124:127], v[146:149], v[162:165], v[124:127]
	v_mfma_f32_16x16x32_bf16 v[120:123], v[154:157], v[162:165], v[120:123]
	v_mfma_f32_16x16x32_bf16 v[108:111], v[146:149], v[170:173], v[108:111]
	v_mfma_f32_16x16x32_bf16 v[104:107], v[154:157], v[170:173], v[104:107]
	v_mfma_f32_16x16x32_bf16 v[92:95], v[146:149], v[178:181], v[92:95]
	v_mfma_f32_16x16x32_bf16 v[88:91], v[154:157], v[178:181], v[88:91]
	v_mfma_f32_16x16x32_bf16 v[76:79], v[146:149], v[186:189], v[76:79]
	v_mfma_f32_16x16x32_bf16 v[72:75], v[154:157], v[186:189], v[72:75]
	v_mfma_f32_16x16x32_bf16 v[124:127], v[150:153], v[166:169], v[124:127]
	v_mfma_f32_16x16x32_bf16 v[120:123], v[158:161], v[166:169], v[120:123]
	v_mfma_f32_16x16x32_bf16 v[108:111], v[150:153], v[174:177], v[108:111]
	v_mfma_f32_16x16x32_bf16 v[104:107], v[158:161], v[174:177], v[104:107]
	v_mfma_f32_16x16x32_bf16 v[92:95], v[150:153], v[182:185], v[92:95]
	v_mfma_f32_16x16x32_bf16 v[88:91], v[158:161], v[182:185], v[88:91]
	v_mfma_f32_16x16x32_bf16 v[76:79], v[150:153], v[190:193], v[76:79]
	v_mfma_f32_16x16x32_bf16 v[72:75], v[158:161], v[190:193], v[72:75]
	s_barrier
	s_add_i32 s53, s42, s31
	s_mov_b32 m0, s53
	ds_read_b128 v[194:197], v145
	ds_read_b128 v[198:201], v145 offset:1024
	ds_read_b128 v[204:207], v145 offset:2048
	ds_read_b128 v[208:211], v145 offset:3072
	global_load_lds_dwordx4 v132, s[26:27]
	s_add_i32 m0, s53, 0x2000
	s_nop 0
	global_load_lds_dwordx4 v128, s[26:27]
	s_barrier
	s_waitcnt lgkmcnt(0)
	v_mfma_f32_16x16x32_bf16 v[116:119], v[194:197], v[162:165], v[116:119]
	v_mfma_f32_16x16x32_bf16 v[112:115], v[204:207], v[162:165], v[112:115]
	v_mfma_f32_16x16x32_bf16 v[100:103], v[194:197], v[170:173], v[100:103]
	v_mfma_f32_16x16x32_bf16 v[96:99], v[204:207], v[170:173], v[96:99]
	v_mfma_f32_16x16x32_bf16 v[84:87], v[194:197], v[178:181], v[84:87]
	v_mfma_f32_16x16x32_bf16 v[80:83], v[204:207], v[178:181], v[80:83]
	v_mfma_f32_16x16x32_bf16 v[68:71], v[194:197], v[186:189], v[68:71]
	v_mfma_f32_16x16x32_bf16 v[64:67], v[204:207], v[186:189], v[64:67]
	v_mfma_f32_16x16x32_bf16 v[116:119], v[198:201], v[166:169], v[116:119]
	v_mfma_f32_16x16x32_bf16 v[112:115], v[208:211], v[166:169], v[112:115]
	v_mfma_f32_16x16x32_bf16 v[100:103], v[198:201], v[174:177], v[100:103]
	v_mfma_f32_16x16x32_bf16 v[96:99], v[208:211], v[174:177], v[96:99]
	v_mfma_f32_16x16x32_bf16 v[84:87], v[198:201], v[182:185], v[84:87]
	v_mfma_f32_16x16x32_bf16 v[80:83], v[208:211], v[182:185], v[80:83]
	v_mfma_f32_16x16x32_bf16 v[68:71], v[198:201], v[190:193], v[68:71]
	v_mfma_f32_16x16x32_bf16 v[64:67], v[208:211], v[190:193], v[64:67]
	s_mov_b32 m0, s1
	s_mov_b64 s[98:99], s[28:29]
	s_barrier
	ds_read_b128 v[162:165], v144 offset:16384
	ds_read_b128 v[166:169], v144 offset:17408
	ds_read_b128 v[170:173], v144 offset:18432
	ds_read_b128 v[174:177], v144 offset:19456
	ds_read_b128 v[178:181], v144 offset:20480
	ds_read_b128 v[182:185], v144 offset:21504
	ds_read_b128 v[186:189], v144 offset:22528
	ds_read_b128 v[190:193], v144 offset:23552
	global_load_lds_dwordx4 v134, s[28:29]
	s_mov_b32 m0, s33
	s_nop 0
	global_load_lds_dwordx4 v130, s[28:29]
	s_barrier
	s_waitcnt lgkmcnt(0)
	v_mfma_f32_16x16x32_bf16 v[60:63], v[146:149], v[162:165], v[60:63]
	v_mfma_f32_16x16x32_bf16 v[56:59], v[154:157], v[162:165], v[56:59]
	v_mfma_f32_16x16x32_bf16 v[44:47], v[146:149], v[170:173], v[44:47]
	v_mfma_f32_16x16x32_bf16 v[40:43], v[154:157], v[170:173], v[40:43]
	v_mfma_f32_16x16x32_bf16 v[28:31], v[146:149], v[178:181], v[28:31]
	v_mfma_f32_16x16x32_bf16 v[24:27], v[154:157], v[178:181], v[24:27]
	v_mfma_f32_16x16x32_bf16 v[12:15], v[146:149], v[186:189], v[12:15]
	v_mfma_f32_16x16x32_bf16 v[8:11], v[154:157], v[186:189], v[8:11]
	v_mfma_f32_16x16x32_bf16 v[60:63], v[150:153], v[166:169], v[60:63]
	v_mfma_f32_16x16x32_bf16 v[56:59], v[158:161], v[166:169], v[56:59]
	v_mfma_f32_16x16x32_bf16 v[44:47], v[150:153], v[174:177], v[44:47]
	v_mfma_f32_16x16x32_bf16 v[40:43], v[158:161], v[174:177], v[40:43]
	v_mfma_f32_16x16x32_bf16 v[28:31], v[150:153], v[182:185], v[28:31]
	v_mfma_f32_16x16x32_bf16 v[24:27], v[158:161], v[182:185], v[24:27]
	v_mfma_f32_16x16x32_bf16 v[12:15], v[150:153], v[190:193], v[12:15]
	v_mfma_f32_16x16x32_bf16 v[8:11], v[158:161], v[190:193], v[8:11]
	s_barrier
	s_add_u32 s54, s26, 0x20000
	s_addc_u32 s55, s27, 0
	s_add_i32 s53, s43, s31
	s_mov_b32 m0, s53
	s_nop 0
	global_load_lds_dwordx4 v132, s[54:55]
	s_add_i32 m0, s53, 0x2000
	s_nop 0
	global_load_lds_dwordx4 v128, s[54:55]
	s_waitcnt vmcnt(6)
	s_barrier
	v_mfma_f32_16x16x32_bf16 v[52:55], v[194:197], v[162:165], v[52:55]
	v_mfma_f32_16x16x32_bf16 v[48:51], v[204:207], v[162:165], v[48:51]
	v_mfma_f32_16x16x32_bf16 v[36:39], v[194:197], v[170:173], v[36:39]
	v_mfma_f32_16x16x32_bf16 v[32:35], v[204:207], v[170:173], v[32:35]
	v_mfma_f32_16x16x32_bf16 v[20:23], v[194:197], v[178:181], v[20:23]
	v_mfma_f32_16x16x32_bf16 v[16:19], v[204:207], v[178:181], v[16:19]
	v_mfma_f32_16x16x32_bf16 v[4:7], v[194:197], v[186:189], v[4:7]
	v_mfma_f32_16x16x32_bf16 v[0:3], v[204:207], v[186:189], v[0:3]
	v_mfma_f32_16x16x32_bf16 v[52:55], v[198:201], v[166:169], v[52:55]
	v_mfma_f32_16x16x32_bf16 v[48:51], v[208:211], v[166:169], v[48:51]
	v_mfma_f32_16x16x32_bf16 v[36:39], v[198:201], v[174:177], v[36:39]
	v_mfma_f32_16x16x32_bf16 v[32:35], v[208:211], v[174:177], v[32:35]
	v_mfma_f32_16x16x32_bf16 v[20:23], v[198:201], v[182:185], v[20:23]
	v_mfma_f32_16x16x32_bf16 v[16:19], v[208:211], v[182:185], v[16:19]
	v_mfma_f32_16x16x32_bf16 v[4:7], v[198:201], v[190:193], v[4:7]
	v_mfma_f32_16x16x32_bf16 v[0:3], v[208:211], v[190:193], v[0:3]
	s_add_i32 s53, 0, 0x18000
	v_add_u32_e32 v158, s53, v141
	s_barrier
	ds_read_b128 v[146:149], v158
	ds_read_b128 v[150:153], v158 offset:1024
	ds_read_b128 v[154:157], v158 offset:2048
	ds_read_b128 v[158:161], v158 offset:3072
	s_add_u32 s28, s28, 0x80000
	s_addc_u32 s29, s29, 0
	s_mov_b32 m0, s34
	ds_read_b128 v[162:165], v144 offset:32768
	ds_read_b128 v[166:169], v144 offset:33792
	ds_read_b128 v[170:173], v144 offset:34816
	ds_read_b128 v[174:177], v144 offset:35840
	ds_read_b128 v[178:181], v144 offset:36864
	ds_read_b128 v[182:185], v144 offset:37888
	ds_read_b128 v[186:189], v144 offset:38912
	ds_read_b128 v[190:193], v144 offset:39936
	global_load_lds_dwordx4 v134, s[28:29]
	s_mov_b32 m0, s35
	s_nop 0
	global_load_lds_dwordx4 v130, s[28:29]
	s_waitcnt lgkmcnt(8)
	s_barrier
	s_waitcnt lgkmcnt(0)
	v_mfma_f32_16x16x32_bf16 v[124:127], v[146:149], v[162:165], v[124:127]
	v_mfma_f32_16x16x32_bf16 v[120:123], v[154:157], v[162:165], v[120:123]
	v_mfma_f32_16x16x32_bf16 v[108:111], v[146:149], v[170:173], v[108:111]
	v_mfma_f32_16x16x32_bf16 v[104:107], v[154:157], v[170:173], v[104:107]
	v_mfma_f32_16x16x32_bf16 v[92:95], v[146:149], v[178:181], v[92:95]
	v_mfma_f32_16x16x32_bf16 v[88:91], v[154:157], v[178:181], v[88:91]
	v_mfma_f32_16x16x32_bf16 v[76:79], v[146:149], v[186:189], v[76:79]
	v_mfma_f32_16x16x32_bf16 v[72:75], v[154:157], v[186:189], v[72:75]
	v_mfma_f32_16x16x32_bf16 v[124:127], v[150:153], v[166:169], v[124:127]
	v_mfma_f32_16x16x32_bf16 v[120:123], v[158:161], v[166:169], v[120:123]
	v_mfma_f32_16x16x32_bf16 v[108:111], v[150:153], v[174:177], v[108:111]
	v_mfma_f32_16x16x32_bf16 v[104:107], v[158:161], v[174:177], v[104:107]
	v_mfma_f32_16x16x32_bf16 v[92:95], v[150:153], v[182:185], v[92:95]
	v_mfma_f32_16x16x32_bf16 v[88:91], v[158:161], v[182:185], v[88:91]
	v_mfma_f32_16x16x32_bf16 v[76:79], v[150:153], v[190:193], v[76:79]
	v_mfma_f32_16x16x32_bf16 v[72:75], v[158:161], v[190:193], v[72:75]
	s_barrier
	s_add_i32 s28, 0, 0x1c000
	s_add_i32 s29, s53, s31
	v_add_u32_e32 v208, s28, v141
	s_mov_b32 m0, s29
	ds_read_b128 v[194:197], v208
	ds_read_b128 v[198:201], v208 offset:1024
	ds_read_b128 v[204:207], v208 offset:2048
	ds_read_b128 v[208:211], v208 offset:3072
	s_add_u32 s100, s26, 0x80
	s_addc_u32 s101, s27, 0
	global_load_lds_dwordx4 v132, s[100:101]
	s_add_i32 m0, s29, 0x2000
	s_nop 0
	s_add_u32 s100, s26, 0x80
	s_addc_u32 s101, s27, 0
	global_load_lds_dwordx4 v128, s[100:101]
	s_barrier
	s_waitcnt lgkmcnt(0)
	v_mfma_f32_16x16x32_bf16 v[116:119], v[194:197], v[162:165], v[116:119]
	v_mfma_f32_16x16x32_bf16 v[112:115], v[204:207], v[162:165], v[112:115]
	v_mfma_f32_16x16x32_bf16 v[100:103], v[194:197], v[170:173], v[100:103]
	v_mfma_f32_16x16x32_bf16 v[96:99], v[204:207], v[170:173], v[96:99]
	v_mfma_f32_16x16x32_bf16 v[84:87], v[194:197], v[178:181], v[84:87]
	v_mfma_f32_16x16x32_bf16 v[80:83], v[204:207], v[178:181], v[80:83]
	v_mfma_f32_16x16x32_bf16 v[68:71], v[194:197], v[186:189], v[68:71]
	v_mfma_f32_16x16x32_bf16 v[64:67], v[204:207], v[186:189], v[64:67]
	v_mfma_f32_16x16x32_bf16 v[116:119], v[198:201], v[166:169], v[116:119]
	v_mfma_f32_16x16x32_bf16 v[112:115], v[208:211], v[166:169], v[112:115]
	v_mfma_f32_16x16x32_bf16 v[100:103], v[198:201], v[174:177], v[100:103]
	v_mfma_f32_16x16x32_bf16 v[96:99], v[208:211], v[174:177], v[96:99]
	v_mfma_f32_16x16x32_bf16 v[84:87], v[198:201], v[182:185], v[84:87]
	v_mfma_f32_16x16x32_bf16 v[80:83], v[208:211], v[182:185], v[80:83]
	v_mfma_f32_16x16x32_bf16 v[68:71], v[198:201], v[190:193], v[68:71]
	v_mfma_f32_16x16x32_bf16 v[64:67], v[208:211], v[190:193], v[64:67]
	s_mov_b32 m0, s40
	s_barrier
	ds_read_b128 v[162:165], v144 offset:49152
	ds_read_b128 v[166:169], v144 offset:50176
	ds_read_b128 v[170:173], v144 offset:51200
	ds_read_b128 v[174:177], v144 offset:52224
	ds_read_b128 v[178:181], v144 offset:53248
	ds_read_b128 v[182:185], v144 offset:54272
	ds_read_b128 v[186:189], v144 offset:55296
	ds_read_b128 v[190:193], v144 offset:56320
	s_add_u32 s100, s98, 0x80
	s_addc_u32 s101, s99, 0
	global_load_lds_dwordx4 v134, s[100:101]
	s_mov_b32 m0, s41
	s_nop 0
	s_add_u32 s100, s98, 0x80
	s_addc_u32 s101, s99, 0
	global_load_lds_dwordx4 v130, s[100:101]
	s_barrier
	s_waitcnt lgkmcnt(0)
	v_mfma_f32_16x16x32_bf16 v[60:63], v[146:149], v[162:165], v[60:63]
	v_mfma_f32_16x16x32_bf16 v[56:59], v[154:157], v[162:165], v[56:59]
	v_mfma_f32_16x16x32_bf16 v[44:47], v[146:149], v[170:173], v[44:47]
	v_mfma_f32_16x16x32_bf16 v[40:43], v[154:157], v[170:173], v[40:43]
	v_mfma_f32_16x16x32_bf16 v[28:31], v[146:149], v[178:181], v[28:31]
	v_mfma_f32_16x16x32_bf16 v[24:27], v[154:157], v[178:181], v[24:27]
	v_mfma_f32_16x16x32_bf16 v[12:15], v[146:149], v[186:189], v[12:15]
	v_mfma_f32_16x16x32_bf16 v[8:11], v[154:157], v[186:189], v[8:11]
	v_mfma_f32_16x16x32_bf16 v[60:63], v[150:153], v[166:169], v[60:63]
	v_mfma_f32_16x16x32_bf16 v[56:59], v[158:161], v[166:169], v[56:59]
	v_mfma_f32_16x16x32_bf16 v[44:47], v[150:153], v[174:177], v[44:47]
	v_mfma_f32_16x16x32_bf16 v[40:43], v[158:161], v[174:177], v[40:43]
	v_mfma_f32_16x16x32_bf16 v[28:31], v[150:153], v[182:185], v[28:31]
	v_mfma_f32_16x16x32_bf16 v[24:27], v[158:161], v[182:185], v[24:27]
	v_mfma_f32_16x16x32_bf16 v[12:15], v[150:153], v[190:193], v[12:15]
	v_mfma_f32_16x16x32_bf16 v[8:11], v[158:161], v[190:193], v[8:11]
	s_barrier
	s_add_u32 s26, s26, 0x20080
	s_addc_u32 s27, s27, 0
	s_add_i32 s28, s28, s31
	s_mov_b32 m0, s28
	s_nop 0
	global_load_lds_dwordx4 v132, s[26:27]
	s_add_i32 m0, s28, 0x2000
	s_nop 0
	global_load_lds_dwordx4 v128, s[26:27]
	s_waitcnt vmcnt(6)
	s_barrier
	v_mfma_f32_16x16x32_bf16 v[52:55], v[194:197], v[162:165], v[52:55]
	v_mfma_f32_16x16x32_bf16 v[48:51], v[204:207], v[162:165], v[48:51]
	v_mfma_f32_16x16x32_bf16 v[36:39], v[194:197], v[170:173], v[36:39]
	v_mfma_f32_16x16x32_bf16 v[32:35], v[204:207], v[170:173], v[32:35]
	v_mfma_f32_16x16x32_bf16 v[20:23], v[194:197], v[178:181], v[20:23]
	v_mfma_f32_16x16x32_bf16 v[16:19], v[204:207], v[178:181], v[16:19]
	v_mfma_f32_16x16x32_bf16 v[4:7], v[194:197], v[186:189], v[4:7]
	v_mfma_f32_16x16x32_bf16 v[0:3], v[204:207], v[186:189], v[0:3]
	v_mfma_f32_16x16x32_bf16 v[52:55], v[198:201], v[166:169], v[52:55]
	v_mfma_f32_16x16x32_bf16 v[48:51], v[208:211], v[166:169], v[48:51]
	v_mfma_f32_16x16x32_bf16 v[36:39], v[198:201], v[174:177], v[36:39]
	v_mfma_f32_16x16x32_bf16 v[32:35], v[208:211], v[174:177], v[32:35]
	v_mfma_f32_16x16x32_bf16 v[20:23], v[198:201], v[182:185], v[20:23]
	v_mfma_f32_16x16x32_bf16 v[16:19], v[208:211], v[182:185], v[16:19]
	v_mfma_f32_16x16x32_bf16 v[4:7], v[198:201], v[190:193], v[4:7]
	v_mfma_f32_16x16x32_bf16 v[0:3], v[208:211], v[190:193], v[0:3]
	s_add_u32 s24, s24, 0x100
	s_addc_u32 s25, s25, 0
	s_add_u32 s50, s50, 0x100
	s_addc_u32 s51, s51, 0
	s_cmp_ge_i32 s52, s46
	s_mov_b32 s26, s52
	s_barrier
	s_cbranch_scc0 .LBB0_368
	s_branch .LBB0_363

.LBB0_531:
	ds_read_b128 v[152:155], v149
	ds_read_b128 v[156:159], v149 offset:1024
	ds_read_b128 v[160:163], v149 offset:2048
	ds_read_b128 v[164:167], v149 offset:3072
	s_add_u32 s24, s22, 0xfff80080
	s_addc_u32 s25, s23, -1
	s_cmp_eq_u32 s45, 28
	s_cselect_b32 s27, s15, s25
	s_cselect_b32 s26, s41, s24
	s_cselect_b32 s25, s9, s44
	s_cselect_b32 s24, s42, s43
	s_add_i32 m0, s21, 0xc000
	ds_read_b128 v[168:171], v150
	ds_read_b128 v[172:175], v150 offset:1024
	ds_read_b128 v[176:179], v150 offset:2048
	ds_read_b128 v[180:183], v150 offset:3072
	ds_read_b128 v[184:187], v150 offset:4096
	ds_read_b128 v[188:191], v150 offset:5120
	ds_read_b128 v[192:195], v150 offset:6144
	ds_read_b128 v[196:199], v150 offset:7168
	global_load_lds_dwordx4 v136, s[22:23]
	s_add_i32 m0, s21, 0xe000
	s_nop 0
	global_load_lds_dwordx4 v138, s[22:23]
	s_waitcnt lgkmcnt(8)
	s_barrier
	s_waitcnt lgkmcnt(0)
	v_mfma_f32_16x16x32_bf16 v[124:127], v[152:155], v[168:171], v[124:127]
	v_mfma_f32_16x16x32_bf16 v[120:123], v[160:163], v[168:171], v[120:123]
	v_mfma_f32_16x16x32_bf16 v[108:111], v[152:155], v[176:179], v[108:111]
	v_mfma_f32_16x16x32_bf16 v[104:107], v[160:163], v[176:179], v[104:107]
	v_mfma_f32_16x16x32_bf16 v[92:95], v[152:155], v[184:187], v[92:95]
	v_mfma_f32_16x16x32_bf16 v[88:91], v[160:163], v[184:187], v[88:91]
	v_mfma_f32_16x16x32_bf16 v[76:79], v[152:155], v[192:195], v[76:79]
	v_mfma_f32_16x16x32_bf16 v[72:75], v[160:163], v[192:195], v[72:75]
	v_mfma_f32_16x16x32_bf16 v[124:127], v[156:159], v[172:175], v[124:127]
	v_mfma_f32_16x16x32_bf16 v[120:123], v[164:167], v[172:175], v[120:123]
	v_mfma_f32_16x16x32_bf16 v[108:111], v[156:159], v[180:183], v[108:111]
	v_mfma_f32_16x16x32_bf16 v[104:107], v[164:167], v[180:183], v[104:107]
	v_mfma_f32_16x16x32_bf16 v[92:95], v[156:159], v[188:191], v[92:95]
	v_mfma_f32_16x16x32_bf16 v[88:91], v[164:167], v[188:191], v[88:91]
	v_mfma_f32_16x16x32_bf16 v[76:79], v[156:159], v[196:199], v[76:79]
	v_mfma_f32_16x16x32_bf16 v[72:75], v[164:167], v[196:199], v[72:75]
	s_barrier
	s_add_i32 s46, s38, s29
	s_mov_b32 m0, s46
	ds_read_b128 v[204:207], v151
	ds_read_b128 v[208:211], v151 offset:1024
	ds_read_b128 v[212:215], v151 offset:2048
	ds_read_b128 v[216:219], v151 offset:3072
	global_load_lds_dwordx4 v132, s[24:25]
	s_add_i32 m0, s46, 0x2000
	s_nop 0
	global_load_lds_dwordx4 v128, s[24:25]
	s_barrier
	s_waitcnt lgkmcnt(0)
	v_mfma_f32_16x16x32_bf16 v[116:119], v[204:207], v[168:171], v[116:119]
	v_mfma_f32_16x16x32_bf16 v[112:115], v[212:215], v[168:171], v[112:115]
	v_mfma_f32_16x16x32_bf16 v[100:103], v[204:207], v[176:179], v[100:103]
	v_mfma_f32_16x16x32_bf16 v[96:99], v[212:215], v[176:179], v[96:99]
	v_mfma_f32_16x16x32_bf16 v[84:87], v[204:207], v[184:187], v[84:87]
	v_mfma_f32_16x16x32_bf16 v[80:83], v[212:215], v[184:187], v[80:83]
	v_mfma_f32_16x16x32_bf16 v[68:71], v[204:207], v[192:195], v[68:71]
	v_mfma_f32_16x16x32_bf16 v[64:67], v[212:215], v[192:195], v[64:67]
	v_mfma_f32_16x16x32_bf16 v[116:119], v[208:211], v[172:175], v[116:119]
	v_mfma_f32_16x16x32_bf16 v[112:115], v[216:219], v[172:175], v[112:115]
	v_mfma_f32_16x16x32_bf16 v[100:103], v[208:211], v[180:183], v[100:103]
	v_mfma_f32_16x16x32_bf16 v[96:99], v[216:219], v[180:183], v[96:99]
	v_mfma_f32_16x16x32_bf16 v[84:87], v[208:211], v[188:191], v[84:87]
	v_mfma_f32_16x16x32_bf16 v[80:83], v[216:219], v[188:191], v[80:83]
	v_mfma_f32_16x16x32_bf16 v[68:71], v[208:211], v[196:199], v[68:71]
	v_mfma_f32_16x16x32_bf16 v[64:67], v[216:219], v[196:199], v[64:67]
	s_mov_b32 m0, s21
	s_mov_b64 s[98:99], s[26:27]
	s_barrier
	ds_read_b128 v[168:171], v150 offset:16384
	ds_read_b128 v[172:175], v150 offset:17408
	ds_read_b128 v[176:179], v150 offset:18432
	ds_read_b128 v[180:183], v150 offset:19456
	ds_read_b128 v[184:187], v150 offset:20480
	ds_read_b128 v[188:191], v150 offset:21504
	ds_read_b128 v[192:195], v150 offset:22528
	ds_read_b128 v[196:199], v150 offset:23552
	global_load_lds_dwordx4 v134, s[26:27]
	s_mov_b32 m0, s31
	s_nop 0
	global_load_lds_dwordx4 v130, s[26:27]
	s_barrier
	s_waitcnt lgkmcnt(0)
	v_mfma_f32_16x16x32_bf16 v[60:63], v[152:155], v[168:171], v[60:63]
	v_mfma_f32_16x16x32_bf16 v[56:59], v[160:163], v[168:171], v[56:59]
	v_mfma_f32_16x16x32_bf16 v[44:47], v[152:155], v[176:179], v[44:47]
	v_mfma_f32_16x16x32_bf16 v[40:43], v[160:163], v[176:179], v[40:43]
	v_mfma_f32_16x16x32_bf16 v[28:31], v[152:155], v[184:187], v[28:31]
	v_mfma_f32_16x16x32_bf16 v[24:27], v[160:163], v[184:187], v[24:27]
	v_mfma_f32_16x16x32_bf16 v[12:15], v[152:155], v[192:195], v[12:15]
	v_mfma_f32_16x16x32_bf16 v[8:11], v[160:163], v[192:195], v[8:11]
	v_mfma_f32_16x16x32_bf16 v[60:63], v[156:159], v[172:175], v[60:63]
	v_mfma_f32_16x16x32_bf16 v[56:59], v[164:167], v[172:175], v[56:59]
	v_mfma_f32_16x16x32_bf16 v[44:47], v[156:159], v[180:183], v[44:47]
	v_mfma_f32_16x16x32_bf16 v[40:43], v[164:167], v[180:183], v[40:43]
	v_mfma_f32_16x16x32_bf16 v[28:31], v[156:159], v[188:191], v[28:31]
	v_mfma_f32_16x16x32_bf16 v[24:27], v[164:167], v[188:191], v[24:27]
	v_mfma_f32_16x16x32_bf16 v[12:15], v[156:159], v[196:199], v[12:15]
	v_mfma_f32_16x16x32_bf16 v[8:11], v[164:167], v[196:199], v[8:11]
	s_barrier
	s_add_u32 s46, s24, 0x20000
	s_addc_u32 s47, s25, 0
	s_add_i32 s48, s39, s29
	s_mov_b32 m0, s48
	s_nop 0
	global_load_lds_dwordx4 v132, s[46:47]
	s_add_i32 m0, s48, 0x2000
	s_nop 0
	global_load_lds_dwordx4 v128, s[46:47]
	s_waitcnt vmcnt(6)
	s_barrier
	v_mfma_f32_16x16x32_bf16 v[52:55], v[204:207], v[168:171], v[52:55]
	v_mfma_f32_16x16x32_bf16 v[48:51], v[212:215], v[168:171], v[48:51]
	v_mfma_f32_16x16x32_bf16 v[36:39], v[204:207], v[176:179], v[36:39]
	v_mfma_f32_16x16x32_bf16 v[32:35], v[212:215], v[176:179], v[32:35]
	v_mfma_f32_16x16x32_bf16 v[20:23], v[204:207], v[184:187], v[20:23]
	v_mfma_f32_16x16x32_bf16 v[16:19], v[212:215], v[184:187], v[16:19]
	v_mfma_f32_16x16x32_bf16 v[4:7], v[204:207], v[192:195], v[4:7]
	v_mfma_f32_16x16x32_bf16 v[0:3], v[212:215], v[192:195], v[0:3]
	v_mfma_f32_16x16x32_bf16 v[52:55], v[208:211], v[172:175], v[52:55]
	v_mfma_f32_16x16x32_bf16 v[48:51], v[216:219], v[172:175], v[48:51]
	v_mfma_f32_16x16x32_bf16 v[36:39], v[208:211], v[180:183], v[36:39]
	v_mfma_f32_16x16x32_bf16 v[32:35], v[216:219], v[180:183], v[32:35]
	v_mfma_f32_16x16x32_bf16 v[20:23], v[208:211], v[188:191], v[20:23]
	v_mfma_f32_16x16x32_bf16 v[16:19], v[216:219], v[188:191], v[16:19]
	v_mfma_f32_16x16x32_bf16 v[4:7], v[208:211], v[196:199], v[4:7]
	v_mfma_f32_16x16x32_bf16 v[0:3], v[216:219], v[196:199], v[0:3]
	s_add_i32 s46, 0, 0x18000
	v_add_u32_e32 v164, s46, v147
	s_barrier
	ds_read_b128 v[152:155], v164
	ds_read_b128 v[156:159], v164 offset:1024
	ds_read_b128 v[160:163], v164 offset:2048
	ds_read_b128 v[164:167], v164 offset:3072
	s_add_u32 s26, s26, 0x80000
	s_addc_u32 s27, s27, 0
	s_mov_b32 m0, s33
	ds_read_b128 v[168:171], v150 offset:32768
	ds_read_b128 v[172:175], v150 offset:33792
	ds_read_b128 v[176:179], v150 offset:34816
	ds_read_b128 v[180:183], v150 offset:35840
	ds_read_b128 v[184:187], v150 offset:36864
	ds_read_b128 v[188:191], v150 offset:37888
	ds_read_b128 v[192:195], v150 offset:38912
	ds_read_b128 v[196:199], v150 offset:39936
	global_load_lds_dwordx4 v134, s[26:27]
	s_mov_b32 m0, s34
	s_nop 0
	global_load_lds_dwordx4 v130, s[26:27]
	s_waitcnt lgkmcnt(8)
	s_barrier
	s_waitcnt lgkmcnt(0)
	v_mfma_f32_16x16x32_bf16 v[124:127], v[152:155], v[168:171], v[124:127]
	v_mfma_f32_16x16x32_bf16 v[120:123], v[160:163], v[168:171], v[120:123]
	v_mfma_f32_16x16x32_bf16 v[108:111], v[152:155], v[176:179], v[108:111]
	v_mfma_f32_16x16x32_bf16 v[104:107], v[160:163], v[176:179], v[104:107]
	v_mfma_f32_16x16x32_bf16 v[92:95], v[152:155], v[184:187], v[92:95]
	v_mfma_f32_16x16x32_bf16 v[88:91], v[160:163], v[184:187], v[88:91]
	v_mfma_f32_16x16x32_bf16 v[76:79], v[152:155], v[192:195], v[76:79]
	v_mfma_f32_16x16x32_bf16 v[72:75], v[160:163], v[192:195], v[72:75]
	v_mfma_f32_16x16x32_bf16 v[124:127], v[156:159], v[172:175], v[124:127]
	v_mfma_f32_16x16x32_bf16 v[120:123], v[164:167], v[172:175], v[120:123]
	v_mfma_f32_16x16x32_bf16 v[108:111], v[156:159], v[180:183], v[108:111]
	v_mfma_f32_16x16x32_bf16 v[104:107], v[164:167], v[180:183], v[104:107]
	v_mfma_f32_16x16x32_bf16 v[92:95], v[156:159], v[188:191], v[92:95]
	v_mfma_f32_16x16x32_bf16 v[88:91], v[164:167], v[188:191], v[88:91]
	v_mfma_f32_16x16x32_bf16 v[76:79], v[156:159], v[196:199], v[76:79]
	v_mfma_f32_16x16x32_bf16 v[72:75], v[164:167], v[196:199], v[72:75]
	s_barrier
	s_add_i32 s26, 0, 0x1c000
	s_add_i32 s27, s46, s29
	v_add_u32_e32 v216, s26, v147
	s_mov_b32 m0, s27
	ds_read_b128 v[204:207], v216
	ds_read_b128 v[208:211], v216 offset:1024
	ds_read_b128 v[212:215], v216 offset:2048
	ds_read_b128 v[216:219], v216 offset:3072
	s_add_u32 s100, s24, 0x80
	s_addc_u32 s101, s25, 0
	global_load_lds_dwordx4 v132, s[100:101]
	s_add_i32 m0, s27, 0x2000
	s_nop 0
	s_add_u32 s100, s24, 0x80
	s_addc_u32 s101, s25, 0
	global_load_lds_dwordx4 v128, s[100:101]
	s_barrier
	s_waitcnt lgkmcnt(0)
	v_mfma_f32_16x16x32_bf16 v[116:119], v[204:207], v[168:171], v[116:119]
	v_mfma_f32_16x16x32_bf16 v[112:115], v[212:215], v[168:171], v[112:115]
	v_mfma_f32_16x16x32_bf16 v[100:103], v[204:207], v[176:179], v[100:103]
	v_mfma_f32_16x16x32_bf16 v[96:99], v[212:215], v[176:179], v[96:99]
	v_mfma_f32_16x16x32_bf16 v[84:87], v[204:207], v[184:187], v[84:87]
	v_mfma_f32_16x16x32_bf16 v[80:83], v[212:215], v[184:187], v[80:83]
	v_mfma_f32_16x16x32_bf16 v[68:71], v[204:207], v[192:195], v[68:71]
	v_mfma_f32_16x16x32_bf16 v[64:67], v[212:215], v[192:195], v[64:67]
	v_mfma_f32_16x16x32_bf16 v[116:119], v[208:211], v[172:175], v[116:119]
	v_mfma_f32_16x16x32_bf16 v[112:115], v[216:219], v[172:175], v[112:115]
	v_mfma_f32_16x16x32_bf16 v[100:103], v[208:211], v[180:183], v[100:103]
	v_mfma_f32_16x16x32_bf16 v[96:99], v[216:219], v[180:183], v[96:99]
	v_mfma_f32_16x16x32_bf16 v[84:87], v[208:211], v[188:191], v[84:87]
	v_mfma_f32_16x16x32_bf16 v[80:83], v[216:219], v[188:191], v[80:83]
	v_mfma_f32_16x16x32_bf16 v[68:71], v[208:211], v[196:199], v[68:71]
	v_mfma_f32_16x16x32_bf16 v[64:67], v[216:219], v[196:199], v[64:67]
	s_mov_b32 m0, s36
	s_barrier
	ds_read_b128 v[168:171], v150 offset:49152
	ds_read_b128 v[172:175], v150 offset:50176
	ds_read_b128 v[176:179], v150 offset:51200
	ds_read_b128 v[180:183], v150 offset:52224
	ds_read_b128 v[184:187], v150 offset:53248
	ds_read_b128 v[188:191], v150 offset:54272
	ds_read_b128 v[192:195], v150 offset:55296
	ds_read_b128 v[196:199], v150 offset:56320
	s_add_u32 s100, s98, 0x80
	s_addc_u32 s101, s99, 0
	global_load_lds_dwordx4 v134, s[100:101]
	s_mov_b32 m0, s37
	s_nop 0
	s_add_u32 s100, s98, 0x80
	s_addc_u32 s101, s99, 0
	global_load_lds_dwordx4 v130, s[100:101]
	s_barrier
	s_waitcnt lgkmcnt(0)
	v_mfma_f32_16x16x32_bf16 v[60:63], v[152:155], v[168:171], v[60:63]
	v_mfma_f32_16x16x32_bf16 v[56:59], v[160:163], v[168:171], v[56:59]
	v_mfma_f32_16x16x32_bf16 v[44:47], v[152:155], v[176:179], v[44:47]
	v_mfma_f32_16x16x32_bf16 v[40:43], v[160:163], v[176:179], v[40:43]
	v_mfma_f32_16x16x32_bf16 v[28:31], v[152:155], v[184:187], v[28:31]
	v_mfma_f32_16x16x32_bf16 v[24:27], v[160:163], v[184:187], v[24:27]
	v_mfma_f32_16x16x32_bf16 v[12:15], v[152:155], v[192:195], v[12:15]
	v_mfma_f32_16x16x32_bf16 v[8:11], v[160:163], v[192:195], v[8:11]
	v_mfma_f32_16x16x32_bf16 v[60:63], v[156:159], v[172:175], v[60:63]
	v_mfma_f32_16x16x32_bf16 v[56:59], v[164:167], v[172:175], v[56:59]
	v_mfma_f32_16x16x32_bf16 v[44:47], v[156:159], v[180:183], v[44:47]
	v_mfma_f32_16x16x32_bf16 v[40:43], v[164:167], v[180:183], v[40:43]
	v_mfma_f32_16x16x32_bf16 v[28:31], v[156:159], v[188:191], v[28:31]
	v_mfma_f32_16x16x32_bf16 v[24:27], v[164:167], v[188:191], v[24:27]
	v_mfma_f32_16x16x32_bf16 v[12:15], v[156:159], v[196:199], v[12:15]
	v_mfma_f32_16x16x32_bf16 v[8:11], v[164:167], v[196:199], v[8:11]
	s_barrier
	s_add_u32 s24, s24, 0x20080
	s_addc_u32 s25, s25, 0
	s_add_i32 s26, s26, s29
	s_mov_b32 m0, s26
	s_nop 0
	global_load_lds_dwordx4 v132, s[24:25]
	s_add_i32 m0, s26, 0x2000
	s_nop 0
	global_load_lds_dwordx4 v128, s[24:25]
	s_waitcnt vmcnt(6)
	s_barrier
	v_mfma_f32_16x16x32_bf16 v[52:55], v[204:207], v[168:171], v[52:55]
	v_mfma_f32_16x16x32_bf16 v[48:51], v[212:215], v[168:171], v[48:51]
	v_mfma_f32_16x16x32_bf16 v[36:39], v[204:207], v[176:179], v[36:39]
	v_mfma_f32_16x16x32_bf16 v[32:35], v[212:215], v[176:179], v[32:35]
	v_mfma_f32_16x16x32_bf16 v[20:23], v[204:207], v[184:187], v[20:23]
	v_mfma_f32_16x16x32_bf16 v[16:19], v[212:215], v[184:187], v[16:19]
	v_mfma_f32_16x16x32_bf16 v[4:7], v[204:207], v[192:195], v[4:7]
	v_mfma_f32_16x16x32_bf16 v[0:3], v[212:215], v[192:195], v[0:3]
	v_mfma_f32_16x16x32_bf16 v[52:55], v[208:211], v[172:175], v[52:55]
	v_mfma_f32_16x16x32_bf16 v[48:51], v[216:219], v[172:175], v[48:51]
	v_mfma_f32_16x16x32_bf16 v[36:39], v[208:211], v[180:183], v[36:39]
	v_mfma_f32_16x16x32_bf16 v[32:35], v[216:219], v[180:183], v[32:35]
	v_mfma_f32_16x16x32_bf16 v[20:23], v[208:211], v[188:191], v[20:23]
	v_mfma_f32_16x16x32_bf16 v[16:19], v[216:219], v[188:191], v[16:19]
	v_mfma_f32_16x16x32_bf16 v[4:7], v[208:211], v[196:199], v[4:7]
	v_mfma_f32_16x16x32_bf16 v[0:3], v[216:219], v[196:199], v[0:3]
	s_add_i32 s45, s45, 2
	s_add_u32 s22, s22, 0x100
	s_addc_u32 s23, s23, 0
	s_add_u32 s43, s43, 0x100
	s_addc_u32 s44, s44, 0
	s_cmp_gt_u32 s45, 29
	s_barrier
	s_cbranch_scc0 .LBB0_531
	v_readlane_b32 s100, v248, 63
	v_readlane_b32 s101, v247, 0
	v_and_b32_e32 v242, 15, v202
	v_bfe_u32 v243, v202, 4, 2
	v_bfe_u32 v244, v202, 6, 2
	v_lshrrev_b32_e32 v245, 8, v202
	v_and_b32_e32 v240, 7, v242
	v_lshl_add_u32 v240, v245, 6, v240
	v_lshl_add_u32 v240, s20, 8, v240
	v_lshlrev_b32_e32 v240, 14, v240
	v_lshrrev_b32_e32 v241, 3, v242
	v_lshlrev_b32_e32 v241, 6, v241
	v_lshl_add_u32 v241, v244, 7, v241
	v_lshl_add_u32 v241, v243, 4, v241
	v_add_u32_e32 v240, v240, v241
	s_lshl_b32 s98, s40, 9
	v_add_u32_e32 v240, s98, v240
	v_max_f32_e32 v124, 0, v124
	v_max_f32_e32 v125, 0, v125
	v_max_f32_e32 v126, 0, v126
	v_max_f32_e32 v127, 0, v127
	v_max_f32_e32 v120, 0, v120
	v_max_f32_e32 v121, 0, v121
	v_max_f32_e32 v122, 0, v122
	v_max_f32_e32 v123, 0, v123
	v_pk_mul_f32 v[124:125], v[124:125], v[124:125]
	v_pk_mul_f32 v[126:127], v[126:127], v[126:127]
	v_pk_mul_f32 v[120:121], v[120:121], v[120:121]
	v_pk_mul_f32 v[122:123], v[122:123], v[122:123]
	v_cvt_pk_bf16_f32 v228, v124, v125
	v_cvt_pk_bf16_f32 v229, v126, v127
	v_cvt_pk_bf16_f32 v230, v120, v121
	v_cvt_pk_bf16_f32 v231, v122, v123
	v_max_f32_e32 v116, 0, v116
	v_max_f32_e32 v117, 0, v117
	v_max_f32_e32 v118, 0, v118
	v_max_f32_e32 v119, 0, v119
	v_max_f32_e32 v112, 0, v112
	v_max_f32_e32 v113, 0, v113
	v_max_f32_e32 v114, 0, v114
	v_max_f32_e32 v115, 0, v115
	v_pk_mul_f32 v[116:117], v[116:117], v[116:117]
	v_pk_mul_f32 v[118:119], v[118:119], v[118:119]
	v_pk_mul_f32 v[112:113], v[112:113], v[112:113]
	v_pk_mul_f32 v[114:115], v[114:115], v[114:115]
	v_cvt_pk_bf16_f32 v232, v116, v117
	v_cvt_pk_bf16_f32 v233, v118, v119
	v_cvt_pk_bf16_f32 v234, v112, v113
	v_cvt_pk_bf16_f32 v235, v114, v115
	v_mov_b32_e32 v236, v228
	v_mov_b32_e32 v237, v229
	v_mov_b32_e32 v238, v230
	v_mov_b32_e32 v239, v231
	v_mov_b32_dpp v228, v232 row_ror:8 row_mask:0xf bank_mask:0xc
	v_mov_b32_dpp v229, v233 row_ror:8 row_mask:0xf bank_mask:0xc
	v_mov_b32_dpp v230, v234 row_ror:8 row_mask:0xf bank_mask:0xc
	v_mov_b32_dpp v231, v235 row_ror:8 row_mask:0xf bank_mask:0xc
	v_mov_b32_dpp v232, v236 row_ror:8 row_mask:0xf bank_mask:0x3
	v_mov_b32_dpp v233, v237 row_ror:8 row_mask:0xf bank_mask:0x3
	v_mov_b32_dpp v234, v238 row_ror:8 row_mask:0xf bank_mask:0x3
	v_mov_b32_dpp v235, v239 row_ror:8 row_mask:0xf bank_mask:0x3
	global_store_dwordx4 v240, v[228:231], s[100:101]
	s_add_u32 s100, s100, 0x20000
	s_addc_u32 s101, s101, 0
	global_store_dwordx4 v240, v[232:235], s[100:101]
	v_max_f32_e32 v108, 0, v108
	v_max_f32_e32 v109, 0, v109
	v_max_f32_e32 v110, 0, v110
	v_max_f32_e32 v111, 0, v111
	v_max_f32_e32 v104, 0, v104
	v_max_f32_e32 v105, 0, v105
	v_max_f32_e32 v106, 0, v106
	v_max_f32_e32 v107, 0, v107
	v_pk_mul_f32 v[108:109], v[108:109], v[108:109]
	v_pk_mul_f32 v[110:111], v[110:111], v[110:111]
	v_pk_mul_f32 v[104:105], v[104:105], v[104:105]
	v_pk_mul_f32 v[106:107], v[106:107], v[106:107]
	v_cvt_pk_bf16_f32 v228, v108, v109
	v_cvt_pk_bf16_f32 v229, v110, v111
	v_cvt_pk_bf16_f32 v230, v104, v105
	v_cvt_pk_bf16_f32 v231, v106, v107
	v_max_f32_e32 v100, 0, v100
	v_max_f32_e32 v101, 0, v101
	v_max_f32_e32 v102, 0, v102
	v_max_f32_e32 v103, 0, v103
	v_max_f32_e32 v96, 0, v96
	v_max_f32_e32 v97, 0, v97
	v_max_f32_e32 v98, 0, v98
	v_max_f32_e32 v99, 0, v99
	v_pk_mul_f32 v[100:101], v[100:101], v[100:101]
	v_pk_mul_f32 v[102:103], v[102:103], v[102:103]
	v_pk_mul_f32 v[96:97], v[96:97], v[96:97]
	v_pk_mul_f32 v[98:99], v[98:99], v[98:99]
	v_cvt_pk_bf16_f32 v232, v100, v101
	v_cvt_pk_bf16_f32 v233, v102, v103
	v_cvt_pk_bf16_f32 v234, v96, v97
	v_cvt_pk_bf16_f32 v235, v98, v99
	v_mov_b32_e32 v236, v228
	v_mov_b32_e32 v237, v229
	v_mov_b32_e32 v238, v230
	v_mov_b32_e32 v239, v231
	v_mov_b32_dpp v228, v232 row_ror:8 row_mask:0xf bank_mask:0xc
	v_mov_b32_dpp v229, v233 row_ror:8 row_mask:0xf bank_mask:0xc
	v_mov_b32_dpp v230, v234 row_ror:8 row_mask:0xf bank_mask:0xc
	v_mov_b32_dpp v231, v235 row_ror:8 row_mask:0xf bank_mask:0xc
	v_mov_b32_dpp v232, v236 row_ror:8 row_mask:0xf bank_mask:0x3
	v_mov_b32_dpp v233, v237 row_ror:8 row_mask:0xf bank_mask:0x3
	v_mov_b32_dpp v234, v238 row_ror:8 row_mask:0xf bank_mask:0x3
	v_mov_b32_dpp v235, v239 row_ror:8 row_mask:0xf bank_mask:0x3
	s_add_u32 s100, s100, 0x20000
	s_addc_u32 s101, s101, 0
	global_store_dwordx4 v240, v[228:231], s[100:101]
	s_add_u32 s100, s100, 0x20000
	s_addc_u32 s101, s101, 0
	global_store_dwordx4 v240, v[232:235], s[100:101]
	v_max_f32_e32 v92, 0, v92
	v_max_f32_e32 v93, 0, v93
	v_max_f32_e32 v94, 0, v94
	v_max_f32_e32 v95, 0, v95
	v_max_f32_e32 v88, 0, v88
	v_max_f32_e32 v89, 0, v89
	v_max_f32_e32 v90, 0, v90
	v_max_f32_e32 v91, 0, v91
	v_pk_mul_f32 v[92:93], v[92:93], v[92:93]
	v_pk_mul_f32 v[94:95], v[94:95], v[94:95]
	v_pk_mul_f32 v[88:89], v[88:89], v[88:89]
	v_pk_mul_f32 v[90:91], v[90:91], v[90:91]
	v_cvt_pk_bf16_f32 v228, v92, v93
	v_cvt_pk_bf16_f32 v229, v94, v95
	v_cvt_pk_bf16_f32 v230, v88, v89
	v_cvt_pk_bf16_f32 v231, v90, v91
	v_max_f32_e32 v84, 0, v84
	v_max_f32_e32 v85, 0, v85
	v_max_f32_e32 v86, 0, v86
	v_max_f32_e32 v87, 0, v87
	v_max_f32_e32 v80, 0, v80
	v_max_f32_e32 v81, 0, v81
	v_max_f32_e32 v82, 0, v82
	v_max_f32_e32 v83, 0, v83
	v_pk_mul_f32 v[84:85], v[84:85], v[84:85]
	v_pk_mul_f32 v[86:87], v[86:87], v[86:87]
	v_pk_mul_f32 v[80:81], v[80:81], v[80:81]
	v_pk_mul_f32 v[82:83], v[82:83], v[82:83]
	v_cvt_pk_bf16_f32 v232, v84, v85
	v_cvt_pk_bf16_f32 v233, v86, v87
	v_cvt_pk_bf16_f32 v234, v80, v81
	v_cvt_pk_bf16_f32 v235, v82, v83
	v_mov_b32_e32 v236, v228
	v_mov_b32_e32 v237, v229
	v_mov_b32_e32 v238, v230
	v_mov_b32_e32 v239, v231
	v_mov_b32_dpp v228, v232 row_ror:8 row_mask:0xf bank_mask:0xc
	v_mov_b32_dpp v229, v233 row_ror:8 row_mask:0xf bank_mask:0xc
	v_mov_b32_dpp v230, v234 row_ror:8 row_mask:0xf bank_mask:0xc
	v_mov_b32_dpp v231, v235 row_ror:8 row_mask:0xf bank_mask:0xc
	v_mov_b32_dpp v232, v236 row_ror:8 row_mask:0xf bank_mask:0x3
	v_mov_b32_dpp v233, v237 row_ror:8 row_mask:0xf bank_mask:0x3
	v_mov_b32_dpp v234, v238 row_ror:8 row_mask:0xf bank_mask:0x3
	v_mov_b32_dpp v235, v239 row_ror:8 row_mask:0xf bank_mask:0x3
	s_add_u32 s100, s100, 0x20000
	s_addc_u32 s101, s101, 0
	global_store_dwordx4 v240, v[228:231], s[100:101]
	s_add_u32 s100, s100, 0x20000
	s_addc_u32 s101, s101, 0
	global_store_dwordx4 v240, v[232:235], s[100:101]
	v_max_f32_e32 v76, 0, v76
	v_max_f32_e32 v77, 0, v77
	v_max_f32_e32 v78, 0, v78
	v_max_f32_e32 v79, 0, v79
	v_max_f32_e32 v72, 0, v72
	v_max_f32_e32 v73, 0, v73
	v_max_f32_e32 v74, 0, v74
	v_max_f32_e32 v75, 0, v75
	v_pk_mul_f32 v[76:77], v[76:77], v[76:77]
	v_pk_mul_f32 v[78:79], v[78:79], v[78:79]
	v_pk_mul_f32 v[72:73], v[72:73], v[72:73]
	v_pk_mul_f32 v[74:75], v[74:75], v[74:75]
	v_cvt_pk_bf16_f32 v228, v76, v77
	v_cvt_pk_bf16_f32 v229, v78, v79
	v_cvt_pk_bf16_f32 v230, v72, v73
	v_cvt_pk_bf16_f32 v231, v74, v75
	v_max_f32_e32 v68, 0, v68
	v_max_f32_e32 v69, 0, v69
	v_max_f32_e32 v70, 0, v70
	v_max_f32_e32 v71, 0, v71
	v_max_f32_e32 v64, 0, v64
	v_max_f32_e32 v65, 0, v65
	v_max_f32_e32 v66, 0, v66
	v_max_f32_e32 v67, 0, v67
	v_pk_mul_f32 v[68:69], v[68:69], v[68:69]
	v_pk_mul_f32 v[70:71], v[70:71], v[70:71]
	v_pk_mul_f32 v[64:65], v[64:65], v[64:65]
	v_pk_mul_f32 v[66:67], v[66:67], v[66:67]
	v_cvt_pk_bf16_f32 v232, v68, v69
	v_cvt_pk_bf16_f32 v233, v70, v71
	v_cvt_pk_bf16_f32 v234, v64, v65
	v_cvt_pk_bf16_f32 v235, v66, v67
	v_mov_b32_e32 v236, v228
	v_mov_b32_e32 v237, v229
	v_mov_b32_e32 v238, v230
	v_mov_b32_e32 v239, v231
	v_mov_b32_dpp v228, v232 row_ror:8 row_mask:0xf bank_mask:0xc
	v_mov_b32_dpp v229, v233 row_ror:8 row_mask:0xf bank_mask:0xc
	v_mov_b32_dpp v230, v234 row_ror:8 row_mask:0xf bank_mask:0xc
	v_mov_b32_dpp v231, v235 row_ror:8 row_mask:0xf bank_mask:0xc
	v_mov_b32_dpp v232, v236 row_ror:8 row_mask:0xf bank_mask:0x3
	v_mov_b32_dpp v233, v237 row_ror:8 row_mask:0xf bank_mask:0x3
	v_mov_b32_dpp v234, v238 row_ror:8 row_mask:0xf bank_mask:0x3
	v_mov_b32_dpp v235, v239 row_ror:8 row_mask:0xf bank_mask:0x3
	s_add_u32 s100, s100, 0x20000
	s_addc_u32 s101, s101, 0
	global_store_dwordx4 v240, v[228:231], s[100:101]
	s_add_u32 s100, s100, 0x20000
	s_addc_u32 s101, s101, 0
	global_store_dwordx4 v240, v[232:235], s[100:101]
	v_max_f32_e32 v60, 0, v60
	v_max_f32_e32 v61, 0, v61
	v_max_f32_e32 v62, 0, v62
	v_max_f32_e32 v63, 0, v63
	v_max_f32_e32 v56, 0, v56
	v_max_f32_e32 v57, 0, v57
	v_max_f32_e32 v58, 0, v58
	v_max_f32_e32 v59, 0, v59
	v_pk_mul_f32 v[60:61], v[60:61], v[60:61]
	v_pk_mul_f32 v[62:63], v[62:63], v[62:63]
	v_pk_mul_f32 v[56:57], v[56:57], v[56:57]
	v_pk_mul_f32 v[58:59], v[58:59], v[58:59]
	v_cvt_pk_bf16_f32 v228, v60, v61
	v_cvt_pk_bf16_f32 v229, v62, v63
	v_cvt_pk_bf16_f32 v230, v56, v57
	v_cvt_pk_bf16_f32 v231, v58, v59
	v_max_f32_e32 v52, 0, v52
	v_max_f32_e32 v53, 0, v53
	v_max_f32_e32 v54, 0, v54
	v_max_f32_e32 v55, 0, v55
	v_max_f32_e32 v48, 0, v48
	v_max_f32_e32 v49, 0, v49
	v_max_f32_e32 v50, 0, v50
	v_max_f32_e32 v51, 0, v51
	v_pk_mul_f32 v[52:53], v[52:53], v[52:53]
	v_pk_mul_f32 v[54:55], v[54:55], v[54:55]
	v_pk_mul_f32 v[48:49], v[48:49], v[48:49]
	v_pk_mul_f32 v[50:51], v[50:51], v[50:51]
	v_cvt_pk_bf16_f32 v232, v52, v53
	v_cvt_pk_bf16_f32 v233, v54, v55
	v_cvt_pk_bf16_f32 v234, v48, v49
	v_cvt_pk_bf16_f32 v235, v50, v51
	v_mov_b32_e32 v236, v228
	v_mov_b32_e32 v237, v229
	v_mov_b32_e32 v238, v230
	v_mov_b32_e32 v239, v231
	v_mov_b32_dpp v228, v232 row_ror:8 row_mask:0xf bank_mask:0xc
	v_mov_b32_dpp v229, v233 row_ror:8 row_mask:0xf bank_mask:0xc
	v_mov_b32_dpp v230, v234 row_ror:8 row_mask:0xf bank_mask:0xc
	v_mov_b32_dpp v231, v235 row_ror:8 row_mask:0xf bank_mask:0xc
	v_mov_b32_dpp v232, v236 row_ror:8 row_mask:0xf bank_mask:0x3
	v_mov_b32_dpp v233, v237 row_ror:8 row_mask:0xf bank_mask:0x3
	v_mov_b32_dpp v234, v238 row_ror:8 row_mask:0xf bank_mask:0x3
	v_mov_b32_dpp v235, v239 row_ror:8 row_mask:0xf bank_mask:0x3
	s_add_u32 s100, s100, 0x120000
	s_addc_u32 s101, s101, 0
	global_store_dwordx4 v240, v[228:231], s[100:101]
	s_add_u32 s100, s100, 0x20000
	s_addc_u32 s101, s101, 0
	global_store_dwordx4 v240, v[232:235], s[100:101]
	v_max_f32_e32 v44, 0, v44
	v_max_f32_e32 v45, 0, v45
	v_max_f32_e32 v46, 0, v46
	v_max_f32_e32 v47, 0, v47
	v_max_f32_e32 v40, 0, v40
	v_max_f32_e32 v41, 0, v41
	v_max_f32_e32 v42, 0, v42
	v_max_f32_e32 v43, 0, v43
	v_pk_mul_f32 v[44:45], v[44:45], v[44:45]
	v_pk_mul_f32 v[46:47], v[46:47], v[46:47]
	v_pk_mul_f32 v[40:41], v[40:41], v[40:41]
	v_pk_mul_f32 v[42:43], v[42:43], v[42:43]
	v_cvt_pk_bf16_f32 v228, v44, v45
	v_cvt_pk_bf16_f32 v229, v46, v47
	v_cvt_pk_bf16_f32 v230, v40, v41
	v_cvt_pk_bf16_f32 v231, v42, v43
	v_max_f32_e32 v36, 0, v36
	v_max_f32_e32 v37, 0, v37
	v_max_f32_e32 v38, 0, v38
	v_max_f32_e32 v39, 0, v39
	v_max_f32_e32 v32, 0, v32
	v_max_f32_e32 v33, 0, v33
	v_max_f32_e32 v34, 0, v34
	v_max_f32_e32 v35, 0, v35
	v_pk_mul_f32 v[36:37], v[36:37], v[36:37]
	v_pk_mul_f32 v[38:39], v[38:39], v[38:39]
	v_pk_mul_f32 v[32:33], v[32:33], v[32:33]
	v_pk_mul_f32 v[34:35], v[34:35], v[34:35]
	v_cvt_pk_bf16_f32 v232, v36, v37
	v_cvt_pk_bf16_f32 v233, v38, v39
	v_cvt_pk_bf16_f32 v234, v32, v33
	v_cvt_pk_bf16_f32 v235, v34, v35
	v_mov_b32_e32 v236, v228
	v_mov_b32_e32 v237, v229
	v_mov_b32_e32 v238, v230
	v_mov_b32_e32 v239, v231
	v_mov_b32_dpp v228, v232 row_ror:8 row_mask:0xf bank_mask:0xc
	v_mov_b32_dpp v229, v233 row_ror:8 row_mask:0xf bank_mask:0xc
	v_mov_b32_dpp v230, v234 row_ror:8 row_mask:0xf bank_mask:0xc
	v_mov_b32_dpp v231, v235 row_ror:8 row_mask:0xf bank_mask:0xc
	v_mov_b32_dpp v232, v236 row_ror:8 row_mask:0xf bank_mask:0x3
	v_mov_b32_dpp v233, v237 row_ror:8 row_mask:0xf bank_mask:0x3
	v_mov_b32_dpp v234, v238 row_ror:8 row_mask:0xf bank_mask:0x3
	v_mov_b32_dpp v235, v239 row_ror:8 row_mask:0xf bank_mask:0x3
	s_add_u32 s100, s100, 0x20000
	s_addc_u32 s101, s101, 0
	global_store_dwordx4 v240, v[228:231], s[100:101]
	s_add_u32 s100, s100, 0x20000
	s_addc_u32 s101, s101, 0
	global_store_dwordx4 v240, v[232:235], s[100:101]
	v_max_f32_e32 v28, 0, v28
	v_max_f32_e32 v29, 0, v29
	v_max_f32_e32 v30, 0, v30
	v_max_f32_e32 v31, 0, v31
	v_max_f32_e32 v24, 0, v24
	v_max_f32_e32 v25, 0, v25
	v_max_f32_e32 v26, 0, v26
	v_max_f32_e32 v27, 0, v27
	v_pk_mul_f32 v[28:29], v[28:29], v[28:29]
	v_pk_mul_f32 v[30:31], v[30:31], v[30:31]
	v_pk_mul_f32 v[24:25], v[24:25], v[24:25]
	v_pk_mul_f32 v[26:27], v[26:27], v[26:27]
	v_cvt_pk_bf16_f32 v228, v28, v29
	v_cvt_pk_bf16_f32 v229, v30, v31
	v_cvt_pk_bf16_f32 v230, v24, v25
	v_cvt_pk_bf16_f32 v231, v26, v27
	v_max_f32_e32 v20, 0, v20
	v_max_f32_e32 v21, 0, v21
	v_max_f32_e32 v22, 0, v22
	v_max_f32_e32 v23, 0, v23
	v_max_f32_e32 v16, 0, v16
	v_max_f32_e32 v17, 0, v17
	v_max_f32_e32 v18, 0, v18
	v_max_f32_e32 v19, 0, v19
	v_pk_mul_f32 v[20:21], v[20:21], v[20:21]
	v_pk_mul_f32 v[22:23], v[22:23], v[22:23]
	v_pk_mul_f32 v[16:17], v[16:17], v[16:17]
	v_pk_mul_f32 v[18:19], v[18:19], v[18:19]
	v_cvt_pk_bf16_f32 v232, v20, v21
	v_cvt_pk_bf16_f32 v233, v22, v23
	v_cvt_pk_bf16_f32 v234, v16, v17
	v_cvt_pk_bf16_f32 v235, v18, v19
	v_mov_b32_e32 v236, v228
	v_mov_b32_e32 v237, v229
	v_mov_b32_e32 v238, v230
	v_mov_b32_e32 v239, v231
	v_mov_b32_dpp v228, v232 row_ror:8 row_mask:0xf bank_mask:0xc
	v_mov_b32_dpp v229, v233 row_ror:8 row_mask:0xf bank_mask:0xc
	v_mov_b32_dpp v230, v234 row_ror:8 row_mask:0xf bank_mask:0xc
	v_mov_b32_dpp v231, v235 row_ror:8 row_mask:0xf bank_mask:0xc
	v_mov_b32_dpp v232, v236 row_ror:8 row_mask:0xf bank_mask:0x3
	v_mov_b32_dpp v233, v237 row_ror:8 row_mask:0xf bank_mask:0x3
	v_mov_b32_dpp v234, v238 row_ror:8 row_mask:0xf bank_mask:0x3
	v_mov_b32_dpp v235, v239 row_ror:8 row_mask:0xf bank_mask:0x3
	s_add_u32 s100, s100, 0x20000
	s_addc_u32 s101, s101, 0
	global_store_dwordx4 v240, v[228:231], s[100:101]
	s_add_u32 s100, s100, 0x20000
	s_addc_u32 s101, s101, 0
	global_store_dwordx4 v240, v[232:235], s[100:101]
	v_max_f32_e32 v12, 0, v12
	v_max_f32_e32 v13, 0, v13
	v_max_f32_e32 v14, 0, v14
	v_max_f32_e32 v15, 0, v15
	v_max_f32_e32 v8, 0, v8
	v_max_f32_e32 v9, 0, v9
	v_max_f32_e32 v10, 0, v10
	v_max_f32_e32 v11, 0, v11
	v_pk_mul_f32 v[12:13], v[12:13], v[12:13]
	v_pk_mul_f32 v[14:15], v[14:15], v[14:15]
	v_pk_mul_f32 v[8:9], v[8:9], v[8:9]
	v_pk_mul_f32 v[10:11], v[10:11], v[10:11]
	v_cvt_pk_bf16_f32 v228, v12, v13
	v_cvt_pk_bf16_f32 v229, v14, v15
	v_cvt_pk_bf16_f32 v230, v8, v9
	v_cvt_pk_bf16_f32 v231, v10, v11
	v_max_f32_e32 v4, 0, v4
	v_max_f32_e32 v5, 0, v5
	v_max_f32_e32 v6, 0, v6
	v_max_f32_e32 v7, 0, v7
	v_max_f32_e32 v0, 0, v0
	v_max_f32_e32 v1, 0, v1
	v_max_f32_e32 v2, 0, v2
	v_max_f32_e32 v3, 0, v3
	v_pk_mul_f32 v[4:5], v[4:5], v[4:5]
	v_pk_mul_f32 v[6:7], v[6:7], v[6:7]
	v_pk_mul_f32 v[0:1], v[0:1], v[0:1]
	v_pk_mul_f32 v[2:3], v[2:3], v[2:3]
	v_cvt_pk_bf16_f32 v232, v4, v5
	v_cvt_pk_bf16_f32 v233, v6, v7
	v_cvt_pk_bf16_f32 v234, v0, v1
	v_cvt_pk_bf16_f32 v235, v2, v3
	v_mov_b32_e32 v236, v228
	v_mov_b32_e32 v237, v229
	v_mov_b32_e32 v238, v230
	v_mov_b32_e32 v239, v231
	v_mov_b32_dpp v228, v232 row_ror:8 row_mask:0xf bank_mask:0xc
	v_mov_b32_dpp v229, v233 row_ror:8 row_mask:0xf bank_mask:0xc
	v_mov_b32_dpp v230, v234 row_ror:8 row_mask:0xf bank_mask:0xc
	v_mov_b32_dpp v231, v235 row_ror:8 row_mask:0xf bank_mask:0xc
	v_mov_b32_dpp v232, v236 row_ror:8 row_mask:0xf bank_mask:0x3
	v_mov_b32_dpp v233, v237 row_ror:8 row_mask:0xf bank_mask:0x3
	v_mov_b32_dpp v234, v238 row_ror:8 row_mask:0xf bank_mask:0x3
	v_mov_b32_dpp v235, v239 row_ror:8 row_mask:0xf bank_mask:0x3
	s_add_u32 s100, s100, 0x20000
	s_addc_u32 s101, s101, 0
	global_store_dwordx4 v240, v[228:231], s[100:101]
	s_add_u32 s100, s100, 0x20000
	s_addc_u32 s101, s101, 0
	global_store_dwordx4 v240, v[232:235], s[100:101]
	s_and_b64 vcc, exec, s[2:3]
	s_mov_b32 s40, s8
	s_mov_b32 s20, s14
	s_mov_b64 s[24:25], s[18:19]
	s_mov_b64 s[22:23], s[16:17]
	s_cbranch_vccz .LBB0_528
	s_waitcnt vmcnt(0)
	s_cmpk_gt_u32 s28, 0xff
	s_cbranch_scc1 .LBB0_535
	s_barrier

.LBB0_644:
	ds_read_b128 v[146:149], v143
	ds_read_b128 v[150:153], v143 offset:1024
	ds_read_b128 v[154:157], v143 offset:2048
	ds_read_b128 v[158:161], v143 offset:3072
	s_add_i32 s46, s18, 2
	s_add_u32 s19, s16, 0xffe00080
	s_addc_u32 s20, s17, -1
	s_cmp_eq_u32 s43, s18
	s_cselect_b32 s18, s42, s44
	s_cselect_b32 s21, s3, s20
	s_cselect_b32 s20, s5, s19
	s_cselect_b32 s19, s41, s45
	s_add_i32 m0, s26, 0xc000
	ds_read_b128 v[162:165], v144
	ds_read_b128 v[166:169], v144 offset:1024
	ds_read_b128 v[170:173], v144 offset:2048
	ds_read_b128 v[174:177], v144 offset:3072
	ds_read_b128 v[178:181], v144 offset:4096
	ds_read_b128 v[182:185], v144 offset:5120
	ds_read_b128 v[186:189], v144 offset:6144
	ds_read_b128 v[190:193], v144 offset:7168
	global_load_lds_dwordx4 v136, s[16:17]
	s_add_i32 m0, s26, 0xe000
	s_nop 0
	global_load_lds_dwordx4 v138, s[16:17]
	s_waitcnt lgkmcnt(8)
	s_barrier
	s_waitcnt lgkmcnt(0)
	v_mfma_f32_16x16x32_bf16 v[124:127], v[146:149], v[162:165], v[124:127]
	v_mfma_f32_16x16x32_bf16 v[120:123], v[154:157], v[162:165], v[120:123]
	v_mfma_f32_16x16x32_bf16 v[108:111], v[146:149], v[170:173], v[108:111]
	v_mfma_f32_16x16x32_bf16 v[104:107], v[154:157], v[170:173], v[104:107]
	v_mfma_f32_16x16x32_bf16 v[92:95], v[146:149], v[178:181], v[92:95]
	v_mfma_f32_16x16x32_bf16 v[88:91], v[154:157], v[178:181], v[88:91]
	v_mfma_f32_16x16x32_bf16 v[76:79], v[146:149], v[186:189], v[76:79]
	v_mfma_f32_16x16x32_bf16 v[72:75], v[154:157], v[186:189], v[72:75]
	v_mfma_f32_16x16x32_bf16 v[124:127], v[150:153], v[166:169], v[124:127]
	v_mfma_f32_16x16x32_bf16 v[120:123], v[158:161], v[166:169], v[120:123]
	v_mfma_f32_16x16x32_bf16 v[108:111], v[150:153], v[174:177], v[108:111]
	v_mfma_f32_16x16x32_bf16 v[104:107], v[158:161], v[174:177], v[104:107]
	v_mfma_f32_16x16x32_bf16 v[92:95], v[150:153], v[182:185], v[92:95]
	v_mfma_f32_16x16x32_bf16 v[88:91], v[158:161], v[182:185], v[88:91]
	v_mfma_f32_16x16x32_bf16 v[76:79], v[150:153], v[190:193], v[76:79]
	v_mfma_f32_16x16x32_bf16 v[72:75], v[158:161], v[190:193], v[72:75]
	s_barrier
	s_add_i32 s47, s35, s25
	s_mov_b32 m0, s47
	ds_read_b128 v[194:197], v145
	ds_read_b128 v[198:201], v145 offset:1024
	ds_read_b128 v[204:207], v145 offset:2048
	ds_read_b128 v[208:211], v145 offset:3072
	global_load_lds_dwordx4 v132, s[18:19]
	s_add_i32 m0, s47, 0x2000
	s_nop 0
	global_load_lds_dwordx4 v128, s[18:19]
	s_barrier
	s_waitcnt lgkmcnt(0)
	v_mfma_f32_16x16x32_bf16 v[116:119], v[194:197], v[162:165], v[116:119]
	v_mfma_f32_16x16x32_bf16 v[112:115], v[204:207], v[162:165], v[112:115]
	v_mfma_f32_16x16x32_bf16 v[100:103], v[194:197], v[170:173], v[100:103]
	v_mfma_f32_16x16x32_bf16 v[96:99], v[204:207], v[170:173], v[96:99]
	v_mfma_f32_16x16x32_bf16 v[84:87], v[194:197], v[178:181], v[84:87]
	v_mfma_f32_16x16x32_bf16 v[80:83], v[204:207], v[178:181], v[80:83]
	v_mfma_f32_16x16x32_bf16 v[68:71], v[194:197], v[186:189], v[68:71]
	v_mfma_f32_16x16x32_bf16 v[64:67], v[204:207], v[186:189], v[64:67]
	v_mfma_f32_16x16x32_bf16 v[116:119], v[198:201], v[166:169], v[116:119]
	v_mfma_f32_16x16x32_bf16 v[112:115], v[208:211], v[166:169], v[112:115]
	v_mfma_f32_16x16x32_bf16 v[100:103], v[198:201], v[174:177], v[100:103]
	v_mfma_f32_16x16x32_bf16 v[96:99], v[208:211], v[174:177], v[96:99]
	v_mfma_f32_16x16x32_bf16 v[84:87], v[198:201], v[182:185], v[84:87]
	v_mfma_f32_16x16x32_bf16 v[80:83], v[208:211], v[182:185], v[80:83]
	v_mfma_f32_16x16x32_bf16 v[68:71], v[198:201], v[190:193], v[68:71]
	v_mfma_f32_16x16x32_bf16 v[64:67], v[208:211], v[190:193], v[64:67]
	s_mov_b32 m0, s26
	s_mov_b64 s[98:99], s[20:21]
	s_barrier
	ds_read_b128 v[162:165], v144 offset:16384
	ds_read_b128 v[166:169], v144 offset:17408
	ds_read_b128 v[170:173], v144 offset:18432
	ds_read_b128 v[174:177], v144 offset:19456
	ds_read_b128 v[178:181], v144 offset:20480
	ds_read_b128 v[182:185], v144 offset:21504
	ds_read_b128 v[186:189], v144 offset:22528
	ds_read_b128 v[190:193], v144 offset:23552
	global_load_lds_dwordx4 v134, s[20:21]
	s_mov_b32 m0, s27
	s_nop 0
	global_load_lds_dwordx4 v130, s[20:21]
	s_barrier
	s_waitcnt lgkmcnt(0)
	v_mfma_f32_16x16x32_bf16 v[60:63], v[146:149], v[162:165], v[60:63]
	v_mfma_f32_16x16x32_bf16 v[56:59], v[154:157], v[162:165], v[56:59]
	v_mfma_f32_16x16x32_bf16 v[44:47], v[146:149], v[170:173], v[44:47]
	v_mfma_f32_16x16x32_bf16 v[40:43], v[154:157], v[170:173], v[40:43]
	v_mfma_f32_16x16x32_bf16 v[28:31], v[146:149], v[178:181], v[28:31]
	v_mfma_f32_16x16x32_bf16 v[24:27], v[154:157], v[178:181], v[24:27]
	v_mfma_f32_16x16x32_bf16 v[12:15], v[146:149], v[186:189], v[12:15]
	v_mfma_f32_16x16x32_bf16 v[8:11], v[154:157], v[186:189], v[8:11]
	v_mfma_f32_16x16x32_bf16 v[60:63], v[150:153], v[166:169], v[60:63]
	v_mfma_f32_16x16x32_bf16 v[56:59], v[158:161], v[166:169], v[56:59]
	v_mfma_f32_16x16x32_bf16 v[44:47], v[150:153], v[174:177], v[44:47]
	v_mfma_f32_16x16x32_bf16 v[40:43], v[158:161], v[174:177], v[40:43]
	v_mfma_f32_16x16x32_bf16 v[28:31], v[150:153], v[182:185], v[28:31]
	v_mfma_f32_16x16x32_bf16 v[24:27], v[158:161], v[182:185], v[24:27]
	v_mfma_f32_16x16x32_bf16 v[12:15], v[150:153], v[190:193], v[12:15]
	v_mfma_f32_16x16x32_bf16 v[8:11], v[158:161], v[190:193], v[8:11]
	s_barrier
	s_add_u32 s48, s18, 0x80000
	s_addc_u32 s49, s19, 0
	s_add_i32 s47, s36, s25
	s_mov_b32 m0, s47
	s_nop 0
	global_load_lds_dwordx4 v132, s[48:49]
	s_add_i32 m0, s47, 0x2000
	s_nop 0
	global_load_lds_dwordx4 v128, s[48:49]
	s_waitcnt vmcnt(6)
	s_barrier
	v_mfma_f32_16x16x32_bf16 v[52:55], v[194:197], v[162:165], v[52:55]
	v_mfma_f32_16x16x32_bf16 v[48:51], v[204:207], v[162:165], v[48:51]
	v_mfma_f32_16x16x32_bf16 v[36:39], v[194:197], v[170:173], v[36:39]
	v_mfma_f32_16x16x32_bf16 v[32:35], v[204:207], v[170:173], v[32:35]
	v_mfma_f32_16x16x32_bf16 v[20:23], v[194:197], v[178:181], v[20:23]
	v_mfma_f32_16x16x32_bf16 v[16:19], v[204:207], v[178:181], v[16:19]
	v_mfma_f32_16x16x32_bf16 v[4:7], v[194:197], v[186:189], v[4:7]
	v_mfma_f32_16x16x32_bf16 v[0:3], v[204:207], v[186:189], v[0:3]
	v_mfma_f32_16x16x32_bf16 v[52:55], v[198:201], v[166:169], v[52:55]
	v_mfma_f32_16x16x32_bf16 v[48:51], v[208:211], v[166:169], v[48:51]
	v_mfma_f32_16x16x32_bf16 v[36:39], v[198:201], v[174:177], v[36:39]
	v_mfma_f32_16x16x32_bf16 v[32:35], v[208:211], v[174:177], v[32:35]
	v_mfma_f32_16x16x32_bf16 v[20:23], v[198:201], v[182:185], v[20:23]
	v_mfma_f32_16x16x32_bf16 v[16:19], v[208:211], v[182:185], v[16:19]
	v_mfma_f32_16x16x32_bf16 v[4:7], v[198:201], v[190:193], v[4:7]
	v_mfma_f32_16x16x32_bf16 v[0:3], v[208:211], v[190:193], v[0:3]
	s_add_i32 s47, 0, 0x18000
	v_add_u32_e32 v158, s47, v141
	s_barrier
	ds_read_b128 v[146:149], v158
	ds_read_b128 v[150:153], v158 offset:1024
	ds_read_b128 v[154:157], v158 offset:2048
	ds_read_b128 v[158:161], v158 offset:3072
	s_add_u32 s20, s20, 0x200000
	s_addc_u32 s21, s21, 0
	s_mov_b32 m0, s28
	ds_read_b128 v[162:165], v144 offset:32768
	ds_read_b128 v[166:169], v144 offset:33792
	ds_read_b128 v[170:173], v144 offset:34816
	ds_read_b128 v[174:177], v144 offset:35840
	ds_read_b128 v[178:181], v144 offset:36864
	ds_read_b128 v[182:185], v144 offset:37888
	ds_read_b128 v[186:189], v144 offset:38912
	ds_read_b128 v[190:193], v144 offset:39936
	global_load_lds_dwordx4 v134, s[20:21]
	s_mov_b32 m0, s29
	s_nop 0
	global_load_lds_dwordx4 v130, s[20:21]
	s_waitcnt lgkmcnt(8)
	s_barrier
	s_waitcnt lgkmcnt(0)
	v_mfma_f32_16x16x32_bf16 v[124:127], v[146:149], v[162:165], v[124:127]
	v_mfma_f32_16x16x32_bf16 v[120:123], v[154:157], v[162:165], v[120:123]
	v_mfma_f32_16x16x32_bf16 v[108:111], v[146:149], v[170:173], v[108:111]
	v_mfma_f32_16x16x32_bf16 v[104:107], v[154:157], v[170:173], v[104:107]
	v_mfma_f32_16x16x32_bf16 v[92:95], v[146:149], v[178:181], v[92:95]
	v_mfma_f32_16x16x32_bf16 v[88:91], v[154:157], v[178:181], v[88:91]
	v_mfma_f32_16x16x32_bf16 v[76:79], v[146:149], v[186:189], v[76:79]
	v_mfma_f32_16x16x32_bf16 v[72:75], v[154:157], v[186:189], v[72:75]
	v_mfma_f32_16x16x32_bf16 v[124:127], v[150:153], v[166:169], v[124:127]
	v_mfma_f32_16x16x32_bf16 v[120:123], v[158:161], v[166:169], v[120:123]
	v_mfma_f32_16x16x32_bf16 v[108:111], v[150:153], v[174:177], v[108:111]
	v_mfma_f32_16x16x32_bf16 v[104:107], v[158:161], v[174:177], v[104:107]
	v_mfma_f32_16x16x32_bf16 v[92:95], v[150:153], v[182:185], v[92:95]
	v_mfma_f32_16x16x32_bf16 v[88:91], v[158:161], v[182:185], v[88:91]
	v_mfma_f32_16x16x32_bf16 v[76:79], v[150:153], v[190:193], v[76:79]
	v_mfma_f32_16x16x32_bf16 v[72:75], v[158:161], v[190:193], v[72:75]
	s_barrier
	s_add_i32 s20, 0, 0x1c000
	s_add_i32 s21, s47, s25
	v_add_u32_e32 v208, s20, v141
	s_mov_b32 m0, s21
	ds_read_b128 v[194:197], v208
	ds_read_b128 v[198:201], v208 offset:1024
	ds_read_b128 v[204:207], v208 offset:2048
	ds_read_b128 v[208:211], v208 offset:3072
	s_add_u32 s100, s18, 0x80
	s_addc_u32 s101, s19, 0
	global_load_lds_dwordx4 v132, s[100:101]
	s_add_i32 m0, s21, 0x2000
	s_nop 0
	s_add_u32 s100, s18, 0x80
	s_addc_u32 s101, s19, 0
	global_load_lds_dwordx4 v128, s[100:101]
	s_barrier
	s_waitcnt lgkmcnt(0)
	v_mfma_f32_16x16x32_bf16 v[116:119], v[194:197], v[162:165], v[116:119]
	v_mfma_f32_16x16x32_bf16 v[112:115], v[204:207], v[162:165], v[112:115]
	v_mfma_f32_16x16x32_bf16 v[100:103], v[194:197], v[170:173], v[100:103]
	v_mfma_f32_16x16x32_bf16 v[96:99], v[204:207], v[170:173], v[96:99]
	v_mfma_f32_16x16x32_bf16 v[84:87], v[194:197], v[178:181], v[84:87]
	v_mfma_f32_16x16x32_bf16 v[80:83], v[204:207], v[178:181], v[80:83]
	v_mfma_f32_16x16x32_bf16 v[68:71], v[194:197], v[186:189], v[68:71]
	v_mfma_f32_16x16x32_bf16 v[64:67], v[204:207], v[186:189], v[64:67]
	v_mfma_f32_16x16x32_bf16 v[116:119], v[198:201], v[166:169], v[116:119]
	v_mfma_f32_16x16x32_bf16 v[112:115], v[208:211], v[166:169], v[112:115]
	v_mfma_f32_16x16x32_bf16 v[100:103], v[198:201], v[174:177], v[100:103]
	v_mfma_f32_16x16x32_bf16 v[96:99], v[208:211], v[174:177], v[96:99]
	v_mfma_f32_16x16x32_bf16 v[84:87], v[198:201], v[182:185], v[84:87]
	v_mfma_f32_16x16x32_bf16 v[80:83], v[208:211], v[182:185], v[80:83]
	v_mfma_f32_16x16x32_bf16 v[68:71], v[198:201], v[190:193], v[68:71]
	v_mfma_f32_16x16x32_bf16 v[64:67], v[208:211], v[190:193], v[64:67]
	s_mov_b32 m0, s30
	s_barrier
	ds_read_b128 v[162:165], v144 offset:49152
	ds_read_b128 v[166:169], v144 offset:50176
	ds_read_b128 v[170:173], v144 offset:51200
	ds_read_b128 v[174:177], v144 offset:52224
	ds_read_b128 v[178:181], v144 offset:53248
	ds_read_b128 v[182:185], v144 offset:54272
	ds_read_b128 v[186:189], v144 offset:55296
	ds_read_b128 v[190:193], v144 offset:56320
	s_add_u32 s100, s98, 0x80
	s_addc_u32 s101, s99, 0
	global_load_lds_dwordx4 v134, s[100:101]
	s_mov_b32 m0, s31
	s_nop 0
	s_add_u32 s100, s98, 0x80
	s_addc_u32 s101, s99, 0
	global_load_lds_dwordx4 v130, s[100:101]
	s_barrier
	s_waitcnt lgkmcnt(0)
	v_mfma_f32_16x16x32_bf16 v[60:63], v[146:149], v[162:165], v[60:63]
	v_mfma_f32_16x16x32_bf16 v[56:59], v[154:157], v[162:165], v[56:59]
	v_mfma_f32_16x16x32_bf16 v[44:47], v[146:149], v[170:173], v[44:47]
	v_mfma_f32_16x16x32_bf16 v[40:43], v[154:157], v[170:173], v[40:43]
	v_mfma_f32_16x16x32_bf16 v[28:31], v[146:149], v[178:181], v[28:31]
	v_mfma_f32_16x16x32_bf16 v[24:27], v[154:157], v[178:181], v[24:27]
	v_mfma_f32_16x16x32_bf16 v[12:15], v[146:149], v[186:189], v[12:15]
	v_mfma_f32_16x16x32_bf16 v[8:11], v[154:157], v[186:189], v[8:11]
	v_mfma_f32_16x16x32_bf16 v[60:63], v[150:153], v[166:169], v[60:63]
	v_mfma_f32_16x16x32_bf16 v[56:59], v[158:161], v[166:169], v[56:59]
	v_mfma_f32_16x16x32_bf16 v[44:47], v[150:153], v[174:177], v[44:47]
	v_mfma_f32_16x16x32_bf16 v[40:43], v[158:161], v[174:177], v[40:43]
	v_mfma_f32_16x16x32_bf16 v[28:31], v[150:153], v[182:185], v[28:31]
	v_mfma_f32_16x16x32_bf16 v[24:27], v[158:161], v[182:185], v[24:27]
	v_mfma_f32_16x16x32_bf16 v[12:15], v[150:153], v[190:193], v[12:15]
	v_mfma_f32_16x16x32_bf16 v[8:11], v[158:161], v[190:193], v[8:11]
	s_barrier
	s_add_u32 s18, s18, 0x80080
	s_addc_u32 s19, s19, 0
	s_add_i32 s20, s20, s25
	s_mov_b32 m0, s20
	s_nop 0
	global_load_lds_dwordx4 v132, s[18:19]
	s_add_i32 m0, s20, 0x2000
	s_nop 0
	global_load_lds_dwordx4 v128, s[18:19]
	s_waitcnt vmcnt(6)
	s_barrier
	v_mfma_f32_16x16x32_bf16 v[52:55], v[194:197], v[162:165], v[52:55]
	v_mfma_f32_16x16x32_bf16 v[48:51], v[204:207], v[162:165], v[48:51]
	v_mfma_f32_16x16x32_bf16 v[36:39], v[194:197], v[170:173], v[36:39]
	v_mfma_f32_16x16x32_bf16 v[32:35], v[204:207], v[170:173], v[32:35]
	v_mfma_f32_16x16x32_bf16 v[20:23], v[194:197], v[178:181], v[20:23]
	v_mfma_f32_16x16x32_bf16 v[16:19], v[204:207], v[178:181], v[16:19]
	v_mfma_f32_16x16x32_bf16 v[4:7], v[194:197], v[186:189], v[4:7]
	v_mfma_f32_16x16x32_bf16 v[0:3], v[204:207], v[186:189], v[0:3]
	v_mfma_f32_16x16x32_bf16 v[52:55], v[198:201], v[166:169], v[52:55]
	v_mfma_f32_16x16x32_bf16 v[48:51], v[208:211], v[166:169], v[48:51]
	v_mfma_f32_16x16x32_bf16 v[36:39], v[198:201], v[174:177], v[36:39]
	v_mfma_f32_16x16x32_bf16 v[32:35], v[208:211], v[174:177], v[32:35]
	v_mfma_f32_16x16x32_bf16 v[20:23], v[198:201], v[182:185], v[20:23]
	v_mfma_f32_16x16x32_bf16 v[16:19], v[208:211], v[182:185], v[16:19]
	v_mfma_f32_16x16x32_bf16 v[4:7], v[198:201], v[190:193], v[4:7]
	v_mfma_f32_16x16x32_bf16 v[0:3], v[208:211], v[190:193], v[0:3]
	s_add_u32 s16, s16, 0x100
	s_addc_u32 s17, s17, 0
	s_add_u32 s44, s44, 0x100
	s_addc_u32 s45, s45, 0
	s_cmp_ge_i32 s46, s40
	s_mov_b32 s18, s46
	s_barrier
	s_cbranch_scc0 .LBB0_644
	s_branch .LBB0_639

.LBB0_804:
	ds_read_b128 v[154:157], v151
	ds_read_b128 v[158:161], v151 offset:1024
	ds_read_b128 v[162:165], v151 offset:2048
	ds_read_b128 v[166:169], v151 offset:3072
	s_add_u32 s22, s20, 0xfff80080
	s_addc_u32 s23, s21, -1
	s_cmp_eq_u32 s45, 28
	s_cselect_b32 s25, s9, s23
	s_cselect_b32 s24, s17, s22
	s_cselect_b32 s23, s7, s44
	s_cselect_b32 s22, s42, s43
	s_add_i32 m0, s30, 0xc000
	ds_read_b128 v[170:173], v152
	ds_read_b128 v[174:177], v152 offset:1024
	ds_read_b128 v[178:181], v152 offset:2048
	ds_read_b128 v[182:185], v152 offset:3072
	ds_read_b128 v[186:189], v152 offset:4096
	ds_read_b128 v[190:193], v152 offset:5120
	ds_read_b128 v[194:197], v152 offset:6144
	ds_read_b128 v[198:201], v152 offset:7168
	global_load_lds_dwordx4 v138, s[20:21]
	s_add_i32 m0, s30, 0xe000
	s_nop 0
	global_load_lds_dwordx4 v140, s[20:21]
	s_waitcnt lgkmcnt(8)
	s_barrier
	s_waitcnt lgkmcnt(0)
	v_mfma_f32_16x16x32_bf16 v[124:127], v[154:157], v[170:173], v[124:127]
	v_mfma_f32_16x16x32_bf16 v[120:123], v[162:165], v[170:173], v[120:123]
	v_mfma_f32_16x16x32_bf16 v[116:119], v[154:157], v[178:181], v[116:119]
	v_mfma_f32_16x16x32_bf16 v[112:115], v[162:165], v[178:181], v[112:115]
	v_mfma_f32_16x16x32_bf16 v[100:103], v[154:157], v[186:189], v[100:103]
	v_mfma_f32_16x16x32_bf16 v[96:99], v[162:165], v[186:189], v[96:99]
	v_mfma_f32_16x16x32_bf16 v[84:87], v[154:157], v[194:197], v[84:87]
	v_mfma_f32_16x16x32_bf16 v[80:83], v[162:165], v[194:197], v[80:83]
	v_mfma_f32_16x16x32_bf16 v[124:127], v[158:161], v[174:177], v[124:127]
	v_mfma_f32_16x16x32_bf16 v[120:123], v[166:169], v[174:177], v[120:123]
	v_mfma_f32_16x16x32_bf16 v[116:119], v[158:161], v[182:185], v[116:119]
	v_mfma_f32_16x16x32_bf16 v[112:115], v[166:169], v[182:185], v[112:115]
	v_mfma_f32_16x16x32_bf16 v[100:103], v[158:161], v[190:193], v[100:103]
	v_mfma_f32_16x16x32_bf16 v[96:99], v[166:169], v[190:193], v[96:99]
	v_mfma_f32_16x16x32_bf16 v[84:87], v[158:161], v[198:201], v[84:87]
	v_mfma_f32_16x16x32_bf16 v[80:83], v[166:169], v[198:201], v[80:83]
	s_barrier
	s_add_i32 s46, s39, s29
	s_mov_b32 m0, s46
	ds_read_b128 v[204:207], v153
	ds_read_b128 v[208:211], v153 offset:1024
	ds_read_b128 v[212:215], v153 offset:2048
	ds_read_b128 v[216:219], v153 offset:3072
	global_load_lds_dwordx4 v132, s[22:23]
	s_add_i32 m0, s46, 0x2000
	s_nop 0
	global_load_lds_dwordx4 v128, s[22:23]
	s_barrier
	s_waitcnt lgkmcnt(0)
	v_mfma_f32_16x16x32_bf16 v[108:111], v[204:207], v[170:173], v[108:111]
	v_mfma_f32_16x16x32_bf16 v[104:107], v[212:215], v[170:173], v[104:107]
	v_mfma_f32_16x16x32_bf16 v[92:95], v[204:207], v[178:181], v[92:95]
	v_mfma_f32_16x16x32_bf16 v[88:91], v[212:215], v[178:181], v[88:91]
	v_mfma_f32_16x16x32_bf16 v[76:79], v[204:207], v[186:189], v[76:79]
	v_mfma_f32_16x16x32_bf16 v[72:75], v[212:215], v[186:189], v[72:75]
	v_mfma_f32_16x16x32_bf16 v[68:71], v[204:207], v[194:197], v[68:71]
	v_mfma_f32_16x16x32_bf16 v[64:67], v[212:215], v[194:197], v[64:67]
	v_mfma_f32_16x16x32_bf16 v[108:111], v[208:211], v[174:177], v[108:111]
	v_mfma_f32_16x16x32_bf16 v[104:107], v[216:219], v[174:177], v[104:107]
	v_mfma_f32_16x16x32_bf16 v[92:95], v[208:211], v[182:185], v[92:95]
	v_mfma_f32_16x16x32_bf16 v[88:91], v[216:219], v[182:185], v[88:91]
	v_mfma_f32_16x16x32_bf16 v[76:79], v[208:211], v[190:193], v[76:79]
	v_mfma_f32_16x16x32_bf16 v[72:75], v[216:219], v[190:193], v[72:75]
	v_mfma_f32_16x16x32_bf16 v[68:71], v[208:211], v[198:201], v[68:71]
	v_mfma_f32_16x16x32_bf16 v[64:67], v[216:219], v[198:201], v[64:67]
	s_mov_b32 m0, s30
	s_mov_b64 s[98:99], s[24:25]
	s_barrier
	ds_read_b128 v[170:173], v152 offset:16384
	ds_read_b128 v[174:177], v152 offset:17408
	ds_read_b128 v[178:181], v152 offset:18432
	ds_read_b128 v[182:185], v152 offset:19456
	ds_read_b128 v[186:189], v152 offset:20480
	ds_read_b128 v[190:193], v152 offset:21504
	ds_read_b128 v[194:197], v152 offset:22528
	ds_read_b128 v[198:201], v152 offset:23552
	global_load_lds_dwordx4 v134, s[24:25]
	s_mov_b32 m0, s31
	s_nop 0
	global_load_lds_dwordx4 v130, s[24:25]
	s_barrier
	s_waitcnt lgkmcnt(0)
	v_mfma_f32_16x16x32_bf16 v[60:63], v[154:157], v[170:173], v[60:63]
	v_mfma_f32_16x16x32_bf16 v[56:59], v[162:165], v[170:173], v[56:59]
	v_mfma_f32_16x16x32_bf16 v[52:55], v[154:157], v[178:181], v[52:55]
	v_mfma_f32_16x16x32_bf16 v[48:51], v[162:165], v[178:181], v[48:51]
	v_mfma_f32_16x16x32_bf16 v[36:39], v[154:157], v[186:189], v[36:39]
	v_mfma_f32_16x16x32_bf16 v[32:35], v[162:165], v[186:189], v[32:35]
	v_mfma_f32_16x16x32_bf16 v[20:23], v[154:157], v[194:197], v[20:23]
	v_mfma_f32_16x16x32_bf16 v[16:19], v[162:165], v[194:197], v[16:19]
	v_mfma_f32_16x16x32_bf16 v[60:63], v[158:161], v[174:177], v[60:63]
	v_mfma_f32_16x16x32_bf16 v[56:59], v[166:169], v[174:177], v[56:59]
	v_mfma_f32_16x16x32_bf16 v[52:55], v[158:161], v[182:185], v[52:55]
	v_mfma_f32_16x16x32_bf16 v[48:51], v[166:169], v[182:185], v[48:51]
	v_mfma_f32_16x16x32_bf16 v[36:39], v[158:161], v[190:193], v[36:39]
	v_mfma_f32_16x16x32_bf16 v[32:35], v[166:169], v[190:193], v[32:35]
	v_mfma_f32_16x16x32_bf16 v[20:23], v[158:161], v[198:201], v[20:23]
	v_mfma_f32_16x16x32_bf16 v[16:19], v[166:169], v[198:201], v[16:19]
	s_barrier
	s_add_u32 s46, s22, 0x20000
	s_addc_u32 s47, s23, 0
	s_add_i32 s48, s40, s29
	s_mov_b32 m0, s48
	s_nop 0
	global_load_lds_dwordx4 v132, s[46:47]
	s_add_i32 m0, s48, 0x2000
	s_nop 0
	global_load_lds_dwordx4 v128, s[46:47]
	s_waitcnt vmcnt(6)
	s_barrier
	v_mfma_f32_16x16x32_bf16 v[44:47], v[204:207], v[170:173], v[44:47]
	v_mfma_f32_16x16x32_bf16 v[40:43], v[212:215], v[170:173], v[40:43]
	v_mfma_f32_16x16x32_bf16 v[28:31], v[204:207], v[178:181], v[28:31]
	v_mfma_f32_16x16x32_bf16 v[24:27], v[212:215], v[178:181], v[24:27]
	v_mfma_f32_16x16x32_bf16 v[12:15], v[204:207], v[186:189], v[12:15]
	v_mfma_f32_16x16x32_bf16 v[8:11], v[212:215], v[186:189], v[8:11]
	v_mfma_f32_16x16x32_bf16 v[4:7], v[204:207], v[194:197], v[4:7]
	v_mfma_f32_16x16x32_bf16 v[0:3], v[212:215], v[194:197], v[0:3]
	v_mfma_f32_16x16x32_bf16 v[44:47], v[208:211], v[174:177], v[44:47]
	v_mfma_f32_16x16x32_bf16 v[40:43], v[216:219], v[174:177], v[40:43]
	v_mfma_f32_16x16x32_bf16 v[28:31], v[208:211], v[182:185], v[28:31]
	v_mfma_f32_16x16x32_bf16 v[24:27], v[216:219], v[182:185], v[24:27]
	v_mfma_f32_16x16x32_bf16 v[12:15], v[208:211], v[190:193], v[12:15]
	v_mfma_f32_16x16x32_bf16 v[8:11], v[216:219], v[190:193], v[8:11]
	v_mfma_f32_16x16x32_bf16 v[4:7], v[208:211], v[198:201], v[4:7]
	v_mfma_f32_16x16x32_bf16 v[0:3], v[216:219], v[198:201], v[0:3]
	s_add_i32 s46, 0, 0x18000
	v_add_u32_e32 v166, s46, v149
	s_barrier
	ds_read_b128 v[154:157], v166
	ds_read_b128 v[158:161], v166 offset:1024
	ds_read_b128 v[162:165], v166 offset:2048
	ds_read_b128 v[166:169], v166 offset:3072
	s_add_u32 s24, s24, 0x80000
	s_addc_u32 s25, s25, 0
	s_mov_b32 m0, s34
	ds_read_b128 v[170:173], v152 offset:32768
	ds_read_b128 v[174:177], v152 offset:33792
	ds_read_b128 v[178:181], v152 offset:34816
	ds_read_b128 v[182:185], v152 offset:35840
	ds_read_b128 v[186:189], v152 offset:36864
	ds_read_b128 v[190:193], v152 offset:37888
	ds_read_b128 v[194:197], v152 offset:38912
	ds_read_b128 v[198:201], v152 offset:39936
	global_load_lds_dwordx4 v134, s[24:25]
	s_mov_b32 m0, s35
	s_nop 0
	global_load_lds_dwordx4 v130, s[24:25]
	s_waitcnt lgkmcnt(8)
	s_barrier
	s_waitcnt lgkmcnt(0)
	v_mfma_f32_16x16x32_bf16 v[124:127], v[154:157], v[170:173], v[124:127]
	v_mfma_f32_16x16x32_bf16 v[120:123], v[162:165], v[170:173], v[120:123]
	v_mfma_f32_16x16x32_bf16 v[116:119], v[154:157], v[178:181], v[116:119]
	v_mfma_f32_16x16x32_bf16 v[112:115], v[162:165], v[178:181], v[112:115]
	v_mfma_f32_16x16x32_bf16 v[100:103], v[154:157], v[186:189], v[100:103]
	v_mfma_f32_16x16x32_bf16 v[96:99], v[162:165], v[186:189], v[96:99]
	v_mfma_f32_16x16x32_bf16 v[84:87], v[154:157], v[194:197], v[84:87]
	v_mfma_f32_16x16x32_bf16 v[80:83], v[162:165], v[194:197], v[80:83]
	v_mfma_f32_16x16x32_bf16 v[124:127], v[158:161], v[174:177], v[124:127]
	v_mfma_f32_16x16x32_bf16 v[120:123], v[166:169], v[174:177], v[120:123]
	v_mfma_f32_16x16x32_bf16 v[116:119], v[158:161], v[182:185], v[116:119]
	v_mfma_f32_16x16x32_bf16 v[112:115], v[166:169], v[182:185], v[112:115]
	v_mfma_f32_16x16x32_bf16 v[100:103], v[158:161], v[190:193], v[100:103]
	v_mfma_f32_16x16x32_bf16 v[96:99], v[166:169], v[190:193], v[96:99]
	v_mfma_f32_16x16x32_bf16 v[84:87], v[158:161], v[198:201], v[84:87]
	v_mfma_f32_16x16x32_bf16 v[80:83], v[166:169], v[198:201], v[80:83]
	s_barrier
	s_add_i32 s24, 0, 0x1c000
	s_add_i32 s25, s46, s29
	v_add_u32_e32 v216, s24, v149
	s_mov_b32 m0, s25
	ds_read_b128 v[204:207], v216
	ds_read_b128 v[208:211], v216 offset:1024
	ds_read_b128 v[212:215], v216 offset:2048
	ds_read_b128 v[216:219], v216 offset:3072
	s_add_u32 s100, s22, 0x80
	s_addc_u32 s101, s23, 0
	global_load_lds_dwordx4 v132, s[100:101]
	s_add_i32 m0, s25, 0x2000
	s_nop 0
	s_add_u32 s100, s22, 0x80
	s_addc_u32 s101, s23, 0
	global_load_lds_dwordx4 v128, s[100:101]
	s_barrier
	s_waitcnt lgkmcnt(0)
	v_mfma_f32_16x16x32_bf16 v[108:111], v[204:207], v[170:173], v[108:111]
	v_mfma_f32_16x16x32_bf16 v[104:107], v[212:215], v[170:173], v[104:107]
	v_mfma_f32_16x16x32_bf16 v[92:95], v[204:207], v[178:181], v[92:95]
	v_mfma_f32_16x16x32_bf16 v[88:91], v[212:215], v[178:181], v[88:91]
	v_mfma_f32_16x16x32_bf16 v[76:79], v[204:207], v[186:189], v[76:79]
	v_mfma_f32_16x16x32_bf16 v[72:75], v[212:215], v[186:189], v[72:75]
	v_mfma_f32_16x16x32_bf16 v[68:71], v[204:207], v[194:197], v[68:71]
	v_mfma_f32_16x16x32_bf16 v[64:67], v[212:215], v[194:197], v[64:67]
	v_mfma_f32_16x16x32_bf16 v[108:111], v[208:211], v[174:177], v[108:111]
	v_mfma_f32_16x16x32_bf16 v[104:107], v[216:219], v[174:177], v[104:107]
	v_mfma_f32_16x16x32_bf16 v[92:95], v[208:211], v[182:185], v[92:95]
	v_mfma_f32_16x16x32_bf16 v[88:91], v[216:219], v[182:185], v[88:91]
	v_mfma_f32_16x16x32_bf16 v[76:79], v[208:211], v[190:193], v[76:79]
	v_mfma_f32_16x16x32_bf16 v[72:75], v[216:219], v[190:193], v[72:75]
	v_mfma_f32_16x16x32_bf16 v[68:71], v[208:211], v[198:201], v[68:71]
	v_mfma_f32_16x16x32_bf16 v[64:67], v[216:219], v[198:201], v[64:67]
	s_mov_b32 m0, s37
	s_barrier
	ds_read_b128 v[170:173], v152 offset:49152
	ds_read_b128 v[174:177], v152 offset:50176
	ds_read_b128 v[178:181], v152 offset:51200
	ds_read_b128 v[182:185], v152 offset:52224
	ds_read_b128 v[186:189], v152 offset:53248
	ds_read_b128 v[190:193], v152 offset:54272
	ds_read_b128 v[194:197], v152 offset:55296
	ds_read_b128 v[198:201], v152 offset:56320
	s_add_u32 s100, s98, 0x80
	s_addc_u32 s101, s99, 0
	global_load_lds_dwordx4 v134, s[100:101]
	s_mov_b32 m0, s38
	s_nop 0
	s_add_u32 s100, s98, 0x80
	s_addc_u32 s101, s99, 0
	global_load_lds_dwordx4 v130, s[100:101]
	s_barrier
	s_waitcnt lgkmcnt(0)
	v_mfma_f32_16x16x32_bf16 v[60:63], v[154:157], v[170:173], v[60:63]
	v_mfma_f32_16x16x32_bf16 v[56:59], v[162:165], v[170:173], v[56:59]
	v_mfma_f32_16x16x32_bf16 v[52:55], v[154:157], v[178:181], v[52:55]
	v_mfma_f32_16x16x32_bf16 v[48:51], v[162:165], v[178:181], v[48:51]
	v_mfma_f32_16x16x32_bf16 v[36:39], v[154:157], v[186:189], v[36:39]
	v_mfma_f32_16x16x32_bf16 v[32:35], v[162:165], v[186:189], v[32:35]
	v_mfma_f32_16x16x32_bf16 v[20:23], v[154:157], v[194:197], v[20:23]
	v_mfma_f32_16x16x32_bf16 v[16:19], v[162:165], v[194:197], v[16:19]
	v_mfma_f32_16x16x32_bf16 v[60:63], v[158:161], v[174:177], v[60:63]
	v_mfma_f32_16x16x32_bf16 v[56:59], v[166:169], v[174:177], v[56:59]
	v_mfma_f32_16x16x32_bf16 v[52:55], v[158:161], v[182:185], v[52:55]
	v_mfma_f32_16x16x32_bf16 v[48:51], v[166:169], v[182:185], v[48:51]
	v_mfma_f32_16x16x32_bf16 v[36:39], v[158:161], v[190:193], v[36:39]
	v_mfma_f32_16x16x32_bf16 v[32:35], v[166:169], v[190:193], v[32:35]
	v_mfma_f32_16x16x32_bf16 v[20:23], v[158:161], v[198:201], v[20:23]
	v_mfma_f32_16x16x32_bf16 v[16:19], v[166:169], v[198:201], v[16:19]
	s_barrier
	s_add_u32 s22, s22, 0x20080
	s_addc_u32 s23, s23, 0
	s_add_i32 s24, s24, s29
	s_mov_b32 m0, s24
	s_nop 0
	global_load_lds_dwordx4 v132, s[22:23]
	s_add_i32 m0, s24, 0x2000
	s_nop 0
	global_load_lds_dwordx4 v128, s[22:23]
	s_waitcnt vmcnt(6)
	s_barrier
	v_mfma_f32_16x16x32_bf16 v[44:47], v[204:207], v[170:173], v[44:47]
	v_mfma_f32_16x16x32_bf16 v[40:43], v[212:215], v[170:173], v[40:43]
	v_mfma_f32_16x16x32_bf16 v[28:31], v[204:207], v[178:181], v[28:31]
	v_mfma_f32_16x16x32_bf16 v[24:27], v[212:215], v[178:181], v[24:27]
	v_mfma_f32_16x16x32_bf16 v[12:15], v[204:207], v[186:189], v[12:15]
	v_mfma_f32_16x16x32_bf16 v[8:11], v[212:215], v[186:189], v[8:11]
	v_mfma_f32_16x16x32_bf16 v[4:7], v[204:207], v[194:197], v[4:7]
	v_mfma_f32_16x16x32_bf16 v[0:3], v[212:215], v[194:197], v[0:3]
	v_mfma_f32_16x16x32_bf16 v[44:47], v[208:211], v[174:177], v[44:47]
	v_mfma_f32_16x16x32_bf16 v[40:43], v[216:219], v[174:177], v[40:43]
	v_mfma_f32_16x16x32_bf16 v[28:31], v[208:211], v[182:185], v[28:31]
	v_mfma_f32_16x16x32_bf16 v[24:27], v[216:219], v[182:185], v[24:27]
	v_mfma_f32_16x16x32_bf16 v[12:15], v[208:211], v[190:193], v[12:15]
	v_mfma_f32_16x16x32_bf16 v[8:11], v[216:219], v[190:193], v[8:11]
	v_mfma_f32_16x16x32_bf16 v[4:7], v[208:211], v[198:201], v[4:7]
	v_mfma_f32_16x16x32_bf16 v[0:3], v[216:219], v[198:201], v[0:3]
	s_add_i32 s45, s45, 2
	s_add_u32 s20, s20, 0x100
	s_addc_u32 s21, s21, 0
	s_add_u32 s43, s43, 0x100
	s_addc_u32 s44, s44, 0
	s_cmp_gt_u32 s45, 29
	s_barrier
	s_cbranch_scc0 .LBB0_804
	v_and_b32_e32 v242, 15, v202
	v_bfe_u32 v243, v202, 4, 2
	v_bfe_u32 v244, v202, 6, 2
	v_lshrrev_b32_e32 v245, 8, v202
	s_cmp_gt_i32 s41, 47
	s_cbranch_scc1 .Lfl8_ba
	s_cmp_gt_i32 s41, 31
	s_cbranch_scc1 .Lfl8_z
	v_readlane_b32 s100, v248, 63
	v_readlane_b32 s101, v247, 0
	v_and_b32_e32 v240, 7, v242
	v_lshl_add_u32 v240, v245, 6, v240
	v_lshl_add_u32 v240, s16, 8, v240
	v_lshlrev_b32_e32 v240, 14, v240
	v_lshrrev_b32_e32 v241, 3, v242
	v_lshlrev_b32_e32 v241, 6, v241
	v_lshl_add_u32 v241, v244, 7, v241
	v_lshl_add_u32 v241, v243, 4, v241
	v_add_u32_e32 v240, v240, v241
	s_lshl_b32 s98, s41, 9
	v_add_u32_e32 v240, s98, v240
	v_cvt_pk_bf16_f32 v228, v124, v125
	v_cvt_pk_bf16_f32 v229, v126, v127
	v_cvt_pk_bf16_f32 v230, v120, v121
	v_cvt_pk_bf16_f32 v231, v122, v123
	v_cvt_pk_bf16_f32 v232, v108, v109
	v_cvt_pk_bf16_f32 v233, v110, v111
	v_cvt_pk_bf16_f32 v234, v104, v105
	v_cvt_pk_bf16_f32 v235, v106, v107
	v_mov_b32_e32 v236, v228
	v_mov_b32_e32 v237, v229
	v_mov_b32_e32 v238, v230
	v_mov_b32_e32 v239, v231
	v_mov_b32_dpp v228, v232 row_ror:8 row_mask:0xf bank_mask:0xc
	v_mov_b32_dpp v229, v233 row_ror:8 row_mask:0xf bank_mask:0xc
	v_mov_b32_dpp v230, v234 row_ror:8 row_mask:0xf bank_mask:0xc
	v_mov_b32_dpp v231, v235 row_ror:8 row_mask:0xf bank_mask:0xc
	v_mov_b32_dpp v232, v236 row_ror:8 row_mask:0xf bank_mask:0x3
	v_mov_b32_dpp v233, v237 row_ror:8 row_mask:0xf bank_mask:0x3
	v_mov_b32_dpp v234, v238 row_ror:8 row_mask:0xf bank_mask:0x3
	v_mov_b32_dpp v235, v239 row_ror:8 row_mask:0xf bank_mask:0x3
	global_store_dwordx4 v240, v[228:231], s[100:101]
	s_add_u32 s100, s100, 0x20000
	s_addc_u32 s101, s101, 0
	global_store_dwordx4 v240, v[232:235], s[100:101]
	v_cvt_pk_bf16_f32 v228, v116, v117
	v_cvt_pk_bf16_f32 v229, v118, v119
	v_cvt_pk_bf16_f32 v230, v112, v113
	v_cvt_pk_bf16_f32 v231, v114, v115
	v_cvt_pk_bf16_f32 v232, v92, v93
	v_cvt_pk_bf16_f32 v233, v94, v95
	v_cvt_pk_bf16_f32 v234, v88, v89
	v_cvt_pk_bf16_f32 v235, v90, v91
	v_mov_b32_e32 v236, v228
	v_mov_b32_e32 v237, v229
	v_mov_b32_e32 v238, v230
	v_mov_b32_e32 v239, v231
	v_mov_b32_dpp v228, v232 row_ror:8 row_mask:0xf bank_mask:0xc
	v_mov_b32_dpp v229, v233 row_ror:8 row_mask:0xf bank_mask:0xc
	v_mov_b32_dpp v230, v234 row_ror:8 row_mask:0xf bank_mask:0xc
	v_mov_b32_dpp v231, v235 row_ror:8 row_mask:0xf bank_mask:0xc
	v_mov_b32_dpp v232, v236 row_ror:8 row_mask:0xf bank_mask:0x3
	v_mov_b32_dpp v233, v237 row_ror:8 row_mask:0xf bank_mask:0x3
	v_mov_b32_dpp v234, v238 row_ror:8 row_mask:0xf bank_mask:0x3
	v_mov_b32_dpp v235, v239 row_ror:8 row_mask:0xf bank_mask:0x3
	s_add_u32 s100, s100, 0x20000
	s_addc_u32 s101, s101, 0
	global_store_dwordx4 v240, v[228:231], s[100:101]
	s_add_u32 s100, s100, 0x20000
	s_addc_u32 s101, s101, 0
	global_store_dwordx4 v240, v[232:235], s[100:101]
	v_cvt_pk_bf16_f32 v228, v100, v101
	v_cvt_pk_bf16_f32 v229, v102, v103
	v_cvt_pk_bf16_f32 v230, v96, v97
	v_cvt_pk_bf16_f32 v231, v98, v99
	v_cvt_pk_bf16_f32 v232, v76, v77
	v_cvt_pk_bf16_f32 v233, v78, v79
	v_cvt_pk_bf16_f32 v234, v72, v73
	v_cvt_pk_bf16_f32 v235, v74, v75
	v_mov_b32_e32 v236, v228
	v_mov_b32_e32 v237, v229
	v_mov_b32_e32 v238, v230
	v_mov_b32_e32 v239, v231
	v_mov_b32_dpp v228, v232 row_ror:8 row_mask:0xf bank_mask:0xc
	v_mov_b32_dpp v229, v233 row_ror:8 row_mask:0xf bank_mask:0xc
	v_mov_b32_dpp v230, v234 row_ror:8 row_mask:0xf bank_mask:0xc
	v_mov_b32_dpp v231, v235 row_ror:8 row_mask:0xf bank_mask:0xc
	v_mov_b32_dpp v232, v236 row_ror:8 row_mask:0xf bank_mask:0x3
	v_mov_b32_dpp v233, v237 row_ror:8 row_mask:0xf bank_mask:0x3
	v_mov_b32_dpp v234, v238 row_ror:8 row_mask:0xf bank_mask:0x3
	v_mov_b32_dpp v235, v239 row_ror:8 row_mask:0xf bank_mask:0x3
	s_add_u32 s100, s100, 0x20000
	s_addc_u32 s101, s101, 0
	global_store_dwordx4 v240, v[228:231], s[100:101]
	s_add_u32 s100, s100, 0x20000
	s_addc_u32 s101, s101, 0
	global_store_dwordx4 v240, v[232:235], s[100:101]
	v_cvt_pk_bf16_f32 v228, v84, v85
	v_cvt_pk_bf16_f32 v229, v86, v87
	v_cvt_pk_bf16_f32 v230, v80, v81
	v_cvt_pk_bf16_f32 v231, v82, v83
	v_cvt_pk_bf16_f32 v232, v68, v69
	v_cvt_pk_bf16_f32 v233, v70, v71
	v_cvt_pk_bf16_f32 v234, v64, v65
	v_cvt_pk_bf16_f32 v235, v66, v67
	v_mov_b32_e32 v236, v228
	v_mov_b32_e32 v237, v229
	v_mov_b32_e32 v238, v230
	v_mov_b32_e32 v239, v231
	v_mov_b32_dpp v228, v232 row_ror:8 row_mask:0xf bank_mask:0xc
	v_mov_b32_dpp v229, v233 row_ror:8 row_mask:0xf bank_mask:0xc
	v_mov_b32_dpp v230, v234 row_ror:8 row_mask:0xf bank_mask:0xc
	v_mov_b32_dpp v231, v235 row_ror:8 row_mask:0xf bank_mask:0xc
	v_mov_b32_dpp v232, v236 row_ror:8 row_mask:0xf bank_mask:0x3
	v_mov_b32_dpp v233, v237 row_ror:8 row_mask:0xf bank_mask:0x3
	v_mov_b32_dpp v234, v238 row_ror:8 row_mask:0xf bank_mask:0x3
	v_mov_b32_dpp v235, v239 row_ror:8 row_mask:0xf bank_mask:0x3
	s_add_u32 s100, s100, 0x20000
	s_addc_u32 s101, s101, 0
	global_store_dwordx4 v240, v[228:231], s[100:101]
	s_add_u32 s100, s100, 0x20000
	s_addc_u32 s101, s101, 0
	global_store_dwordx4 v240, v[232:235], s[100:101]
	v_cvt_pk_bf16_f32 v228, v60, v61
	v_cvt_pk_bf16_f32 v229, v62, v63
	v_cvt_pk_bf16_f32 v230, v56, v57
	v_cvt_pk_bf16_f32 v231, v58, v59
	v_cvt_pk_bf16_f32 v232, v44, v45
	v_cvt_pk_bf16_f32 v233, v46, v47
	v_cvt_pk_bf16_f32 v234, v40, v41
	v_cvt_pk_bf16_f32 v235, v42, v43
	v_mov_b32_e32 v236, v228
	v_mov_b32_e32 v237, v229
	v_mov_b32_e32 v238, v230
	v_mov_b32_e32 v239, v231
	v_mov_b32_dpp v228, v232 row_ror:8 row_mask:0xf bank_mask:0xc
	v_mov_b32_dpp v229, v233 row_ror:8 row_mask:0xf bank_mask:0xc
	v_mov_b32_dpp v230, v234 row_ror:8 row_mask:0xf bank_mask:0xc
	v_mov_b32_dpp v231, v235 row_ror:8 row_mask:0xf bank_mask:0xc
	v_mov_b32_dpp v232, v236 row_ror:8 row_mask:0xf bank_mask:0x3
	v_mov_b32_dpp v233, v237 row_ror:8 row_mask:0xf bank_mask:0x3
	v_mov_b32_dpp v234, v238 row_ror:8 row_mask:0xf bank_mask:0x3
	v_mov_b32_dpp v235, v239 row_ror:8 row_mask:0xf bank_mask:0x3
	s_add_u32 s100, s100, 0x120000
	s_addc_u32 s101, s101, 0
	global_store_dwordx4 v240, v[228:231], s[100:101]
	s_add_u32 s100, s100, 0x20000
	s_addc_u32 s101, s101, 0
	global_store_dwordx4 v240, v[232:235], s[100:101]
	v_cvt_pk_bf16_f32 v228, v52, v53
	v_cvt_pk_bf16_f32 v229, v54, v55
	v_cvt_pk_bf16_f32 v230, v48, v49
	v_cvt_pk_bf16_f32 v231, v50, v51
	v_cvt_pk_bf16_f32 v232, v28, v29
	v_cvt_pk_bf16_f32 v233, v30, v31
	v_cvt_pk_bf16_f32 v234, v24, v25
	v_cvt_pk_bf16_f32 v235, v26, v27
	v_mov_b32_e32 v236, v228
	v_mov_b32_e32 v237, v229
	v_mov_b32_e32 v238, v230
	v_mov_b32_e32 v239, v231
	v_mov_b32_dpp v228, v232 row_ror:8 row_mask:0xf bank_mask:0xc
	v_mov_b32_dpp v229, v233 row_ror:8 row_mask:0xf bank_mask:0xc
	v_mov_b32_dpp v230, v234 row_ror:8 row_mask:0xf bank_mask:0xc
	v_mov_b32_dpp v231, v235 row_ror:8 row_mask:0xf bank_mask:0xc
	v_mov_b32_dpp v232, v236 row_ror:8 row_mask:0xf bank_mask:0x3
	v_mov_b32_dpp v233, v237 row_ror:8 row_mask:0xf bank_mask:0x3
	v_mov_b32_dpp v234, v238 row_ror:8 row_mask:0xf bank_mask:0x3
	v_mov_b32_dpp v235, v239 row_ror:8 row_mask:0xf bank_mask:0x3
	s_add_u32 s100, s100, 0x20000
	s_addc_u32 s101, s101, 0
	global_store_dwordx4 v240, v[228:231], s[100:101]
	s_add_u32 s100, s100, 0x20000
	s_addc_u32 s101, s101, 0
	global_store_dwordx4 v240, v[232:235], s[100:101]
	v_cvt_pk_bf16_f32 v228, v36, v37
	v_cvt_pk_bf16_f32 v229, v38, v39
	v_cvt_pk_bf16_f32 v230, v32, v33
	v_cvt_pk_bf16_f32 v231, v34, v35
	v_cvt_pk_bf16_f32 v232, v12, v13
	v_cvt_pk_bf16_f32 v233, v14, v15
	v_cvt_pk_bf16_f32 v234, v8, v9
	v_cvt_pk_bf16_f32 v235, v10, v11
	v_mov_b32_e32 v236, v228
	v_mov_b32_e32 v237, v229
	v_mov_b32_e32 v238, v230
	v_mov_b32_e32 v239, v231
	v_mov_b32_dpp v228, v232 row_ror:8 row_mask:0xf bank_mask:0xc
	v_mov_b32_dpp v229, v233 row_ror:8 row_mask:0xf bank_mask:0xc
	v_mov_b32_dpp v230, v234 row_ror:8 row_mask:0xf bank_mask:0xc
	v_mov_b32_dpp v231, v235 row_ror:8 row_mask:0xf bank_mask:0xc
	v_mov_b32_dpp v232, v236 row_ror:8 row_mask:0xf bank_mask:0x3
	v_mov_b32_dpp v233, v237 row_ror:8 row_mask:0xf bank_mask:0x3
	v_mov_b32_dpp v234, v238 row_ror:8 row_mask:0xf bank_mask:0x3
	v_mov_b32_dpp v235, v239 row_ror:8 row_mask:0xf bank_mask:0x3
	s_add_u32 s100, s100, 0x20000
	s_addc_u32 s101, s101, 0
	global_store_dwordx4 v240, v[228:231], s[100:101]
	s_add_u32 s100, s100, 0x20000
	s_addc_u32 s101, s101, 0
	global_store_dwordx4 v240, v[232:235], s[100:101]
	v_cvt_pk_bf16_f32 v228, v20, v21
	v_cvt_pk_bf16_f32 v229, v22, v23
	v_cvt_pk_bf16_f32 v230, v16, v17
	v_cvt_pk_bf16_f32 v231, v18, v19
	v_cvt_pk_bf16_f32 v232, v4, v5
	v_cvt_pk_bf16_f32 v233, v6, v7
	v_cvt_pk_bf16_f32 v234, v0, v1
	v_cvt_pk_bf16_f32 v235, v2, v3
	v_mov_b32_e32 v236, v228
	v_mov_b32_e32 v237, v229
	v_mov_b32_e32 v238, v230
	v_mov_b32_e32 v239, v231
	v_mov_b32_dpp v228, v232 row_ror:8 row_mask:0xf bank_mask:0xc
	v_mov_b32_dpp v229, v233 row_ror:8 row_mask:0xf bank_mask:0xc
	v_mov_b32_dpp v230, v234 row_ror:8 row_mask:0xf bank_mask:0xc
	v_mov_b32_dpp v231, v235 row_ror:8 row_mask:0xf bank_mask:0xc
	v_mov_b32_dpp v232, v236 row_ror:8 row_mask:0xf bank_mask:0x3
	v_mov_b32_dpp v233, v237 row_ror:8 row_mask:0xf bank_mask:0x3
	v_mov_b32_dpp v234, v238 row_ror:8 row_mask:0xf bank_mask:0x3
	v_mov_b32_dpp v235, v239 row_ror:8 row_mask:0xf bank_mask:0x3
	s_add_u32 s100, s100, 0x20000
	s_addc_u32 s101, s101, 0
	global_store_dwordx4 v240, v[228:231], s[100:101]
	s_add_u32 s100, s100, 0x20000
	s_addc_u32 s101, s101, 0
	global_store_dwordx4 v240, v[232:235], s[100:101]
	s_branch .Lfl8_done

.LBB0_1181:
	ds_read_b128 v[88:91], v176
	ds_read_b128 v[92:95], v176 offset:64
	ds_read_b128 v[236:239], v176 offset:128
	ds_read_b128 v[232:235], v176 offset:192
	ds_read_b128 v[250:253], v176 offset:4352
	v_mov_b64_e32 v[106:107], v[2:3]
	v_mov_b64_e32 v[104:105], v[0:1]
	v_mov_b64_e32 v[122:123], v[6:7]
	s_waitcnt lgkmcnt(4)
	v_mfma_f32_16x16x32_bf16 v[96:99], v[40:43], v[88:91], 0
	v_mov_b64_e32 v[120:121], v[4:5]
	s_ashr_i32 s31, s30, 31
	s_lshl_b64 s[0:1], s[30:31], 14
	v_mfma_f32_16x16x32_bf16 v[88:91], v[48:51], v[88:91], 0
	s_and_b32 s27, s25, 0x1000
	s_add_u32 s0, s7, s0
	s_addc_u32 s1, s19, s1
	s_waitcnt lgkmcnt(3)
	v_mfma_f32_16x16x32_bf16 v[96:99], v[28:31], v[92:95], v[96:99]
	v_lshlrev_b32_e32 v130, 1, v175
	v_mov_b32_e32 v244, v139
	v_mov_b32_e32 v139, v131
	v_mfma_f32_16x16x32_bf16 v[88:91], v[24:27], v[92:95], v[88:91]
	ds_read_b128 v[0:3], v176 offset:4416
	s_ashr_i32 s29, s28, 31
	s_waitcnt lgkmcnt(3)
	v_mfma_f32_16x16x32_bf16 v[96:99], v[20:23], v[236:239], v[96:99]
	v_mov_b32_e32 v243, v193
	v_mov_b32_e32 v245, v192
	v_add_u32_e32 v209, s23, v205
	v_mfma_f32_16x16x32_bf16 v[88:91], v[16:19], v[236:239], v[88:91]
	v_mov_b32_e32 v242, v194
	s_waitcnt lgkmcnt(2)
	v_mfma_f32_16x16x32_bf16 v[108:111], v[12:15], v[232:235], v[88:91]
	s_waitcnt lgkmcnt(0)
	v_mfma_f32_16x16x32_bf16 v[88:91], v[40:43], v[250:253], 0
	v_mfma_f32_16x16x32_bf16 v[92:95], v[48:51], v[250:253], 0
	v_mfma_f32_16x16x32_bf16 v[124:127], v[8:11], v[232:235], v[96:99]
	ds_read_b128 v[4:7], v176 offset:4480
	s_nop 1
	ds_read_b128 v[96:99], v176 offset:4544
	ds_read_b128 v[100:103], v176 offset:8704
	ds_read_b128 v[116:119], v176 offset:8768
	ds_read_b128 v[210:213], v176 offset:8832
	ds_read_b128 v[214:217], v176 offset:8896
	ds_read_b128 v[218:221], v176 offset:13056
	ds_read_b128 v[222:225], v176 offset:13120
	ds_read_b128 v[226:229], v176 offset:13184
	ds_read_b128 v[230:233], v176 offset:13248
	v_mfma_f32_16x16x32_bf16 v[88:91], v[28:31], v[0:3], v[88:91]
	v_mfma_f32_16x16x32_bf16 v[0:3], v[24:27], v[0:3], v[92:95]
	s_waitcnt lgkmcnt(9)
	v_mfma_f32_16x16x32_bf16 v[0:3], v[16:19], v[4:7], v[0:3]
	s_nop 0
	v_lshl_add_u64 v[92:93], s[0:1], 0, v[142:143]
	v_mfma_f32_16x16x32_bf16 v[88:91], v[20:23], v[4:7], v[88:91]
	v_lshl_add_u64 v[4:5], v[92:93], 0, v[130:131]
	v_lshl_add_u64 v[4:5], v[4:5], 0, v[138:139]
	s_waitcnt lgkmcnt(8)
	v_mfma_f32_16x16x32_bf16 v[112:115], v[12:15], v[96:99], v[0:3]
	s_waitcnt lgkmcnt(7)
	v_mfma_f32_16x16x32_bf16 v[0:3], v[40:43], v[100:103], 0
	v_mfma_f32_16x16x32_bf16 v[234:237], v[8:11], v[96:99], v[88:91]
	s_nop 2
	v_add_u32_e32 v90, s27, v174
	s_waitcnt lgkmcnt(6)
	v_mfma_f32_16x16x32_bf16 v[0:3], v[28:31], v[116:119], v[0:3]
	v_readfirstlane_b32 s27, v90
	s_mov_b32 m0, s27
	v_add_u32_e32 v91, 0x800, v90
	global_load_lds_dwordx4 v[4:5], off
	v_add_u32_e32 v4, s23, v208
	v_ashrrev_i32_e32 v5, 31, v4
	v_lshlrev_b64 v[88:89], 13, v[4:5]
	v_readfirstlane_b32 s27, v91
	v_lshl_add_u64 v[88:89], v[140:141], 0, v[88:89]
	s_mov_b32 m0, s27
	v_add_u32_e32 v91, 0x400, v90
	global_load_lds_dwordx4 v[88:89], off
	v_lshl_add_u64 v[88:89], s[0:1], 0, v[144:145]
	s_waitcnt lgkmcnt(0)
	v_mfma_f32_16x16x32_bf16 v[0:3], v[20:23], v[210:213], v[0:3]
	v_lshl_add_u64 v[88:89], v[88:89], 0, v[130:131]
	v_readfirstlane_b32 s0, v91
	v_lshl_add_u64 v[88:89], v[88:89], 0, v[138:139]
	s_mov_b32 m0, s0
	v_mfma_f32_16x16x32_bf16 v[238:241], v[8:11], v[214:217], v[0:3]
	global_load_lds_dwordx4 v[88:89], off
	v_add_u32_e32 v88, s23, v207
	v_ashrrev_i32_e32 v89, 31, v88
	v_add_u32_e32 v2, 0xc00, v90
	v_mfma_f32_16x16x32_bf16 v[4:7], v[48:51], v[100:103], 0
	v_lshlrev_b64 v[88:89], 13, v[88:89]
	v_readfirstlane_b32 s0, v2
	v_lshl_add_u64 v[0:1], v[140:141], 0, v[88:89]
	s_mov_b32 m0, s0
	v_mfma_f32_16x16x32_bf16 v[4:7], v[24:27], v[116:119], v[4:7]
	global_load_lds_dwordx4 v[0:1], off
	s_ashr_i32 s27, s26, 31
	v_mfma_f32_16x16x32_bf16 v[0:3], v[40:43], v[218:221], 0
	s_lshl_b64 s[0:1], s[28:29], 13
	s_lshl_b64 s[48:49], s[26:27], 14
	v_mfma_f32_16x16x32_bf16 v[40:43], v[48:51], v[218:221], 0
	v_lshl_add_u64 v[48:49], v[150:151], 0, s[48:49]
	v_add_u32_e32 v220, 0x82, v209
	v_ashrrev_i32_e32 v221, 31, v220
	v_mfma_f32_16x16x32_bf16 v[28:31], v[28:31], v[222:225], v[0:3]
	v_lshlrev_b64 v[220:221], 7, v[220:221]
	v_lshl_add_u64 v[220:221], s[14:15], 0, v[220:221]
	v_mfma_f32_16x16x32_bf16 v[24:27], v[24:27], v[222:225], v[40:43]
	v_add_u32_e32 v222, 0x83, v209
	v_ashrrev_i32_e32 v223, 31, v222
	v_lshlrev_b64 v[222:223], 7, v[222:223]
	v_mfma_f32_16x16x32_bf16 v[4:7], v[16:19], v[210:213], v[4:7]
	v_lshl_add_u64 v[222:223], s[14:15], 0, v[222:223]
	v_mfma_f32_16x16x32_bf16 v[20:23], v[20:23], v[226:229], v[28:31]
	s_nop 2
	v_add_u32_e32 v28, s23, v206
	v_mfma_f32_16x16x32_bf16 v[16:19], v[16:19], v[226:229], v[24:27]
	v_ashrrev_i32_e32 v29, 31, v28
	v_lshlrev_b64 v[28:29], 12, v[28:29]
	v_lshl_add_u64 v[210:211], v[154:155], 0, v[28:29]
	v_mfma_f32_16x16x32_bf16 v[116:119], v[12:15], v[214:217], v[4:7]
	v_mul_f32_e32 v229, 0x3fb8aa3b, v243
	v_exp_f32_e32 v229, v229
	s_nop 0
	v_lshl_add_u64 v[4:5], v[148:149], 0, s[0:1]
	s_lshl_b64 s[0:1], s[28:29], 14
	v_lshl_add_u64 v[192:193], v[152:153], 0, s[0:1]
	global_load_dwordx4 v[0:3], v[4:5], off
	s_nop 0
	global_load_dwordx4 v[4:7], v[4:5], off offset:64
	s_nop 0
	global_load_dwordx4 v[100:103], v[48:49], off
	global_load_dwordx4 v[96:99], v[48:49], off offset:64
	global_load_dwordx4 v[92:95], v[48:49], off offset:2048
	global_load_dwordx4 v[88:91], v[48:49], off offset:2112
	global_load_dwordx4 v[40:43], v[192:193], off
	global_load_dwordx4 v[28:31], v[192:193], off offset:64
	v_mfma_f32_16x16x32_bf16 v[212:215], v[8:11], v[230:233], v[20:23]
	global_load_dwordx4 v[48:51], v[210:211], off
	global_load_dwordx4 v[24:27], v[210:211], off offset:64
	s_nop 0
	global_load_dwordx4 v[20:23], v[192:193], off offset:128
	global_load_dwordx4 v[8:11], v[192:193], off offset:192
	v_add_u32_e32 v192, 0x80, v209
	v_ashrrev_i32_e32 v193, 31, v192
	v_mfma_f32_16x16x32_bf16 v[216:219], v[12:15], v[230:233], v[16:19]
	s_nop 2
	global_load_dwordx4 v[16:19], v[210:211], off offset:128
	global_load_dwordx4 v[12:15], v[210:211], off offset:192
	v_add_u32_e32 v210, 0x81, v209
	v_ashrrev_i32_e32 v211, 31, v210
	v_lshlrev_b64 v[192:193], 7, v[192:193]
	v_lshlrev_b64 v[210:211], 7, v[210:211]
	s_add_i32 s0, s25, 0xfffff000
	v_lshl_add_u64 v[192:193], s[14:15], 0, v[192:193]
	v_lshl_add_u64 v[210:211], s[14:15], 0, v[210:211]
	s_and_b32 s0, s0, 0x1000
	global_load_dword v194, v[192:193], off
	s_nop 0
	global_load_dword v193, v[210:211], off
	global_load_dword v139, v[220:221], off
	global_load_dword v192, v[222:223], off
	global_load_dword v130, v131, s[34:35]
	v_add_u32_e32 v210, s0, v174
	v_add_u32_e32 v211, v210, v195
	v_add3_u32 v211, v211, v196, v197
	ds_read2st64_b64 v[220:223], v211 offset1:1
	ds_read2st64_b64 v[224:227], v211 offset0:2 offset1:3
	v_mul_f32_e32 v211, 0x3fb8aa3b, v242
	v_sub_f32_e32 v230, v204, v243
	v_exp_f32_e32 v228, v211
	s_waitcnt lgkmcnt(0)
	v_lshlrev_b32_e32 v243, 16, v220
	v_sub_f32_e32 v211, v204, v242
	v_mul_f32_e32 v230, 0x3fb8aa3b, v230
	v_sub_f32_e32 v243, v243, v124
	v_and_b32_e32 v124, 0xffff0000, v220
	v_mul_f32_e32 v211, 0x3fb8aa3b, v211
	v_exp_f32_e32 v232, v230
	v_mul_f32_e32 v230, 0x3fb8aa3b, v244
	v_sub_f32_e32 v231, v204, v244
	v_sub_f32_e32 v242, v204, v245
	v_sub_f32_e32 v244, v124, v125
	v_alignbit_b32 v124, v221, v220, 16
	v_exp_f32_e32 v211, v211
	v_mul_f32_e32 v231, 0x3fb8aa3b, v231
	v_mul_f32_e32 v242, 0x3fb8aa3b, v242
	v_and_b32_e32 v124, 0xffff0000, v124
	v_exp_f32_e32 v233, v231
	v_exp_f32_e32 v242, v242
	v_sub_f32_e32 v126, v124, v126
	v_and_b32_e32 v124, 0xffff0000, v221
	v_sub_f32_e32 v127, v124, v127
	v_cvt_pk_bf16_f32 v124, v243, v244
	v_cvt_pk_bf16_f32 v125, v126, v127
	ds_write_b64 v178, v[124:125] offset:34816
	v_mul_f32_e32 v124, v211, v243
	v_mul_f32_e32 v125, v232, v244
	v_cvt_pk_bf16_f32 v124, v124, v125
	v_mul_f32_e32 v125, v233, v126
	v_mul_f32_e32 v126, v242, v127
	v_cvt_pk_bf16_f32 v125, v125, v126
	ds_write_b64 v178, v[124:125] offset:53248
	v_lshlrev_b32_e32 v124, 16, v222
	v_sub_f32_e32 v126, v124, v234
	v_and_b32_e32 v124, 0xffff0000, v222
	v_sub_f32_e32 v127, v124, v235
	v_alignbit_b32 v124, v223, v222, 16
	v_and_b32_e32 v124, 0xffff0000, v124
	v_sub_f32_e32 v220, v124, v236
	v_and_b32_e32 v124, 0xffff0000, v223
	v_sub_f32_e32 v221, v124, v237
	v_cvt_pk_bf16_f32 v124, v126, v127
	v_cvt_pk_bf16_f32 v125, v220, v221
	ds_write_b64 v178, v[124:125] offset:37120
	v_mul_f32_e32 v124, v211, v126
	v_mul_f32_e32 v125, v232, v127
	v_cvt_pk_bf16_f32 v124, v124, v125
	v_mul_f32_e32 v125, v233, v220
	v_mul_f32_e32 v126, v242, v221
	v_cvt_pk_bf16_f32 v125, v125, v126
	ds_write_b64 v178, v[124:125] offset:55552
	v_lshlrev_b32_e32 v124, 16, v224
	v_sub_f32_e32 v126, v124, v238
	v_and_b32_e32 v124, 0xffff0000, v224
	v_sub_f32_e32 v127, v124, v239
	v_alignbit_b32 v124, v225, v224, 16
	v_and_b32_e32 v124, 0xffff0000, v124
	v_sub_f32_e32 v220, v124, v240
	v_and_b32_e32 v124, 0xffff0000, v225
	v_sub_f32_e32 v221, v124, v241
	v_cvt_pk_bf16_f32 v124, v126, v127
	v_cvt_pk_bf16_f32 v125, v220, v221
	ds_write_b64 v178, v[124:125] offset:39424
	v_mul_f32_e32 v124, v211, v126
	v_mul_f32_e32 v125, v232, v127
	v_cvt_pk_bf16_f32 v124, v124, v125
	v_mul_f32_e32 v125, v233, v220
	v_mul_f32_e32 v126, v242, v221
	v_cvt_pk_bf16_f32 v125, v125, v126
	ds_write_b64 v178, v[124:125] offset:57856
	v_lshlrev_b32_e32 v124, 16, v226
	v_sub_f32_e32 v126, v124, v212
	v_and_b32_e32 v124, 0xffff0000, v226
	v_sub_f32_e32 v127, v124, v213
	v_alignbit_b32 v124, v227, v226, 16
	v_and_b32_e32 v124, 0xffff0000, v124
	v_sub_f32_e32 v212, v124, v214
	v_and_b32_e32 v124, 0xffff0000, v227
	v_sub_f32_e32 v213, v124, v215
	v_cvt_pk_bf16_f32 v124, v126, v127
	v_cvt_pk_bf16_f32 v125, v212, v213
	ds_write_b64 v178, v[124:125] offset:41728
	v_mul_f32_e32 v124, v211, v126
	v_mul_f32_e32 v125, v232, v127
	v_cvt_pk_bf16_f32 v124, v124, v125
	v_mul_f32_e32 v125, v233, v212
	v_mul_f32_e32 v126, v242, v213
	v_cvt_pk_bf16_f32 v125, v125, v126
	ds_write_b64 v178, v[124:125] offset:60160
	v_mul_f32_e32 v231, 0x3fb8aa3b, v245
	s_waitcnt lgkmcnt(0)
	s_barrier
	v_exp_f32_e32 v230, v230
	v_exp_f32_e32 v231, v231
	ds_read_b128 v[124:127], v180 offset:34816
	ds_read_b128 v[220:223], v180 offset:34880
	ds_read_b128 v[224:227], v180 offset:37120
	ds_read_b128 v[232:235], v180 offset:37184
	ds_read_b128 v[236:239], v180 offset:39424
	ds_read_b128 v[240:243], v180 offset:39488
	ds_read_b128 v[250:253], v180 offset:41728
	v_mul_f32_e64 v212, v228, v216
	v_mul_f32_e64 v213, v229, v217
	v_pk_mul_f32 v[214:215], v[230:231], v[218:219]
	ds_read_b128 v[216:219], v180 offset:41792
	v_pk_mul_f32 v[108:109], v[228:229], v[108:109]
	v_pk_mul_f32 v[110:111], v[230:231], v[110:111]
	v_pk_mul_f32 v[112:113], v[228:229], v[112:113]
	v_pk_mul_f32 v[114:115], v[230:231], v[114:115]
	s_waitcnt lgkmcnt(6)
	v_mfma_f32_16x16x32_bf16 v[108:111], v[104:107], v[124:127], v[108:111]
	v_pk_mul_f32 v[116:117], v[228:229], v[116:117]
	v_pk_mul_f32 v[118:119], v[230:231], v[118:119]
	v_mfma_f32_16x16x32_bf16 v[108:111], v[120:123], v[220:223], v[108:111]
	s_waitcnt lgkmcnt(4)
	v_mfma_f32_16x16x32_bf16 v[112:115], v[104:107], v[224:227], v[112:115]
	v_mfma_f32_16x16x32_bf16 v[112:115], v[120:123], v[232:235], v[112:115]
	s_waitcnt lgkmcnt(2)
	v_mfma_f32_16x16x32_bf16 v[116:119], v[104:107], v[236:239], v[116:119]
	v_mfma_f32_16x16x32_bf16 v[116:119], v[120:123], v[240:243], v[116:119]
	s_waitcnt lgkmcnt(0)
	v_mfma_f32_16x16x32_bf16 v[104:107], v[104:107], v[250:253], v[212:215]
	v_mfma_f32_16x16x32_bf16 v[104:107], v[120:123], v[216:219], v[104:107]
	v_mul_f32_e64 v120, v114, v114
	v_mul_f32_e64 v121, v115, v115
	v_pk_mul_f32 v[122:123], v[112:113], v[112:113]
	v_pk_fma_f32 v[120:121], v[110:111], v[110:111], v[120:121]
	v_pk_fma_f32 v[122:123], v[108:109], v[108:109], v[122:123]
	v_pk_fma_f32 v[120:121], v[118:119], v[118:119], v[120:121]
	v_pk_fma_f32 v[122:123], v[116:117], v[116:117], v[122:123]
	s_nop 0
	v_pk_fma_f32 v[120:121], v[106:107], v[106:107], v[120:121]
	v_pk_fma_f32 v[122:123], v[104:105], v[104:105], v[122:123]
	s_nop 1
	v_add_f32_dpp v120, v120, v120 quad_perm:[1,0,3,2] row_mask:0xf bank_mask:0xf
	v_add_f32_dpp v121, v121, v121 quad_perm:[1,0,3,2] row_mask:0xf bank_mask:0xf
	v_add_f32_dpp v122, v122, v122 quad_perm:[1,0,3,2] row_mask:0xf bank_mask:0xf
	v_add_f32_dpp v123, v123, v123 quad_perm:[1,0,3,2] row_mask:0xf bank_mask:0xf
	v_add_f32_dpp v120, v120, v120 quad_perm:[2,3,0,1] row_mask:0xf bank_mask:0xf
	v_add_f32_dpp v121, v121, v121 quad_perm:[2,3,0,1] row_mask:0xf bank_mask:0xf
	v_add_f32_dpp v122, v122, v122 quad_perm:[2,3,0,1] row_mask:0xf bank_mask:0xf
	v_add_f32_dpp v123, v123, v123 quad_perm:[2,3,0,1] row_mask:0xf bank_mask:0xf
	v_add_f32_dpp v120, v120, v120 row_ror:12 row_mask:0xf bank_mask:0xf
	v_add_f32_dpp v121, v121, v121 row_ror:12 row_mask:0xf bank_mask:0xf
	v_add_f32_dpp v122, v122, v122 row_ror:12 row_mask:0xf bank_mask:0xf
	v_add_f32_dpp v123, v123, v123 row_ror:12 row_mask:0xf bank_mask:0xf
	v_add_f32_dpp v120, v120, v120 row_ror:8 row_mask:0xf bank_mask:0xf
	v_add_f32_dpp v121, v121, v121 row_ror:8 row_mask:0xf bank_mask:0xf
	v_add_f32_dpp v122, v122, v122 row_ror:8 row_mask:0xf bank_mask:0xf
	v_add_f32_dpp v123, v123, v123 row_ror:8 row_mask:0xf bank_mask:0xf
	s_and_saveexec_b64 s[0:1], vcc
	s_cbranch_execz .LBB0_1183
	ds_write2_b32 v198, v122, v123 offset1:1
	ds_write2_b32 v198, v120, v121 offset0:2 offset1:3

.LBB0_1409:
	ds_read_b128 v[146:149], v143
	ds_read_b128 v[150:153], v143 offset:1024
	ds_read_b128 v[154:157], v143 offset:2048
	ds_read_b128 v[158:161], v143 offset:3072
	s_add_i32 s51, s20, 2
	s_add_u32 s21, s18, 0xfff00080
	s_addc_u32 s22, s19, -1
	s_cmp_eq_u32 s48, s20
	s_cselect_b32 s20, s47, s49
	s_cselect_b32 s23, s7, s22
	s_cselect_b32 s22, s9, s21
	s_cselect_b32 s21, s46, s50
	s_add_i32 m0, s3, 0xc000
	ds_read_b128 v[162:165], v144
	ds_read_b128 v[166:169], v144 offset:1024
	ds_read_b128 v[170:173], v144 offset:2048
	ds_read_b128 v[174:177], v144 offset:3072
	ds_read_b128 v[178:181], v144 offset:4096
	ds_read_b128 v[182:185], v144 offset:5120
	ds_read_b128 v[186:189], v144 offset:6144
	ds_read_b128 v[190:193], v144 offset:7168
	global_load_lds_dwordx4 v136, s[18:19]
	s_add_i32 m0, s3, 0xe000
	s_nop 0
	global_load_lds_dwordx4 v138, s[18:19]
	s_waitcnt lgkmcnt(8)
	s_barrier
	s_waitcnt lgkmcnt(0)
	v_mfma_f32_16x16x32_bf16 v[124:127], v[146:149], v[162:165], v[124:127]
	v_mfma_f32_16x16x32_bf16 v[120:123], v[154:157], v[162:165], v[120:123]
	v_mfma_f32_16x16x32_bf16 v[108:111], v[146:149], v[170:173], v[108:111]
	v_mfma_f32_16x16x32_bf16 v[104:107], v[154:157], v[170:173], v[104:107]
	v_mfma_f32_16x16x32_bf16 v[92:95], v[146:149], v[178:181], v[92:95]
	v_mfma_f32_16x16x32_bf16 v[88:91], v[154:157], v[178:181], v[88:91]
	v_mfma_f32_16x16x32_bf16 v[76:79], v[146:149], v[186:189], v[76:79]
	v_mfma_f32_16x16x32_bf16 v[72:75], v[154:157], v[186:189], v[72:75]
	v_mfma_f32_16x16x32_bf16 v[124:127], v[150:153], v[166:169], v[124:127]
	v_mfma_f32_16x16x32_bf16 v[120:123], v[158:161], v[166:169], v[120:123]
	v_mfma_f32_16x16x32_bf16 v[108:111], v[150:153], v[174:177], v[108:111]
	v_mfma_f32_16x16x32_bf16 v[104:107], v[158:161], v[174:177], v[104:107]
	v_mfma_f32_16x16x32_bf16 v[92:95], v[150:153], v[182:185], v[92:95]
	v_mfma_f32_16x16x32_bf16 v[88:91], v[158:161], v[182:185], v[88:91]
	v_mfma_f32_16x16x32_bf16 v[76:79], v[150:153], v[190:193], v[76:79]
	v_mfma_f32_16x16x32_bf16 v[72:75], v[158:161], v[190:193], v[72:75]
	s_barrier
	s_add_i32 s52, s39, s27
	s_mov_b32 m0, s52
	ds_read_b128 v[194:197], v145
	ds_read_b128 v[198:201], v145 offset:1024
	ds_read_b128 v[204:207], v145 offset:2048
	ds_read_b128 v[208:211], v145 offset:3072
	global_load_lds_dwordx4 v132, s[20:21]
	s_add_i32 m0, s52, 0x2000
	s_nop 0
	global_load_lds_dwordx4 v128, s[20:21]
	s_barrier
	s_waitcnt lgkmcnt(0)
	v_mfma_f32_16x16x32_bf16 v[116:119], v[194:197], v[162:165], v[116:119]
	v_mfma_f32_16x16x32_bf16 v[112:115], v[204:207], v[162:165], v[112:115]
	v_mfma_f32_16x16x32_bf16 v[100:103], v[194:197], v[170:173], v[100:103]
	v_mfma_f32_16x16x32_bf16 v[96:99], v[204:207], v[170:173], v[96:99]
	v_mfma_f32_16x16x32_bf16 v[84:87], v[194:197], v[178:181], v[84:87]
	v_mfma_f32_16x16x32_bf16 v[80:83], v[204:207], v[178:181], v[80:83]
	v_mfma_f32_16x16x32_bf16 v[68:71], v[194:197], v[186:189], v[68:71]
	v_mfma_f32_16x16x32_bf16 v[64:67], v[204:207], v[186:189], v[64:67]
	v_mfma_f32_16x16x32_bf16 v[116:119], v[198:201], v[166:169], v[116:119]
	v_mfma_f32_16x16x32_bf16 v[112:115], v[208:211], v[166:169], v[112:115]
	v_mfma_f32_16x16x32_bf16 v[100:103], v[198:201], v[174:177], v[100:103]
	v_mfma_f32_16x16x32_bf16 v[96:99], v[208:211], v[174:177], v[96:99]
	v_mfma_f32_16x16x32_bf16 v[84:87], v[198:201], v[182:185], v[84:87]
	v_mfma_f32_16x16x32_bf16 v[80:83], v[208:211], v[182:185], v[80:83]
	v_mfma_f32_16x16x32_bf16 v[68:71], v[198:201], v[190:193], v[68:71]
	v_mfma_f32_16x16x32_bf16 v[64:67], v[208:211], v[190:193], v[64:67]
	s_mov_b32 m0, s3
	s_mov_b64 s[98:99], s[22:23]
	s_barrier
	ds_read_b128 v[162:165], v144 offset:16384
	ds_read_b128 v[166:169], v144 offset:17408
	ds_read_b128 v[170:173], v144 offset:18432
	ds_read_b128 v[174:177], v144 offset:19456
	ds_read_b128 v[178:181], v144 offset:20480
	ds_read_b128 v[182:185], v144 offset:21504
	ds_read_b128 v[186:189], v144 offset:22528
	ds_read_b128 v[190:193], v144 offset:23552
	global_load_lds_dwordx4 v134, s[22:23]
	s_mov_b32 m0, s28
	s_nop 0
	global_load_lds_dwordx4 v130, s[22:23]
	s_barrier
	s_waitcnt lgkmcnt(0)
	v_mfma_f32_16x16x32_bf16 v[60:63], v[146:149], v[162:165], v[60:63]
	v_mfma_f32_16x16x32_bf16 v[56:59], v[154:157], v[162:165], v[56:59]
	v_mfma_f32_16x16x32_bf16 v[44:47], v[146:149], v[170:173], v[44:47]
	v_mfma_f32_16x16x32_bf16 v[40:43], v[154:157], v[170:173], v[40:43]
	v_mfma_f32_16x16x32_bf16 v[28:31], v[146:149], v[178:181], v[28:31]
	v_mfma_f32_16x16x32_bf16 v[24:27], v[154:157], v[178:181], v[24:27]
	v_mfma_f32_16x16x32_bf16 v[12:15], v[146:149], v[186:189], v[12:15]
	v_mfma_f32_16x16x32_bf16 v[8:11], v[154:157], v[186:189], v[8:11]
	v_mfma_f32_16x16x32_bf16 v[60:63], v[150:153], v[166:169], v[60:63]
	v_mfma_f32_16x16x32_bf16 v[56:59], v[158:161], v[166:169], v[56:59]
	v_mfma_f32_16x16x32_bf16 v[44:47], v[150:153], v[174:177], v[44:47]
	v_mfma_f32_16x16x32_bf16 v[40:43], v[158:161], v[174:177], v[40:43]
	v_mfma_f32_16x16x32_bf16 v[28:31], v[150:153], v[182:185], v[28:31]
	v_mfma_f32_16x16x32_bf16 v[24:27], v[158:161], v[182:185], v[24:27]
	v_mfma_f32_16x16x32_bf16 v[12:15], v[150:153], v[190:193], v[12:15]
	v_mfma_f32_16x16x32_bf16 v[8:11], v[158:161], v[190:193], v[8:11]
	s_barrier
	s_add_u32 s52, s20, 0x40000
	s_addc_u32 s53, s21, 0
	s_add_i32 s54, s40, s27
	s_mov_b32 m0, s54
	s_nop 0
	global_load_lds_dwordx4 v132, s[52:53]
	s_add_i32 m0, s54, 0x2000
	s_nop 0
	global_load_lds_dwordx4 v128, s[52:53]
	s_waitcnt vmcnt(6)
	s_barrier
	v_mfma_f32_16x16x32_bf16 v[52:55], v[194:197], v[162:165], v[52:55]
	v_mfma_f32_16x16x32_bf16 v[48:51], v[204:207], v[162:165], v[48:51]
	v_mfma_f32_16x16x32_bf16 v[36:39], v[194:197], v[170:173], v[36:39]
	v_mfma_f32_16x16x32_bf16 v[32:35], v[204:207], v[170:173], v[32:35]
	v_mfma_f32_16x16x32_bf16 v[20:23], v[194:197], v[178:181], v[20:23]
	v_mfma_f32_16x16x32_bf16 v[16:19], v[204:207], v[178:181], v[16:19]
	v_mfma_f32_16x16x32_bf16 v[4:7], v[194:197], v[186:189], v[4:7]
	v_mfma_f32_16x16x32_bf16 v[0:3], v[204:207], v[186:189], v[0:3]
	v_mfma_f32_16x16x32_bf16 v[52:55], v[198:201], v[166:169], v[52:55]
	v_mfma_f32_16x16x32_bf16 v[48:51], v[208:211], v[166:169], v[48:51]
	v_mfma_f32_16x16x32_bf16 v[36:39], v[198:201], v[174:177], v[36:39]
	v_mfma_f32_16x16x32_bf16 v[32:35], v[208:211], v[174:177], v[32:35]
	v_mfma_f32_16x16x32_bf16 v[20:23], v[198:201], v[182:185], v[20:23]
	v_mfma_f32_16x16x32_bf16 v[16:19], v[208:211], v[182:185], v[16:19]
	v_mfma_f32_16x16x32_bf16 v[4:7], v[198:201], v[190:193], v[4:7]
	v_mfma_f32_16x16x32_bf16 v[0:3], v[208:211], v[190:193], v[0:3]
	s_add_i32 s52, 0, 0x18000
	v_add_u32_e32 v158, s52, v141
	s_barrier
	ds_read_b128 v[146:149], v158
	ds_read_b128 v[150:153], v158 offset:1024
	ds_read_b128 v[154:157], v158 offset:2048
	ds_read_b128 v[158:161], v158 offset:3072
	s_add_u32 s22, s22, 0x100000
	s_addc_u32 s23, s23, 0
	s_mov_b32 m0, s29
	ds_read_b128 v[162:165], v144 offset:32768
	ds_read_b128 v[166:169], v144 offset:33792
	ds_read_b128 v[170:173], v144 offset:34816
	ds_read_b128 v[174:177], v144 offset:35840
	ds_read_b128 v[178:181], v144 offset:36864
	ds_read_b128 v[182:185], v144 offset:37888
	ds_read_b128 v[186:189], v144 offset:38912
	ds_read_b128 v[190:193], v144 offset:39936
	global_load_lds_dwordx4 v134, s[22:23]
	s_mov_b32 m0, s30
	s_nop 0
	global_load_lds_dwordx4 v130, s[22:23]
	s_waitcnt lgkmcnt(8)
	s_barrier
	s_waitcnt lgkmcnt(0)
	v_mfma_f32_16x16x32_bf16 v[124:127], v[146:149], v[162:165], v[124:127]
	v_mfma_f32_16x16x32_bf16 v[120:123], v[154:157], v[162:165], v[120:123]
	v_mfma_f32_16x16x32_bf16 v[108:111], v[146:149], v[170:173], v[108:111]
	v_mfma_f32_16x16x32_bf16 v[104:107], v[154:157], v[170:173], v[104:107]
	v_mfma_f32_16x16x32_bf16 v[92:95], v[146:149], v[178:181], v[92:95]
	v_mfma_f32_16x16x32_bf16 v[88:91], v[154:157], v[178:181], v[88:91]
	v_mfma_f32_16x16x32_bf16 v[76:79], v[146:149], v[186:189], v[76:79]
	v_mfma_f32_16x16x32_bf16 v[72:75], v[154:157], v[186:189], v[72:75]
	v_mfma_f32_16x16x32_bf16 v[124:127], v[150:153], v[166:169], v[124:127]
	v_mfma_f32_16x16x32_bf16 v[120:123], v[158:161], v[166:169], v[120:123]
	v_mfma_f32_16x16x32_bf16 v[108:111], v[150:153], v[174:177], v[108:111]
	v_mfma_f32_16x16x32_bf16 v[104:107], v[158:161], v[174:177], v[104:107]
	v_mfma_f32_16x16x32_bf16 v[92:95], v[150:153], v[182:185], v[92:95]
	v_mfma_f32_16x16x32_bf16 v[88:91], v[158:161], v[182:185], v[88:91]
	v_mfma_f32_16x16x32_bf16 v[76:79], v[150:153], v[190:193], v[76:79]
	v_mfma_f32_16x16x32_bf16 v[72:75], v[158:161], v[190:193], v[72:75]
	s_barrier
	s_add_i32 s22, 0, 0x1c000
	s_add_i32 s23, s52, s27
	v_add_u32_e32 v208, s22, v141
	s_mov_b32 m0, s23
	ds_read_b128 v[194:197], v208
	ds_read_b128 v[198:201], v208 offset:1024
	ds_read_b128 v[204:207], v208 offset:2048
	ds_read_b128 v[208:211], v208 offset:3072
	s_add_u32 s100, s20, 0x80
	s_addc_u32 s101, s21, 0
	global_load_lds_dwordx4 v132, s[100:101]
	s_add_i32 m0, s23, 0x2000
	s_nop 0
	s_add_u32 s100, s20, 0x80
	s_addc_u32 s101, s21, 0
	global_load_lds_dwordx4 v128, s[100:101]
	s_barrier
	s_waitcnt lgkmcnt(0)
	v_mfma_f32_16x16x32_bf16 v[116:119], v[194:197], v[162:165], v[116:119]
	v_mfma_f32_16x16x32_bf16 v[112:115], v[204:207], v[162:165], v[112:115]
	v_mfma_f32_16x16x32_bf16 v[100:103], v[194:197], v[170:173], v[100:103]
	v_mfma_f32_16x16x32_bf16 v[96:99], v[204:207], v[170:173], v[96:99]
	v_mfma_f32_16x16x32_bf16 v[84:87], v[194:197], v[178:181], v[84:87]
	v_mfma_f32_16x16x32_bf16 v[80:83], v[204:207], v[178:181], v[80:83]
	v_mfma_f32_16x16x32_bf16 v[68:71], v[194:197], v[186:189], v[68:71]
	v_mfma_f32_16x16x32_bf16 v[64:67], v[204:207], v[186:189], v[64:67]
	v_mfma_f32_16x16x32_bf16 v[116:119], v[198:201], v[166:169], v[116:119]
	v_mfma_f32_16x16x32_bf16 v[112:115], v[208:211], v[166:169], v[112:115]
	v_mfma_f32_16x16x32_bf16 v[100:103], v[198:201], v[174:177], v[100:103]
	v_mfma_f32_16x16x32_bf16 v[96:99], v[208:211], v[174:177], v[96:99]
	v_mfma_f32_16x16x32_bf16 v[84:87], v[198:201], v[182:185], v[84:87]
	v_mfma_f32_16x16x32_bf16 v[80:83], v[208:211], v[182:185], v[80:83]
	v_mfma_f32_16x16x32_bf16 v[68:71], v[198:201], v[190:193], v[68:71]
	v_mfma_f32_16x16x32_bf16 v[64:67], v[208:211], v[190:193], v[64:67]
	s_mov_b32 m0, s36
	s_barrier
	ds_read_b128 v[162:165], v144 offset:49152
	ds_read_b128 v[166:169], v144 offset:50176
	ds_read_b128 v[170:173], v144 offset:51200
	ds_read_b128 v[174:177], v144 offset:52224
	ds_read_b128 v[178:181], v144 offset:53248
	ds_read_b128 v[182:185], v144 offset:54272
	ds_read_b128 v[186:189], v144 offset:55296
	ds_read_b128 v[190:193], v144 offset:56320
	s_add_u32 s100, s98, 0x80
	s_addc_u32 s101, s99, 0
	global_load_lds_dwordx4 v134, s[100:101]
	s_mov_b32 m0, s37
	s_nop 0
	s_add_u32 s100, s98, 0x80
	s_addc_u32 s101, s99, 0
	global_load_lds_dwordx4 v130, s[100:101]
	s_barrier
	s_waitcnt lgkmcnt(0)
	v_mfma_f32_16x16x32_bf16 v[60:63], v[146:149], v[162:165], v[60:63]
	v_mfma_f32_16x16x32_bf16 v[56:59], v[154:157], v[162:165], v[56:59]
	v_mfma_f32_16x16x32_bf16 v[44:47], v[146:149], v[170:173], v[44:47]
	v_mfma_f32_16x16x32_bf16 v[40:43], v[154:157], v[170:173], v[40:43]
	v_mfma_f32_16x16x32_bf16 v[28:31], v[146:149], v[178:181], v[28:31]
	v_mfma_f32_16x16x32_bf16 v[24:27], v[154:157], v[178:181], v[24:27]
	v_mfma_f32_16x16x32_bf16 v[12:15], v[146:149], v[186:189], v[12:15]
	v_mfma_f32_16x16x32_bf16 v[8:11], v[154:157], v[186:189], v[8:11]
	v_mfma_f32_16x16x32_bf16 v[60:63], v[150:153], v[166:169], v[60:63]
	v_mfma_f32_16x16x32_bf16 v[56:59], v[158:161], v[166:169], v[56:59]
	v_mfma_f32_16x16x32_bf16 v[44:47], v[150:153], v[174:177], v[44:47]
	v_mfma_f32_16x16x32_bf16 v[40:43], v[158:161], v[174:177], v[40:43]
	v_mfma_f32_16x16x32_bf16 v[28:31], v[150:153], v[182:185], v[28:31]
	v_mfma_f32_16x16x32_bf16 v[24:27], v[158:161], v[182:185], v[24:27]
	v_mfma_f32_16x16x32_bf16 v[12:15], v[150:153], v[190:193], v[12:15]
	v_mfma_f32_16x16x32_bf16 v[8:11], v[158:161], v[190:193], v[8:11]
	s_barrier
	s_add_u32 s20, s20, 0x40080
	s_addc_u32 s21, s21, 0
	s_add_i32 s22, s22, s27
	s_mov_b32 m0, s22
	s_nop 0
	global_load_lds_dwordx4 v132, s[20:21]
	s_add_i32 m0, s22, 0x2000
	s_nop 0
	global_load_lds_dwordx4 v128, s[20:21]
	s_waitcnt vmcnt(6)
	s_barrier
	v_mfma_f32_16x16x32_bf16 v[52:55], v[194:197], v[162:165], v[52:55]
	v_mfma_f32_16x16x32_bf16 v[48:51], v[204:207], v[162:165], v[48:51]
	v_mfma_f32_16x16x32_bf16 v[36:39], v[194:197], v[170:173], v[36:39]
	v_mfma_f32_16x16x32_bf16 v[32:35], v[204:207], v[170:173], v[32:35]
	v_mfma_f32_16x16x32_bf16 v[20:23], v[194:197], v[178:181], v[20:23]
	v_mfma_f32_16x16x32_bf16 v[16:19], v[204:207], v[178:181], v[16:19]
	v_mfma_f32_16x16x32_bf16 v[4:7], v[194:197], v[186:189], v[4:7]
	v_mfma_f32_16x16x32_bf16 v[0:3], v[204:207], v[186:189], v[0:3]
	v_mfma_f32_16x16x32_bf16 v[52:55], v[198:201], v[166:169], v[52:55]
	v_mfma_f32_16x16x32_bf16 v[48:51], v[208:211], v[166:169], v[48:51]
	v_mfma_f32_16x16x32_bf16 v[36:39], v[198:201], v[174:177], v[36:39]
	v_mfma_f32_16x16x32_bf16 v[32:35], v[208:211], v[174:177], v[32:35]
	v_mfma_f32_16x16x32_bf16 v[20:23], v[198:201], v[182:185], v[20:23]
	v_mfma_f32_16x16x32_bf16 v[16:19], v[208:211], v[182:185], v[16:19]
	v_mfma_f32_16x16x32_bf16 v[4:7], v[198:201], v[190:193], v[4:7]
	v_mfma_f32_16x16x32_bf16 v[0:3], v[208:211], v[190:193], v[0:3]
	s_add_u32 s18, s18, 0x100
	s_addc_u32 s19, s19, 0
	s_add_u32 s49, s49, 0x100
	s_addc_u32 s50, s50, 0
	s_cmp_ge_i32 s51, s45
	s_mov_b32 s20, s51
	s_barrier
	s_cbranch_scc0 .LBB0_1409
	s_branch .LBB0_1404

.LBB0_1564:
	ds_read_b128 v[152:155], v149
	ds_read_b128 v[156:159], v149 offset:1024
	ds_read_b128 v[160:163], v149 offset:2048
	ds_read_b128 v[164:167], v149 offset:3072
	s_add_u32 s24, s22, 0xfff80080
	s_addc_u32 s25, s23, -1
	s_cmp_eq_u32 s52, 28
	s_cselect_b32 s27, s15, s25
	s_cselect_b32 s26, s48, s24
	s_cselect_b32 s25, s13, s51
	s_cselect_b32 s24, s49, s50
	s_add_i32 m0, s21, 0xc000
	ds_read_b128 v[168:171], v150
	ds_read_b128 v[172:175], v150 offset:1024
	ds_read_b128 v[176:179], v150 offset:2048
	ds_read_b128 v[180:183], v150 offset:3072
	ds_read_b128 v[184:187], v150 offset:4096
	ds_read_b128 v[188:191], v150 offset:5120
	ds_read_b128 v[192:195], v150 offset:6144
	ds_read_b128 v[196:199], v150 offset:7168
	global_load_lds_dwordx4 v136, s[22:23]
	s_add_i32 m0, s21, 0xe000
	s_nop 0
	global_load_lds_dwordx4 v138, s[22:23]
	s_waitcnt lgkmcnt(8)
	s_barrier
	s_waitcnt lgkmcnt(0)
	v_mfma_f32_16x16x32_bf16 v[124:127], v[152:155], v[168:171], v[124:127]
	v_mfma_f32_16x16x32_bf16 v[120:123], v[160:163], v[168:171], v[120:123]
	v_mfma_f32_16x16x32_bf16 v[108:111], v[152:155], v[176:179], v[108:111]
	v_mfma_f32_16x16x32_bf16 v[104:107], v[160:163], v[176:179], v[104:107]
	v_mfma_f32_16x16x32_bf16 v[92:95], v[152:155], v[184:187], v[92:95]
	v_mfma_f32_16x16x32_bf16 v[88:91], v[160:163], v[184:187], v[88:91]
	v_mfma_f32_16x16x32_bf16 v[76:79], v[152:155], v[192:195], v[76:79]
	v_mfma_f32_16x16x32_bf16 v[72:75], v[160:163], v[192:195], v[72:75]
	v_mfma_f32_16x16x32_bf16 v[124:127], v[156:159], v[172:175], v[124:127]
	v_mfma_f32_16x16x32_bf16 v[120:123], v[164:167], v[172:175], v[120:123]
	v_mfma_f32_16x16x32_bf16 v[108:111], v[156:159], v[180:183], v[108:111]
	v_mfma_f32_16x16x32_bf16 v[104:107], v[164:167], v[180:183], v[104:107]
	v_mfma_f32_16x16x32_bf16 v[92:95], v[156:159], v[188:191], v[92:95]
	v_mfma_f32_16x16x32_bf16 v[88:91], v[164:167], v[188:191], v[88:91]
	v_mfma_f32_16x16x32_bf16 v[76:79], v[156:159], v[196:199], v[76:79]
	v_mfma_f32_16x16x32_bf16 v[72:75], v[164:167], v[196:199], v[72:75]
	s_barrier
	s_add_i32 s53, s41, s31
	s_mov_b32 m0, s53
	ds_read_b128 v[204:207], v151
	ds_read_b128 v[208:211], v151 offset:1024
	ds_read_b128 v[212:215], v151 offset:2048
	ds_read_b128 v[216:219], v151 offset:3072
	global_load_lds_dwordx4 v132, s[24:25]
	s_add_i32 m0, s53, 0x2000
	s_nop 0
	global_load_lds_dwordx4 v128, s[24:25]
	s_barrier
	s_waitcnt lgkmcnt(0)
	v_mfma_f32_16x16x32_bf16 v[116:119], v[204:207], v[168:171], v[116:119]
	v_mfma_f32_16x16x32_bf16 v[112:115], v[212:215], v[168:171], v[112:115]
	v_mfma_f32_16x16x32_bf16 v[100:103], v[204:207], v[176:179], v[100:103]
	v_mfma_f32_16x16x32_bf16 v[96:99], v[212:215], v[176:179], v[96:99]
	v_mfma_f32_16x16x32_bf16 v[84:87], v[204:207], v[184:187], v[84:87]
	v_mfma_f32_16x16x32_bf16 v[80:83], v[212:215], v[184:187], v[80:83]
	v_mfma_f32_16x16x32_bf16 v[68:71], v[204:207], v[192:195], v[68:71]
	v_mfma_f32_16x16x32_bf16 v[64:67], v[212:215], v[192:195], v[64:67]
	v_mfma_f32_16x16x32_bf16 v[116:119], v[208:211], v[172:175], v[116:119]
	v_mfma_f32_16x16x32_bf16 v[112:115], v[216:219], v[172:175], v[112:115]
	v_mfma_f32_16x16x32_bf16 v[100:103], v[208:211], v[180:183], v[100:103]
	v_mfma_f32_16x16x32_bf16 v[96:99], v[216:219], v[180:183], v[96:99]
	v_mfma_f32_16x16x32_bf16 v[84:87], v[208:211], v[188:191], v[84:87]
	v_mfma_f32_16x16x32_bf16 v[80:83], v[216:219], v[188:191], v[80:83]
	v_mfma_f32_16x16x32_bf16 v[68:71], v[208:211], v[196:199], v[68:71]
	v_mfma_f32_16x16x32_bf16 v[64:67], v[216:219], v[196:199], v[64:67]
	s_mov_b32 m0, s21
	s_mov_b64 s[98:99], s[26:27]
	s_barrier
	ds_read_b128 v[168:171], v150 offset:16384
	ds_read_b128 v[172:175], v150 offset:17408
	ds_read_b128 v[176:179], v150 offset:18432
	ds_read_b128 v[180:183], v150 offset:19456
	ds_read_b128 v[184:187], v150 offset:20480
	ds_read_b128 v[188:191], v150 offset:21504
	ds_read_b128 v[192:195], v150 offset:22528
	ds_read_b128 v[196:199], v150 offset:23552
	global_load_lds_dwordx4 v134, s[26:27]
	s_mov_b32 m0, s35
	s_nop 0
	global_load_lds_dwordx4 v130, s[26:27]
	s_barrier
	s_waitcnt lgkmcnt(0)
	v_mfma_f32_16x16x32_bf16 v[60:63], v[152:155], v[168:171], v[60:63]
	v_mfma_f32_16x16x32_bf16 v[56:59], v[160:163], v[168:171], v[56:59]
	v_mfma_f32_16x16x32_bf16 v[44:47], v[152:155], v[176:179], v[44:47]
	v_mfma_f32_16x16x32_bf16 v[40:43], v[160:163], v[176:179], v[40:43]
	v_mfma_f32_16x16x32_bf16 v[28:31], v[152:155], v[184:187], v[28:31]
	v_mfma_f32_16x16x32_bf16 v[24:27], v[160:163], v[184:187], v[24:27]
	v_mfma_f32_16x16x32_bf16 v[12:15], v[152:155], v[192:195], v[12:15]
	v_mfma_f32_16x16x32_bf16 v[8:11], v[160:163], v[192:195], v[8:11]
	v_mfma_f32_16x16x32_bf16 v[60:63], v[156:159], v[172:175], v[60:63]
	v_mfma_f32_16x16x32_bf16 v[56:59], v[164:167], v[172:175], v[56:59]
	v_mfma_f32_16x16x32_bf16 v[44:47], v[156:159], v[180:183], v[44:47]
	v_mfma_f32_16x16x32_bf16 v[40:43], v[164:167], v[180:183], v[40:43]
	v_mfma_f32_16x16x32_bf16 v[28:31], v[156:159], v[188:191], v[28:31]
	v_mfma_f32_16x16x32_bf16 v[24:27], v[164:167], v[188:191], v[24:27]
	v_mfma_f32_16x16x32_bf16 v[12:15], v[156:159], v[196:199], v[12:15]
	v_mfma_f32_16x16x32_bf16 v[8:11], v[164:167], v[196:199], v[8:11]
	s_barrier
	s_add_u32 s54, s24, 0x20000
	s_addc_u32 s55, s25, 0
	s_add_i32 s53, s42, s31
	s_mov_b32 m0, s53
	s_nop 0
	global_load_lds_dwordx4 v132, s[54:55]
	s_add_i32 m0, s53, 0x2000
	s_nop 0
	global_load_lds_dwordx4 v128, s[54:55]
	s_waitcnt vmcnt(6)
	s_barrier
	v_mfma_f32_16x16x32_bf16 v[52:55], v[204:207], v[168:171], v[52:55]
	v_mfma_f32_16x16x32_bf16 v[48:51], v[212:215], v[168:171], v[48:51]
	v_mfma_f32_16x16x32_bf16 v[36:39], v[204:207], v[176:179], v[36:39]
	v_mfma_f32_16x16x32_bf16 v[32:35], v[212:215], v[176:179], v[32:35]
	v_mfma_f32_16x16x32_bf16 v[20:23], v[204:207], v[184:187], v[20:23]
	v_mfma_f32_16x16x32_bf16 v[16:19], v[212:215], v[184:187], v[16:19]
	v_mfma_f32_16x16x32_bf16 v[4:7], v[204:207], v[192:195], v[4:7]
	v_mfma_f32_16x16x32_bf16 v[0:3], v[212:215], v[192:195], v[0:3]
	v_mfma_f32_16x16x32_bf16 v[52:55], v[208:211], v[172:175], v[52:55]
	v_mfma_f32_16x16x32_bf16 v[48:51], v[216:219], v[172:175], v[48:51]
	v_mfma_f32_16x16x32_bf16 v[36:39], v[208:211], v[180:183], v[36:39]
	v_mfma_f32_16x16x32_bf16 v[32:35], v[216:219], v[180:183], v[32:35]
	v_mfma_f32_16x16x32_bf16 v[20:23], v[208:211], v[188:191], v[20:23]
	v_mfma_f32_16x16x32_bf16 v[16:19], v[216:219], v[188:191], v[16:19]
	v_mfma_f32_16x16x32_bf16 v[4:7], v[208:211], v[196:199], v[4:7]
	v_mfma_f32_16x16x32_bf16 v[0:3], v[216:219], v[196:199], v[0:3]
	s_add_i32 s53, 0, 0x18000
	v_add_u32_e32 v164, s53, v147
	s_barrier
	ds_read_b128 v[152:155], v164
	ds_read_b128 v[156:159], v164 offset:1024
	ds_read_b128 v[160:163], v164 offset:2048
	ds_read_b128 v[164:167], v164 offset:3072
	s_add_u32 s26, s26, 0x80000
	s_addc_u32 s27, s27, 0
	s_mov_b32 m0, s36
	ds_read_b128 v[168:171], v150 offset:32768
	ds_read_b128 v[172:175], v150 offset:33792
	ds_read_b128 v[176:179], v150 offset:34816
	ds_read_b128 v[180:183], v150 offset:35840
	ds_read_b128 v[184:187], v150 offset:36864
	ds_read_b128 v[188:191], v150 offset:37888
	ds_read_b128 v[192:195], v150 offset:38912
	ds_read_b128 v[196:199], v150 offset:39936
	global_load_lds_dwordx4 v134, s[26:27]
	s_mov_b32 m0, s37
	s_nop 0
	global_load_lds_dwordx4 v130, s[26:27]
	s_waitcnt lgkmcnt(8)
	s_barrier
	s_waitcnt lgkmcnt(0)
	v_mfma_f32_16x16x32_bf16 v[124:127], v[152:155], v[168:171], v[124:127]
	v_mfma_f32_16x16x32_bf16 v[120:123], v[160:163], v[168:171], v[120:123]
	v_mfma_f32_16x16x32_bf16 v[108:111], v[152:155], v[176:179], v[108:111]
	v_mfma_f32_16x16x32_bf16 v[104:107], v[160:163], v[176:179], v[104:107]
	v_mfma_f32_16x16x32_bf16 v[92:95], v[152:155], v[184:187], v[92:95]
	v_mfma_f32_16x16x32_bf16 v[88:91], v[160:163], v[184:187], v[88:91]
	v_mfma_f32_16x16x32_bf16 v[76:79], v[152:155], v[192:195], v[76:79]
	v_mfma_f32_16x16x32_bf16 v[72:75], v[160:163], v[192:195], v[72:75]
	v_mfma_f32_16x16x32_bf16 v[124:127], v[156:159], v[172:175], v[124:127]
	v_mfma_f32_16x16x32_bf16 v[120:123], v[164:167], v[172:175], v[120:123]
	v_mfma_f32_16x16x32_bf16 v[108:111], v[156:159], v[180:183], v[108:111]
	v_mfma_f32_16x16x32_bf16 v[104:107], v[164:167], v[180:183], v[104:107]
	v_mfma_f32_16x16x32_bf16 v[92:95], v[156:159], v[188:191], v[92:95]
	v_mfma_f32_16x16x32_bf16 v[88:91], v[164:167], v[188:191], v[88:91]
	v_mfma_f32_16x16x32_bf16 v[76:79], v[156:159], v[196:199], v[76:79]
	v_mfma_f32_16x16x32_bf16 v[72:75], v[164:167], v[196:199], v[72:75]
	s_barrier
	s_add_i32 s26, 0, 0x1c000
	s_add_i32 s27, s53, s31
	v_add_u32_e32 v216, s26, v147
	s_mov_b32 m0, s27
	ds_read_b128 v[204:207], v216
	ds_read_b128 v[208:211], v216 offset:1024
	ds_read_b128 v[212:215], v216 offset:2048
	ds_read_b128 v[216:219], v216 offset:3072
	s_add_u32 s100, s24, 0x80
	s_addc_u32 s101, s25, 0
	global_load_lds_dwordx4 v132, s[100:101]
	s_add_i32 m0, s27, 0x2000
	s_nop 0
	s_add_u32 s100, s24, 0x80
	s_addc_u32 s101, s25, 0
	global_load_lds_dwordx4 v128, s[100:101]
	s_barrier
	s_waitcnt lgkmcnt(0)
	v_mfma_f32_16x16x32_bf16 v[116:119], v[204:207], v[168:171], v[116:119]
	v_mfma_f32_16x16x32_bf16 v[112:115], v[212:215], v[168:171], v[112:115]
	v_mfma_f32_16x16x32_bf16 v[100:103], v[204:207], v[176:179], v[100:103]
	v_mfma_f32_16x16x32_bf16 v[96:99], v[212:215], v[176:179], v[96:99]
	v_mfma_f32_16x16x32_bf16 v[84:87], v[204:207], v[184:187], v[84:87]
	v_mfma_f32_16x16x32_bf16 v[80:83], v[212:215], v[184:187], v[80:83]
	v_mfma_f32_16x16x32_bf16 v[68:71], v[204:207], v[192:195], v[68:71]
	v_mfma_f32_16x16x32_bf16 v[64:67], v[212:215], v[192:195], v[64:67]
	v_mfma_f32_16x16x32_bf16 v[116:119], v[208:211], v[172:175], v[116:119]
	v_mfma_f32_16x16x32_bf16 v[112:115], v[216:219], v[172:175], v[112:115]
	v_mfma_f32_16x16x32_bf16 v[100:103], v[208:211], v[180:183], v[100:103]
	v_mfma_f32_16x16x32_bf16 v[96:99], v[216:219], v[180:183], v[96:99]
	v_mfma_f32_16x16x32_bf16 v[84:87], v[208:211], v[188:191], v[84:87]
	v_mfma_f32_16x16x32_bf16 v[80:83], v[216:219], v[188:191], v[80:83]
	v_mfma_f32_16x16x32_bf16 v[68:71], v[208:211], v[196:199], v[68:71]
	v_mfma_f32_16x16x32_bf16 v[64:67], v[216:219], v[196:199], v[64:67]
	s_mov_b32 m0, s39
	s_barrier
	ds_read_b128 v[168:171], v150 offset:49152
	ds_read_b128 v[172:175], v150 offset:50176
	ds_read_b128 v[176:179], v150 offset:51200
	ds_read_b128 v[180:183], v150 offset:52224
	ds_read_b128 v[184:187], v150 offset:53248
	ds_read_b128 v[188:191], v150 offset:54272
	ds_read_b128 v[192:195], v150 offset:55296
	ds_read_b128 v[196:199], v150 offset:56320
	s_add_u32 s100, s98, 0x80
	s_addc_u32 s101, s99, 0
	global_load_lds_dwordx4 v134, s[100:101]
	s_mov_b32 m0, s40
	s_nop 0
	s_add_u32 s100, s98, 0x80
	s_addc_u32 s101, s99, 0
	global_load_lds_dwordx4 v130, s[100:101]
	s_barrier
	s_waitcnt lgkmcnt(0)
	v_mfma_f32_16x16x32_bf16 v[60:63], v[152:155], v[168:171], v[60:63]
	v_mfma_f32_16x16x32_bf16 v[56:59], v[160:163], v[168:171], v[56:59]
	v_mfma_f32_16x16x32_bf16 v[44:47], v[152:155], v[176:179], v[44:47]
	v_mfma_f32_16x16x32_bf16 v[40:43], v[160:163], v[176:179], v[40:43]
	v_mfma_f32_16x16x32_bf16 v[28:31], v[152:155], v[184:187], v[28:31]
	v_mfma_f32_16x16x32_bf16 v[24:27], v[160:163], v[184:187], v[24:27]
	v_mfma_f32_16x16x32_bf16 v[12:15], v[152:155], v[192:195], v[12:15]
	v_mfma_f32_16x16x32_bf16 v[8:11], v[160:163], v[192:195], v[8:11]
	v_mfma_f32_16x16x32_bf16 v[60:63], v[156:159], v[172:175], v[60:63]
	v_mfma_f32_16x16x32_bf16 v[56:59], v[164:167], v[172:175], v[56:59]
	v_mfma_f32_16x16x32_bf16 v[44:47], v[156:159], v[180:183], v[44:47]
	v_mfma_f32_16x16x32_bf16 v[40:43], v[164:167], v[180:183], v[40:43]
	v_mfma_f32_16x16x32_bf16 v[28:31], v[156:159], v[188:191], v[28:31]
	v_mfma_f32_16x16x32_bf16 v[24:27], v[164:167], v[188:191], v[24:27]
	v_mfma_f32_16x16x32_bf16 v[12:15], v[156:159], v[196:199], v[12:15]
	v_mfma_f32_16x16x32_bf16 v[8:11], v[164:167], v[196:199], v[8:11]
	s_barrier
	s_add_u32 s24, s24, 0x20080
	s_addc_u32 s25, s25, 0
	s_add_i32 s26, s26, s31
	s_mov_b32 m0, s26
	s_nop 0
	global_load_lds_dwordx4 v132, s[24:25]
	s_add_i32 m0, s26, 0x2000
	s_nop 0
	global_load_lds_dwordx4 v128, s[24:25]
	s_waitcnt vmcnt(6)
	s_barrier
	v_mfma_f32_16x16x32_bf16 v[52:55], v[204:207], v[168:171], v[52:55]
	v_mfma_f32_16x16x32_bf16 v[48:51], v[212:215], v[168:171], v[48:51]
	v_mfma_f32_16x16x32_bf16 v[36:39], v[204:207], v[176:179], v[36:39]
	v_mfma_f32_16x16x32_bf16 v[32:35], v[212:215], v[176:179], v[32:35]
	v_mfma_f32_16x16x32_bf16 v[20:23], v[204:207], v[184:187], v[20:23]
	v_mfma_f32_16x16x32_bf16 v[16:19], v[212:215], v[184:187], v[16:19]
	v_mfma_f32_16x16x32_bf16 v[4:7], v[204:207], v[192:195], v[4:7]
	v_mfma_f32_16x16x32_bf16 v[0:3], v[212:215], v[192:195], v[0:3]
	v_mfma_f32_16x16x32_bf16 v[52:55], v[208:211], v[172:175], v[52:55]
	v_mfma_f32_16x16x32_bf16 v[48:51], v[216:219], v[172:175], v[48:51]
	v_mfma_f32_16x16x32_bf16 v[36:39], v[208:211], v[180:183], v[36:39]
	v_mfma_f32_16x16x32_bf16 v[32:35], v[216:219], v[180:183], v[32:35]
	v_mfma_f32_16x16x32_bf16 v[20:23], v[208:211], v[188:191], v[20:23]
	v_mfma_f32_16x16x32_bf16 v[16:19], v[216:219], v[188:191], v[16:19]
	v_mfma_f32_16x16x32_bf16 v[4:7], v[208:211], v[196:199], v[4:7]
	v_mfma_f32_16x16x32_bf16 v[0:3], v[216:219], v[196:199], v[0:3]
	s_add_i32 s52, s52, 2
	s_add_u32 s22, s22, 0x100
	s_addc_u32 s23, s23, 0
	s_add_u32 s50, s50, 0x100
	s_addc_u32 s51, s51, 0
	s_cmp_gt_u32 s52, 29
	s_barrier
	s_cbranch_scc0 .LBB0_1564
	v_readlane_b32 s100, v248, 63
	v_readlane_b32 s101, v247, 0
	v_and_b32_e32 v242, 15, v202
	v_bfe_u32 v243, v202, 4, 2
	v_bfe_u32 v244, v202, 6, 2
	v_lshrrev_b32_e32 v245, 8, v202
	v_and_b32_e32 v240, 7, v242
	v_lshl_add_u32 v240, v245, 6, v240
	v_lshl_add_u32 v240, s20, 8, v240
	v_lshlrev_b32_e32 v240, 14, v240
	v_lshrrev_b32_e32 v241, 3, v242
	v_lshlrev_b32_e32 v241, 6, v241
	v_lshl_add_u32 v241, v244, 7, v241
	v_lshl_add_u32 v241, v243, 4, v241
	v_add_u32_e32 v240, v240, v241
	s_lshl_b32 s98, s47, 9
	v_add_u32_e32 v240, s98, v240
	v_max_f32_e32 v124, 0, v124
	v_max_f32_e32 v125, 0, v125
	v_max_f32_e32 v126, 0, v126
	v_max_f32_e32 v127, 0, v127
	v_max_f32_e32 v120, 0, v120
	v_max_f32_e32 v121, 0, v121
	v_max_f32_e32 v122, 0, v122
	v_max_f32_e32 v123, 0, v123
	v_pk_mul_f32 v[124:125], v[124:125], v[124:125]
	v_pk_mul_f32 v[126:127], v[126:127], v[126:127]
	v_pk_mul_f32 v[120:121], v[120:121], v[120:121]
	v_pk_mul_f32 v[122:123], v[122:123], v[122:123]
	v_cvt_pk_bf16_f32 v228, v124, v125
	v_cvt_pk_bf16_f32 v229, v126, v127
	v_cvt_pk_bf16_f32 v230, v120, v121
	v_cvt_pk_bf16_f32 v231, v122, v123
	v_max_f32_e32 v116, 0, v116
	v_max_f32_e32 v117, 0, v117
	v_max_f32_e32 v118, 0, v118
	v_max_f32_e32 v119, 0, v119
	v_max_f32_e32 v112, 0, v112
	v_max_f32_e32 v113, 0, v113
	v_max_f32_e32 v114, 0, v114
	v_max_f32_e32 v115, 0, v115
	v_pk_mul_f32 v[116:117], v[116:117], v[116:117]
	v_pk_mul_f32 v[118:119], v[118:119], v[118:119]
	v_pk_mul_f32 v[112:113], v[112:113], v[112:113]
	v_pk_mul_f32 v[114:115], v[114:115], v[114:115]
	v_cvt_pk_bf16_f32 v232, v116, v117
	v_cvt_pk_bf16_f32 v233, v118, v119
	v_cvt_pk_bf16_f32 v234, v112, v113
	v_cvt_pk_bf16_f32 v235, v114, v115
	v_mov_b32_e32 v236, v228
	v_mov_b32_e32 v237, v229
	v_mov_b32_e32 v238, v230
	v_mov_b32_e32 v239, v231
	v_mov_b32_dpp v228, v232 row_ror:8 row_mask:0xf bank_mask:0xc
	v_mov_b32_dpp v229, v233 row_ror:8 row_mask:0xf bank_mask:0xc
	v_mov_b32_dpp v230, v234 row_ror:8 row_mask:0xf bank_mask:0xc
	v_mov_b32_dpp v231, v235 row_ror:8 row_mask:0xf bank_mask:0xc
	v_mov_b32_dpp v232, v236 row_ror:8 row_mask:0xf bank_mask:0x3
	v_mov_b32_dpp v233, v237 row_ror:8 row_mask:0xf bank_mask:0x3
	v_mov_b32_dpp v234, v238 row_ror:8 row_mask:0xf bank_mask:0x3
	v_mov_b32_dpp v235, v239 row_ror:8 row_mask:0xf bank_mask:0x3
	global_store_dwordx4 v240, v[228:231], s[100:101]
	s_add_u32 s100, s100, 0x20000
	s_addc_u32 s101, s101, 0
	global_store_dwordx4 v240, v[232:235], s[100:101]
	v_max_f32_e32 v108, 0, v108
	v_max_f32_e32 v109, 0, v109
	v_max_f32_e32 v110, 0, v110
	v_max_f32_e32 v111, 0, v111
	v_max_f32_e32 v104, 0, v104
	v_max_f32_e32 v105, 0, v105
	v_max_f32_e32 v106, 0, v106
	v_max_f32_e32 v107, 0, v107
	v_pk_mul_f32 v[108:109], v[108:109], v[108:109]
	v_pk_mul_f32 v[110:111], v[110:111], v[110:111]
	v_pk_mul_f32 v[104:105], v[104:105], v[104:105]
	v_pk_mul_f32 v[106:107], v[106:107], v[106:107]
	v_cvt_pk_bf16_f32 v228, v108, v109
	v_cvt_pk_bf16_f32 v229, v110, v111
	v_cvt_pk_bf16_f32 v230, v104, v105
	v_cvt_pk_bf16_f32 v231, v106, v107
	v_max_f32_e32 v100, 0, v100
	v_max_f32_e32 v101, 0, v101
	v_max_f32_e32 v102, 0, v102
	v_max_f32_e32 v103, 0, v103
	v_max_f32_e32 v96, 0, v96
	v_max_f32_e32 v97, 0, v97
	v_max_f32_e32 v98, 0, v98
	v_max_f32_e32 v99, 0, v99
	v_pk_mul_f32 v[100:101], v[100:101], v[100:101]
	v_pk_mul_f32 v[102:103], v[102:103], v[102:103]
	v_pk_mul_f32 v[96:97], v[96:97], v[96:97]
	v_pk_mul_f32 v[98:99], v[98:99], v[98:99]
	v_cvt_pk_bf16_f32 v232, v100, v101
	v_cvt_pk_bf16_f32 v233, v102, v103
	v_cvt_pk_bf16_f32 v234, v96, v97
	v_cvt_pk_bf16_f32 v235, v98, v99
	v_mov_b32_e32 v236, v228
	v_mov_b32_e32 v237, v229
	v_mov_b32_e32 v238, v230
	v_mov_b32_e32 v239, v231
	v_mov_b32_dpp v228, v232 row_ror:8 row_mask:0xf bank_mask:0xc
	v_mov_b32_dpp v229, v233 row_ror:8 row_mask:0xf bank_mask:0xc
	v_mov_b32_dpp v230, v234 row_ror:8 row_mask:0xf bank_mask:0xc
	v_mov_b32_dpp v231, v235 row_ror:8 row_mask:0xf bank_mask:0xc
	v_mov_b32_dpp v232, v236 row_ror:8 row_mask:0xf bank_mask:0x3
	v_mov_b32_dpp v233, v237 row_ror:8 row_mask:0xf bank_mask:0x3
	v_mov_b32_dpp v234, v238 row_ror:8 row_mask:0xf bank_mask:0x3
	v_mov_b32_dpp v235, v239 row_ror:8 row_mask:0xf bank_mask:0x3
	s_add_u32 s100, s100, 0x20000
	s_addc_u32 s101, s101, 0
	global_store_dwordx4 v240, v[228:231], s[100:101]
	s_add_u32 s100, s100, 0x20000
	s_addc_u32 s101, s101, 0
	global_store_dwordx4 v240, v[232:235], s[100:101]
	v_max_f32_e32 v92, 0, v92
	v_max_f32_e32 v93, 0, v93
	v_max_f32_e32 v94, 0, v94
	v_max_f32_e32 v95, 0, v95
	v_max_f32_e32 v88, 0, v88
	v_max_f32_e32 v89, 0, v89
	v_max_f32_e32 v90, 0, v90
	v_max_f32_e32 v91, 0, v91
	v_pk_mul_f32 v[92:93], v[92:93], v[92:93]
	v_pk_mul_f32 v[94:95], v[94:95], v[94:95]
	v_pk_mul_f32 v[88:89], v[88:89], v[88:89]
	v_pk_mul_f32 v[90:91], v[90:91], v[90:91]
	v_cvt_pk_bf16_f32 v228, v92, v93
	v_cvt_pk_bf16_f32 v229, v94, v95
	v_cvt_pk_bf16_f32 v230, v88, v89
	v_cvt_pk_bf16_f32 v231, v90, v91
	v_max_f32_e32 v84, 0, v84
	v_max_f32_e32 v85, 0, v85
	v_max_f32_e32 v86, 0, v86
	v_max_f32_e32 v87, 0, v87
	v_max_f32_e32 v80, 0, v80
	v_max_f32_e32 v81, 0, v81
	v_max_f32_e32 v82, 0, v82
	v_max_f32_e32 v83, 0, v83
	v_pk_mul_f32 v[84:85], v[84:85], v[84:85]
	v_pk_mul_f32 v[86:87], v[86:87], v[86:87]
	v_pk_mul_f32 v[80:81], v[80:81], v[80:81]
	v_pk_mul_f32 v[82:83], v[82:83], v[82:83]
	v_cvt_pk_bf16_f32 v232, v84, v85
	v_cvt_pk_bf16_f32 v233, v86, v87
	v_cvt_pk_bf16_f32 v234, v80, v81
	v_cvt_pk_bf16_f32 v235, v82, v83
	v_mov_b32_e32 v236, v228
	v_mov_b32_e32 v237, v229
	v_mov_b32_e32 v238, v230
	v_mov_b32_e32 v239, v231
	v_mov_b32_dpp v228, v232 row_ror:8 row_mask:0xf bank_mask:0xc
	v_mov_b32_dpp v229, v233 row_ror:8 row_mask:0xf bank_mask:0xc
	v_mov_b32_dpp v230, v234 row_ror:8 row_mask:0xf bank_mask:0xc
	v_mov_b32_dpp v231, v235 row_ror:8 row_mask:0xf bank_mask:0xc
	v_mov_b32_dpp v232, v236 row_ror:8 row_mask:0xf bank_mask:0x3
	v_mov_b32_dpp v233, v237 row_ror:8 row_mask:0xf bank_mask:0x3
	v_mov_b32_dpp v234, v238 row_ror:8 row_mask:0xf bank_mask:0x3
	v_mov_b32_dpp v235, v239 row_ror:8 row_mask:0xf bank_mask:0x3
	s_add_u32 s100, s100, 0x20000
	s_addc_u32 s101, s101, 0
	global_store_dwordx4 v240, v[228:231], s[100:101]
	s_add_u32 s100, s100, 0x20000
	s_addc_u32 s101, s101, 0
	global_store_dwordx4 v240, v[232:235], s[100:101]
	v_max_f32_e32 v76, 0, v76
	v_max_f32_e32 v77, 0, v77
	v_max_f32_e32 v78, 0, v78
	v_max_f32_e32 v79, 0, v79
	v_max_f32_e32 v72, 0, v72
	v_max_f32_e32 v73, 0, v73
	v_max_f32_e32 v74, 0, v74
	v_max_f32_e32 v75, 0, v75
	v_pk_mul_f32 v[76:77], v[76:77], v[76:77]
	v_pk_mul_f32 v[78:79], v[78:79], v[78:79]
	v_pk_mul_f32 v[72:73], v[72:73], v[72:73]
	v_pk_mul_f32 v[74:75], v[74:75], v[74:75]
	v_cvt_pk_bf16_f32 v228, v76, v77
	v_cvt_pk_bf16_f32 v229, v78, v79
	v_cvt_pk_bf16_f32 v230, v72, v73
	v_cvt_pk_bf16_f32 v231, v74, v75
	v_max_f32_e32 v68, 0, v68
	v_max_f32_e32 v69, 0, v69
	v_max_f32_e32 v70, 0, v70
	v_max_f32_e32 v71, 0, v71
	v_max_f32_e32 v64, 0, v64
	v_max_f32_e32 v65, 0, v65
	v_max_f32_e32 v66, 0, v66
	v_max_f32_e32 v67, 0, v67
	v_pk_mul_f32 v[68:69], v[68:69], v[68:69]
	v_pk_mul_f32 v[70:71], v[70:71], v[70:71]
	v_pk_mul_f32 v[64:65], v[64:65], v[64:65]
	v_pk_mul_f32 v[66:67], v[66:67], v[66:67]
	v_cvt_pk_bf16_f32 v232, v68, v69
	v_cvt_pk_bf16_f32 v233, v70, v71
	v_cvt_pk_bf16_f32 v234, v64, v65
	v_cvt_pk_bf16_f32 v235, v66, v67
	v_mov_b32_e32 v236, v228
	v_mov_b32_e32 v237, v229
	v_mov_b32_e32 v238, v230
	v_mov_b32_e32 v239, v231
	v_mov_b32_dpp v228, v232 row_ror:8 row_mask:0xf bank_mask:0xc
	v_mov_b32_dpp v229, v233 row_ror:8 row_mask:0xf bank_mask:0xc
	v_mov_b32_dpp v230, v234 row_ror:8 row_mask:0xf bank_mask:0xc
	v_mov_b32_dpp v231, v235 row_ror:8 row_mask:0xf bank_mask:0xc
	v_mov_b32_dpp v232, v236 row_ror:8 row_mask:0xf bank_mask:0x3
	v_mov_b32_dpp v233, v237 row_ror:8 row_mask:0xf bank_mask:0x3
	v_mov_b32_dpp v234, v238 row_ror:8 row_mask:0xf bank_mask:0x3
	v_mov_b32_dpp v235, v239 row_ror:8 row_mask:0xf bank_mask:0x3
	s_add_u32 s100, s100, 0x20000
	s_addc_u32 s101, s101, 0
	global_store_dwordx4 v240, v[228:231], s[100:101]
	s_add_u32 s100, s100, 0x20000
	s_addc_u32 s101, s101, 0
	global_store_dwordx4 v240, v[232:235], s[100:101]
	v_max_f32_e32 v60, 0, v60
	v_max_f32_e32 v61, 0, v61
	v_max_f32_e32 v62, 0, v62
	v_max_f32_e32 v63, 0, v63
	v_max_f32_e32 v56, 0, v56
	v_max_f32_e32 v57, 0, v57
	v_max_f32_e32 v58, 0, v58
	v_max_f32_e32 v59, 0, v59
	v_pk_mul_f32 v[60:61], v[60:61], v[60:61]
	v_pk_mul_f32 v[62:63], v[62:63], v[62:63]
	v_pk_mul_f32 v[56:57], v[56:57], v[56:57]
	v_pk_mul_f32 v[58:59], v[58:59], v[58:59]
	v_cvt_pk_bf16_f32 v228, v60, v61
	v_cvt_pk_bf16_f32 v229, v62, v63
	v_cvt_pk_bf16_f32 v230, v56, v57
	v_cvt_pk_bf16_f32 v231, v58, v59
	v_max_f32_e32 v52, 0, v52
	v_max_f32_e32 v53, 0, v53
	v_max_f32_e32 v54, 0, v54
	v_max_f32_e32 v55, 0, v55
	v_max_f32_e32 v48, 0, v48
	v_max_f32_e32 v49, 0, v49
	v_max_f32_e32 v50, 0, v50
	v_max_f32_e32 v51, 0, v51
	v_pk_mul_f32 v[52:53], v[52:53], v[52:53]
	v_pk_mul_f32 v[54:55], v[54:55], v[54:55]
	v_pk_mul_f32 v[48:49], v[48:49], v[48:49]
	v_pk_mul_f32 v[50:51], v[50:51], v[50:51]
	v_cvt_pk_bf16_f32 v232, v52, v53
	v_cvt_pk_bf16_f32 v233, v54, v55
	v_cvt_pk_bf16_f32 v234, v48, v49
	v_cvt_pk_bf16_f32 v235, v50, v51
	v_mov_b32_e32 v236, v228
	v_mov_b32_e32 v237, v229
	v_mov_b32_e32 v238, v230
	v_mov_b32_e32 v239, v231
	v_mov_b32_dpp v228, v232 row_ror:8 row_mask:0xf bank_mask:0xc
	v_mov_b32_dpp v229, v233 row_ror:8 row_mask:0xf bank_mask:0xc
	v_mov_b32_dpp v230, v234 row_ror:8 row_mask:0xf bank_mask:0xc
	v_mov_b32_dpp v231, v235 row_ror:8 row_mask:0xf bank_mask:0xc
	v_mov_b32_dpp v232, v236 row_ror:8 row_mask:0xf bank_mask:0x3
	v_mov_b32_dpp v233, v237 row_ror:8 row_mask:0xf bank_mask:0x3
	v_mov_b32_dpp v234, v238 row_ror:8 row_mask:0xf bank_mask:0x3
	v_mov_b32_dpp v235, v239 row_ror:8 row_mask:0xf bank_mask:0x3
	s_add_u32 s100, s100, 0x120000
	s_addc_u32 s101, s101, 0
	global_store_dwordx4 v240, v[228:231], s[100:101]
	s_add_u32 s100, s100, 0x20000
	s_addc_u32 s101, s101, 0
	global_store_dwordx4 v240, v[232:235], s[100:101]
	v_max_f32_e32 v44, 0, v44
	v_max_f32_e32 v45, 0, v45
	v_max_f32_e32 v46, 0, v46
	v_max_f32_e32 v47, 0, v47
	v_max_f32_e32 v40, 0, v40
	v_max_f32_e32 v41, 0, v41
	v_max_f32_e32 v42, 0, v42
	v_max_f32_e32 v43, 0, v43
	v_pk_mul_f32 v[44:45], v[44:45], v[44:45]
	v_pk_mul_f32 v[46:47], v[46:47], v[46:47]
	v_pk_mul_f32 v[40:41], v[40:41], v[40:41]
	v_pk_mul_f32 v[42:43], v[42:43], v[42:43]
	v_cvt_pk_bf16_f32 v228, v44, v45
	v_cvt_pk_bf16_f32 v229, v46, v47
	v_cvt_pk_bf16_f32 v230, v40, v41
	v_cvt_pk_bf16_f32 v231, v42, v43
	v_max_f32_e32 v36, 0, v36
	v_max_f32_e32 v37, 0, v37
	v_max_f32_e32 v38, 0, v38
	v_max_f32_e32 v39, 0, v39
	v_max_f32_e32 v32, 0, v32
	v_max_f32_e32 v33, 0, v33
	v_max_f32_e32 v34, 0, v34
	v_max_f32_e32 v35, 0, v35
	v_pk_mul_f32 v[36:37], v[36:37], v[36:37]
	v_pk_mul_f32 v[38:39], v[38:39], v[38:39]
	v_pk_mul_f32 v[32:33], v[32:33], v[32:33]
	v_pk_mul_f32 v[34:35], v[34:35], v[34:35]
	v_cvt_pk_bf16_f32 v232, v36, v37
	v_cvt_pk_bf16_f32 v233, v38, v39
	v_cvt_pk_bf16_f32 v234, v32, v33
	v_cvt_pk_bf16_f32 v235, v34, v35
	v_mov_b32_e32 v236, v228
	v_mov_b32_e32 v237, v229
	v_mov_b32_e32 v238, v230
	v_mov_b32_e32 v239, v231
	v_mov_b32_dpp v228, v232 row_ror:8 row_mask:0xf bank_mask:0xc
	v_mov_b32_dpp v229, v233 row_ror:8 row_mask:0xf bank_mask:0xc
	v_mov_b32_dpp v230, v234 row_ror:8 row_mask:0xf bank_mask:0xc
	v_mov_b32_dpp v231, v235 row_ror:8 row_mask:0xf bank_mask:0xc
	v_mov_b32_dpp v232, v236 row_ror:8 row_mask:0xf bank_mask:0x3
	v_mov_b32_dpp v233, v237 row_ror:8 row_mask:0xf bank_mask:0x3
	v_mov_b32_dpp v234, v238 row_ror:8 row_mask:0xf bank_mask:0x3
	v_mov_b32_dpp v235, v239 row_ror:8 row_mask:0xf bank_mask:0x3
	s_add_u32 s100, s100, 0x20000
	s_addc_u32 s101, s101, 0
	global_store_dwordx4 v240, v[228:231], s[100:101]
	s_add_u32 s100, s100, 0x20000
	s_addc_u32 s101, s101, 0
	global_store_dwordx4 v240, v[232:235], s[100:101]
	v_max_f32_e32 v28, 0, v28
	v_max_f32_e32 v29, 0, v29
	v_max_f32_e32 v30, 0, v30
	v_max_f32_e32 v31, 0, v31
	v_max_f32_e32 v24, 0, v24
	v_max_f32_e32 v25, 0, v25
	v_max_f32_e32 v26, 0, v26
	v_max_f32_e32 v27, 0, v27
	v_pk_mul_f32 v[28:29], v[28:29], v[28:29]
	v_pk_mul_f32 v[30:31], v[30:31], v[30:31]
	v_pk_mul_f32 v[24:25], v[24:25], v[24:25]
	v_pk_mul_f32 v[26:27], v[26:27], v[26:27]
	v_cvt_pk_bf16_f32 v228, v28, v29
	v_cvt_pk_bf16_f32 v229, v30, v31
	v_cvt_pk_bf16_f32 v230, v24, v25
	v_cvt_pk_bf16_f32 v231, v26, v27
	v_max_f32_e32 v20, 0, v20
	v_max_f32_e32 v21, 0, v21
	v_max_f32_e32 v22, 0, v22
	v_max_f32_e32 v23, 0, v23
	v_max_f32_e32 v16, 0, v16
	v_max_f32_e32 v17, 0, v17
	v_max_f32_e32 v18, 0, v18
	v_max_f32_e32 v19, 0, v19
	v_pk_mul_f32 v[20:21], v[20:21], v[20:21]
	v_pk_mul_f32 v[22:23], v[22:23], v[22:23]
	v_pk_mul_f32 v[16:17], v[16:17], v[16:17]
	v_pk_mul_f32 v[18:19], v[18:19], v[18:19]
	v_cvt_pk_bf16_f32 v232, v20, v21
	v_cvt_pk_bf16_f32 v233, v22, v23
	v_cvt_pk_bf16_f32 v234, v16, v17
	v_cvt_pk_bf16_f32 v235, v18, v19
	v_mov_b32_e32 v236, v228
	v_mov_b32_e32 v237, v229
	v_mov_b32_e32 v238, v230
	v_mov_b32_e32 v239, v231
	v_mov_b32_dpp v228, v232 row_ror:8 row_mask:0xf bank_mask:0xc
	v_mov_b32_dpp v229, v233 row_ror:8 row_mask:0xf bank_mask:0xc
	v_mov_b32_dpp v230, v234 row_ror:8 row_mask:0xf bank_mask:0xc
	v_mov_b32_dpp v231, v235 row_ror:8 row_mask:0xf bank_mask:0xc
	v_mov_b32_dpp v232, v236 row_ror:8 row_mask:0xf bank_mask:0x3
	v_mov_b32_dpp v233, v237 row_ror:8 row_mask:0xf bank_mask:0x3
	v_mov_b32_dpp v234, v238 row_ror:8 row_mask:0xf bank_mask:0x3
	v_mov_b32_dpp v235, v239 row_ror:8 row_mask:0xf bank_mask:0x3
	s_add_u32 s100, s100, 0x20000
	s_addc_u32 s101, s101, 0
	global_store_dwordx4 v240, v[228:231], s[100:101]
	s_add_u32 s100, s100, 0x20000
	s_addc_u32 s101, s101, 0
	global_store_dwordx4 v240, v[232:235], s[100:101]
	v_max_f32_e32 v12, 0, v12
	v_max_f32_e32 v13, 0, v13
	v_max_f32_e32 v14, 0, v14
	v_max_f32_e32 v15, 0, v15
	v_max_f32_e32 v8, 0, v8
	v_max_f32_e32 v9, 0, v9
	v_max_f32_e32 v10, 0, v10
	v_max_f32_e32 v11, 0, v11
	v_pk_mul_f32 v[12:13], v[12:13], v[12:13]
	v_pk_mul_f32 v[14:15], v[14:15], v[14:15]
	v_pk_mul_f32 v[8:9], v[8:9], v[8:9]
	v_pk_mul_f32 v[10:11], v[10:11], v[10:11]
	v_cvt_pk_bf16_f32 v228, v12, v13
	v_cvt_pk_bf16_f32 v229, v14, v15
	v_cvt_pk_bf16_f32 v230, v8, v9
	v_cvt_pk_bf16_f32 v231, v10, v11
	v_max_f32_e32 v4, 0, v4
	v_max_f32_e32 v5, 0, v5
	v_max_f32_e32 v6, 0, v6
	v_max_f32_e32 v7, 0, v7
	v_max_f32_e32 v0, 0, v0
	v_max_f32_e32 v1, 0, v1
	v_max_f32_e32 v2, 0, v2
	v_max_f32_e32 v3, 0, v3
	v_pk_mul_f32 v[4:5], v[4:5], v[4:5]
	v_pk_mul_f32 v[6:7], v[6:7], v[6:7]
	v_pk_mul_f32 v[0:1], v[0:1], v[0:1]
	v_pk_mul_f32 v[2:3], v[2:3], v[2:3]
	v_cvt_pk_bf16_f32 v232, v4, v5
	v_cvt_pk_bf16_f32 v233, v6, v7
	v_cvt_pk_bf16_f32 v234, v0, v1
	v_cvt_pk_bf16_f32 v235, v2, v3
	v_mov_b32_e32 v236, v228
	v_mov_b32_e32 v237, v229
	v_mov_b32_e32 v238, v230
	v_mov_b32_e32 v239, v231
	v_mov_b32_dpp v228, v232 row_ror:8 row_mask:0xf bank_mask:0xc
	v_mov_b32_dpp v229, v233 row_ror:8 row_mask:0xf bank_mask:0xc
	v_mov_b32_dpp v230, v234 row_ror:8 row_mask:0xf bank_mask:0xc
	v_mov_b32_dpp v231, v235 row_ror:8 row_mask:0xf bank_mask:0xc
	v_mov_b32_dpp v232, v236 row_ror:8 row_mask:0xf bank_mask:0x3
	v_mov_b32_dpp v233, v237 row_ror:8 row_mask:0xf bank_mask:0x3
	v_mov_b32_dpp v234, v238 row_ror:8 row_mask:0xf bank_mask:0x3
	v_mov_b32_dpp v235, v239 row_ror:8 row_mask:0xf bank_mask:0x3
	s_add_u32 s100, s100, 0x20000
	s_addc_u32 s101, s101, 0
	global_store_dwordx4 v240, v[228:231], s[100:101]
	s_add_u32 s100, s100, 0x20000
	s_addc_u32 s101, s101, 0
	global_store_dwordx4 v240, v[232:235], s[100:101]
	s_and_b64 vcc, exec, s[2:3]
	s_mov_b32 s47, s12
	s_mov_b32 s20, s14
	s_mov_b64 s[24:25], s[18:19]
	s_mov_b64 s[22:23], s[16:17]
	s_cbranch_vccz .LBB0_1561
	s_waitcnt vmcnt(0)
	s_cmpk_gt_u32 s28, 0xff
	s_cbranch_scc1 .LBB0_1568
	s_barrier

.LBB0_1631:
	ds_read_b128 v[146:149], v143
	ds_read_b128 v[150:153], v143 offset:1024
	ds_read_b128 v[154:157], v143 offset:2048
	ds_read_b128 v[158:161], v143 offset:3072
	s_add_i32 s51, s22, 2
	s_add_u32 s23, s20, 0xffe00080
	s_addc_u32 s24, s21, -1
	s_cmp_eq_u32 s48, s22
	s_cselect_b32 s22, s47, s49
	s_cselect_b32 s25, s11, s24
	s_cselect_b32 s24, s13, s23
	s_cselect_b32 s23, s46, s50
	s_add_i32 m0, s30, 0xc000
	ds_read_b128 v[162:165], v144
	ds_read_b128 v[166:169], v144 offset:1024
	ds_read_b128 v[170:173], v144 offset:2048
	ds_read_b128 v[174:177], v144 offset:3072
	ds_read_b128 v[178:181], v144 offset:4096
	ds_read_b128 v[182:185], v144 offset:5120
	ds_read_b128 v[186:189], v144 offset:6144
	ds_read_b128 v[190:193], v144 offset:7168
	global_load_lds_dwordx4 v136, s[20:21]
	s_add_i32 m0, s30, 0xe000
	s_nop 0
	global_load_lds_dwordx4 v138, s[20:21]
	s_waitcnt lgkmcnt(8)
	s_barrier
	s_waitcnt lgkmcnt(0)
	v_mfma_f32_16x16x32_bf16 v[124:127], v[146:149], v[162:165], v[124:127]
	v_mfma_f32_16x16x32_bf16 v[120:123], v[154:157], v[162:165], v[120:123]
	v_mfma_f32_16x16x32_bf16 v[108:111], v[146:149], v[170:173], v[108:111]
	v_mfma_f32_16x16x32_bf16 v[104:107], v[154:157], v[170:173], v[104:107]
	v_mfma_f32_16x16x32_bf16 v[92:95], v[146:149], v[178:181], v[92:95]
	v_mfma_f32_16x16x32_bf16 v[88:91], v[154:157], v[178:181], v[88:91]
	v_mfma_f32_16x16x32_bf16 v[76:79], v[146:149], v[186:189], v[76:79]
	v_mfma_f32_16x16x32_bf16 v[72:75], v[154:157], v[186:189], v[72:75]
	v_mfma_f32_16x16x32_bf16 v[124:127], v[150:153], v[166:169], v[124:127]
	v_mfma_f32_16x16x32_bf16 v[120:123], v[158:161], v[166:169], v[120:123]
	v_mfma_f32_16x16x32_bf16 v[108:111], v[150:153], v[174:177], v[108:111]
	v_mfma_f32_16x16x32_bf16 v[104:107], v[158:161], v[174:177], v[104:107]
	v_mfma_f32_16x16x32_bf16 v[92:95], v[150:153], v[182:185], v[92:95]
	v_mfma_f32_16x16x32_bf16 v[88:91], v[158:161], v[182:185], v[88:91]
	v_mfma_f32_16x16x32_bf16 v[76:79], v[150:153], v[190:193], v[76:79]
	v_mfma_f32_16x16x32_bf16 v[72:75], v[158:161], v[190:193], v[72:75]
	s_barrier
	s_add_i32 s52, s39, s29
	s_mov_b32 m0, s52
	ds_read_b128 v[194:197], v145
	ds_read_b128 v[198:201], v145 offset:1024
	ds_read_b128 v[204:207], v145 offset:2048
	ds_read_b128 v[208:211], v145 offset:3072
	global_load_lds_dwordx4 v132, s[22:23]
	s_add_i32 m0, s52, 0x2000
	s_nop 0
	global_load_lds_dwordx4 v128, s[22:23]
	s_barrier
	s_waitcnt lgkmcnt(0)
	v_mfma_f32_16x16x32_bf16 v[116:119], v[194:197], v[162:165], v[116:119]
	v_mfma_f32_16x16x32_bf16 v[112:115], v[204:207], v[162:165], v[112:115]
	v_mfma_f32_16x16x32_bf16 v[100:103], v[194:197], v[170:173], v[100:103]
	v_mfma_f32_16x16x32_bf16 v[96:99], v[204:207], v[170:173], v[96:99]
	v_mfma_f32_16x16x32_bf16 v[84:87], v[194:197], v[178:181], v[84:87]
	v_mfma_f32_16x16x32_bf16 v[80:83], v[204:207], v[178:181], v[80:83]
	v_mfma_f32_16x16x32_bf16 v[68:71], v[194:197], v[186:189], v[68:71]
	v_mfma_f32_16x16x32_bf16 v[64:67], v[204:207], v[186:189], v[64:67]
	v_mfma_f32_16x16x32_bf16 v[116:119], v[198:201], v[166:169], v[116:119]
	v_mfma_f32_16x16x32_bf16 v[112:115], v[208:211], v[166:169], v[112:115]
	v_mfma_f32_16x16x32_bf16 v[100:103], v[198:201], v[174:177], v[100:103]
	v_mfma_f32_16x16x32_bf16 v[96:99], v[208:211], v[174:177], v[96:99]
	v_mfma_f32_16x16x32_bf16 v[84:87], v[198:201], v[182:185], v[84:87]
	v_mfma_f32_16x16x32_bf16 v[80:83], v[208:211], v[182:185], v[80:83]
	v_mfma_f32_16x16x32_bf16 v[68:71], v[198:201], v[190:193], v[68:71]
	v_mfma_f32_16x16x32_bf16 v[64:67], v[208:211], v[190:193], v[64:67]
	s_mov_b32 m0, s30
	s_mov_b64 s[98:99], s[24:25]
	s_barrier
	ds_read_b128 v[162:165], v144 offset:16384
	ds_read_b128 v[166:169], v144 offset:17408
	ds_read_b128 v[170:173], v144 offset:18432
	ds_read_b128 v[174:177], v144 offset:19456
	ds_read_b128 v[178:181], v144 offset:20480
	ds_read_b128 v[182:185], v144 offset:21504
	ds_read_b128 v[186:189], v144 offset:22528
	ds_read_b128 v[190:193], v144 offset:23552
	global_load_lds_dwordx4 v134, s[24:25]
	s_mov_b32 m0, s31
	s_nop 0
	global_load_lds_dwordx4 v130, s[24:25]
	s_barrier
	s_waitcnt lgkmcnt(0)
	v_mfma_f32_16x16x32_bf16 v[60:63], v[146:149], v[162:165], v[60:63]
	v_mfma_f32_16x16x32_bf16 v[56:59], v[154:157], v[162:165], v[56:59]
	v_mfma_f32_16x16x32_bf16 v[44:47], v[146:149], v[170:173], v[44:47]
	v_mfma_f32_16x16x32_bf16 v[40:43], v[154:157], v[170:173], v[40:43]
	v_mfma_f32_16x16x32_bf16 v[28:31], v[146:149], v[178:181], v[28:31]
	v_mfma_f32_16x16x32_bf16 v[24:27], v[154:157], v[178:181], v[24:27]
	v_mfma_f32_16x16x32_bf16 v[12:15], v[146:149], v[186:189], v[12:15]
	v_mfma_f32_16x16x32_bf16 v[8:11], v[154:157], v[186:189], v[8:11]
	v_mfma_f32_16x16x32_bf16 v[60:63], v[150:153], v[166:169], v[60:63]
	v_mfma_f32_16x16x32_bf16 v[56:59], v[158:161], v[166:169], v[56:59]
	v_mfma_f32_16x16x32_bf16 v[44:47], v[150:153], v[174:177], v[44:47]
	v_mfma_f32_16x16x32_bf16 v[40:43], v[158:161], v[174:177], v[40:43]
	v_mfma_f32_16x16x32_bf16 v[28:31], v[150:153], v[182:185], v[28:31]
	v_mfma_f32_16x16x32_bf16 v[24:27], v[158:161], v[182:185], v[24:27]
	v_mfma_f32_16x16x32_bf16 v[12:15], v[150:153], v[190:193], v[12:15]
	v_mfma_f32_16x16x32_bf16 v[8:11], v[158:161], v[190:193], v[8:11]
	s_barrier
	s_add_u32 s52, s22, 0x80000
	s_addc_u32 s53, s23, 0
	s_add_i32 s54, s40, s29
	s_mov_b32 m0, s54
	s_nop 0
	global_load_lds_dwordx4 v132, s[52:53]
	s_add_i32 m0, s54, 0x2000
	s_nop 0
	global_load_lds_dwordx4 v128, s[52:53]
	s_waitcnt vmcnt(6)
	s_barrier
	v_mfma_f32_16x16x32_bf16 v[52:55], v[194:197], v[162:165], v[52:55]
	v_mfma_f32_16x16x32_bf16 v[48:51], v[204:207], v[162:165], v[48:51]
	v_mfma_f32_16x16x32_bf16 v[36:39], v[194:197], v[170:173], v[36:39]
	v_mfma_f32_16x16x32_bf16 v[32:35], v[204:207], v[170:173], v[32:35]
	v_mfma_f32_16x16x32_bf16 v[20:23], v[194:197], v[178:181], v[20:23]
	v_mfma_f32_16x16x32_bf16 v[16:19], v[204:207], v[178:181], v[16:19]
	v_mfma_f32_16x16x32_bf16 v[4:7], v[194:197], v[186:189], v[4:7]
	v_mfma_f32_16x16x32_bf16 v[0:3], v[204:207], v[186:189], v[0:3]
	v_mfma_f32_16x16x32_bf16 v[52:55], v[198:201], v[166:169], v[52:55]
	v_mfma_f32_16x16x32_bf16 v[48:51], v[208:211], v[166:169], v[48:51]
	v_mfma_f32_16x16x32_bf16 v[36:39], v[198:201], v[174:177], v[36:39]
	v_mfma_f32_16x16x32_bf16 v[32:35], v[208:211], v[174:177], v[32:35]
	v_mfma_f32_16x16x32_bf16 v[20:23], v[198:201], v[182:185], v[20:23]
	v_mfma_f32_16x16x32_bf16 v[16:19], v[208:211], v[182:185], v[16:19]
	v_mfma_f32_16x16x32_bf16 v[4:7], v[198:201], v[190:193], v[4:7]
	v_mfma_f32_16x16x32_bf16 v[0:3], v[208:211], v[190:193], v[0:3]
	s_add_i32 s52, 0, 0x18000
	v_add_u32_e32 v158, s52, v141
	s_barrier
	ds_read_b128 v[146:149], v158
	ds_read_b128 v[150:153], v158 offset:1024
	ds_read_b128 v[154:157], v158 offset:2048
	ds_read_b128 v[158:161], v158 offset:3072
	s_add_u32 s24, s24, 0x200000
	s_addc_u32 s25, s25, 0
	s_mov_b32 m0, s34
	ds_read_b128 v[162:165], v144 offset:32768
	ds_read_b128 v[166:169], v144 offset:33792
	ds_read_b128 v[170:173], v144 offset:34816
	ds_read_b128 v[174:177], v144 offset:35840
	ds_read_b128 v[178:181], v144 offset:36864
	ds_read_b128 v[182:185], v144 offset:37888
	ds_read_b128 v[186:189], v144 offset:38912
	ds_read_b128 v[190:193], v144 offset:39936
	global_load_lds_dwordx4 v134, s[24:25]
	s_mov_b32 m0, s35
	s_nop 0
	global_load_lds_dwordx4 v130, s[24:25]
	s_waitcnt lgkmcnt(8)
	s_barrier
	s_waitcnt lgkmcnt(0)
	v_mfma_f32_16x16x32_bf16 v[124:127], v[146:149], v[162:165], v[124:127]
	v_mfma_f32_16x16x32_bf16 v[120:123], v[154:157], v[162:165], v[120:123]
	v_mfma_f32_16x16x32_bf16 v[108:111], v[146:149], v[170:173], v[108:111]
	v_mfma_f32_16x16x32_bf16 v[104:107], v[154:157], v[170:173], v[104:107]
	v_mfma_f32_16x16x32_bf16 v[92:95], v[146:149], v[178:181], v[92:95]
	v_mfma_f32_16x16x32_bf16 v[88:91], v[154:157], v[178:181], v[88:91]
	v_mfma_f32_16x16x32_bf16 v[76:79], v[146:149], v[186:189], v[76:79]
	v_mfma_f32_16x16x32_bf16 v[72:75], v[154:157], v[186:189], v[72:75]
	v_mfma_f32_16x16x32_bf16 v[124:127], v[150:153], v[166:169], v[124:127]
	v_mfma_f32_16x16x32_bf16 v[120:123], v[158:161], v[166:169], v[120:123]
	v_mfma_f32_16x16x32_bf16 v[108:111], v[150:153], v[174:177], v[108:111]
	v_mfma_f32_16x16x32_bf16 v[104:107], v[158:161], v[174:177], v[104:107]
	v_mfma_f32_16x16x32_bf16 v[92:95], v[150:153], v[182:185], v[92:95]
	v_mfma_f32_16x16x32_bf16 v[88:91], v[158:161], v[182:185], v[88:91]
	v_mfma_f32_16x16x32_bf16 v[76:79], v[150:153], v[190:193], v[76:79]
	v_mfma_f32_16x16x32_bf16 v[72:75], v[158:161], v[190:193], v[72:75]
	s_barrier
	s_add_i32 s24, 0, 0x1c000
	s_add_i32 s25, s52, s29
	v_add_u32_e32 v208, s24, v141
	s_mov_b32 m0, s25
	ds_read_b128 v[194:197], v208
	ds_read_b128 v[198:201], v208 offset:1024
	ds_read_b128 v[204:207], v208 offset:2048
	ds_read_b128 v[208:211], v208 offset:3072
	s_add_u32 s100, s22, 0x80
	s_addc_u32 s101, s23, 0
	global_load_lds_dwordx4 v132, s[100:101]
	s_add_i32 m0, s25, 0x2000
	s_nop 0
	s_add_u32 s100, s22, 0x80
	s_addc_u32 s101, s23, 0
	global_load_lds_dwordx4 v128, s[100:101]
	s_barrier
	s_waitcnt lgkmcnt(0)
	v_mfma_f32_16x16x32_bf16 v[116:119], v[194:197], v[162:165], v[116:119]
	v_mfma_f32_16x16x32_bf16 v[112:115], v[204:207], v[162:165], v[112:115]
	v_mfma_f32_16x16x32_bf16 v[100:103], v[194:197], v[170:173], v[100:103]
	v_mfma_f32_16x16x32_bf16 v[96:99], v[204:207], v[170:173], v[96:99]
	v_mfma_f32_16x16x32_bf16 v[84:87], v[194:197], v[178:181], v[84:87]
	v_mfma_f32_16x16x32_bf16 v[80:83], v[204:207], v[178:181], v[80:83]
	v_mfma_f32_16x16x32_bf16 v[68:71], v[194:197], v[186:189], v[68:71]
	v_mfma_f32_16x16x32_bf16 v[64:67], v[204:207], v[186:189], v[64:67]
	v_mfma_f32_16x16x32_bf16 v[116:119], v[198:201], v[166:169], v[116:119]
	v_mfma_f32_16x16x32_bf16 v[112:115], v[208:211], v[166:169], v[112:115]
	v_mfma_f32_16x16x32_bf16 v[100:103], v[198:201], v[174:177], v[100:103]
	v_mfma_f32_16x16x32_bf16 v[96:99], v[208:211], v[174:177], v[96:99]
	v_mfma_f32_16x16x32_bf16 v[84:87], v[198:201], v[182:185], v[84:87]
	v_mfma_f32_16x16x32_bf16 v[80:83], v[208:211], v[182:185], v[80:83]
	v_mfma_f32_16x16x32_bf16 v[68:71], v[198:201], v[190:193], v[68:71]
	v_mfma_f32_16x16x32_bf16 v[64:67], v[208:211], v[190:193], v[64:67]
	s_mov_b32 m0, s37
	s_barrier
	ds_read_b128 v[162:165], v144 offset:49152
	ds_read_b128 v[166:169], v144 offset:50176
	ds_read_b128 v[170:173], v144 offset:51200
	ds_read_b128 v[174:177], v144 offset:52224
	ds_read_b128 v[178:181], v144 offset:53248
	ds_read_b128 v[182:185], v144 offset:54272
	ds_read_b128 v[186:189], v144 offset:55296
	ds_read_b128 v[190:193], v144 offset:56320
	s_add_u32 s100, s98, 0x80
	s_addc_u32 s101, s99, 0
	global_load_lds_dwordx4 v134, s[100:101]
	s_mov_b32 m0, s38
	s_nop 0
	s_add_u32 s100, s98, 0x80
	s_addc_u32 s101, s99, 0
	global_load_lds_dwordx4 v130, s[100:101]
	s_barrier
	s_waitcnt lgkmcnt(0)
	v_mfma_f32_16x16x32_bf16 v[60:63], v[146:149], v[162:165], v[60:63]
	v_mfma_f32_16x16x32_bf16 v[56:59], v[154:157], v[162:165], v[56:59]
	v_mfma_f32_16x16x32_bf16 v[44:47], v[146:149], v[170:173], v[44:47]
	v_mfma_f32_16x16x32_bf16 v[40:43], v[154:157], v[170:173], v[40:43]
	v_mfma_f32_16x16x32_bf16 v[28:31], v[146:149], v[178:181], v[28:31]
	v_mfma_f32_16x16x32_bf16 v[24:27], v[154:157], v[178:181], v[24:27]
	v_mfma_f32_16x16x32_bf16 v[12:15], v[146:149], v[186:189], v[12:15]
	v_mfma_f32_16x16x32_bf16 v[8:11], v[154:157], v[186:189], v[8:11]
	v_mfma_f32_16x16x32_bf16 v[60:63], v[150:153], v[166:169], v[60:63]
	v_mfma_f32_16x16x32_bf16 v[56:59], v[158:161], v[166:169], v[56:59]
	v_mfma_f32_16x16x32_bf16 v[44:47], v[150:153], v[174:177], v[44:47]
	v_mfma_f32_16x16x32_bf16 v[40:43], v[158:161], v[174:177], v[40:43]
	v_mfma_f32_16x16x32_bf16 v[28:31], v[150:153], v[182:185], v[28:31]
	v_mfma_f32_16x16x32_bf16 v[24:27], v[158:161], v[182:185], v[24:27]
	v_mfma_f32_16x16x32_bf16 v[12:15], v[150:153], v[190:193], v[12:15]
	v_mfma_f32_16x16x32_bf16 v[8:11], v[158:161], v[190:193], v[8:11]
	s_barrier
	s_add_u32 s22, s22, 0x80080
	s_addc_u32 s23, s23, 0
	s_add_i32 s24, s24, s29
	s_mov_b32 m0, s24
	s_nop 0
	global_load_lds_dwordx4 v132, s[22:23]
	s_add_i32 m0, s24, 0x2000
	s_nop 0
	global_load_lds_dwordx4 v128, s[22:23]
	s_waitcnt vmcnt(6)
	s_barrier
	v_mfma_f32_16x16x32_bf16 v[52:55], v[194:197], v[162:165], v[52:55]
	v_mfma_f32_16x16x32_bf16 v[48:51], v[204:207], v[162:165], v[48:51]
	v_mfma_f32_16x16x32_bf16 v[36:39], v[194:197], v[170:173], v[36:39]
	v_mfma_f32_16x16x32_bf16 v[32:35], v[204:207], v[170:173], v[32:35]
	v_mfma_f32_16x16x32_bf16 v[20:23], v[194:197], v[178:181], v[20:23]
	v_mfma_f32_16x16x32_bf16 v[16:19], v[204:207], v[178:181], v[16:19]
	v_mfma_f32_16x16x32_bf16 v[4:7], v[194:197], v[186:189], v[4:7]
	v_mfma_f32_16x16x32_bf16 v[0:3], v[204:207], v[186:189], v[0:3]
	v_mfma_f32_16x16x32_bf16 v[52:55], v[198:201], v[166:169], v[52:55]
	v_mfma_f32_16x16x32_bf16 v[48:51], v[208:211], v[166:169], v[48:51]
	v_mfma_f32_16x16x32_bf16 v[36:39], v[198:201], v[174:177], v[36:39]
	v_mfma_f32_16x16x32_bf16 v[32:35], v[208:211], v[174:177], v[32:35]
	v_mfma_f32_16x16x32_bf16 v[20:23], v[198:201], v[182:185], v[20:23]
	v_mfma_f32_16x16x32_bf16 v[16:19], v[208:211], v[182:185], v[16:19]
	v_mfma_f32_16x16x32_bf16 v[4:7], v[198:201], v[190:193], v[4:7]
	v_mfma_f32_16x16x32_bf16 v[0:3], v[208:211], v[190:193], v[0:3]
	s_add_u32 s20, s20, 0x100
	s_addc_u32 s21, s21, 0
	s_add_u32 s49, s49, 0x100
	s_addc_u32 s50, s50, 0
	s_cmp_ge_i32 s51, s33
	s_mov_b32 s22, s51
	s_barrier
	s_cbranch_scc0 .LBB0_1631
	s_branch .LBB0_1626
